# extra setprio 0/1 toggles every 4 MFMAs inside the paired MFMA blocks
# speedup vs baseline: 1.0078x; 1.0078x over previous
.LBB0_257:
	s_or_b64 exec, exec, s[50:51]
	s_add_u32 s0, s12, s6
	ds_read_b128 v[146:149], v137
	ds_read_b128 v[150:153], v137 offset:1024
	ds_read_b128 v[154:157], v137 offset:2048
	ds_read_b128 v[158:161], v137 offset:3072
	ds_read_b128 v[162:165], v138
	ds_read_b128 v[166:169], v138 offset:1024
	ds_read_b128 v[170:173], v138 offset:2048
	ds_read_b128 v[174:177], v138 offset:3072
	s_addc_u32 s1, s13, s7
	s_add_u32 s50, s0, 0x20000
	s_addc_u32 s51, s1, 0
	s_add_u32 s52, s93, s6
	s_addc_u32 s53, s94, s7
	s_cmp_eq_u32 s6, 0x60000
	s_cselect_b32 s62, s95, s50
	s_cselect_b32 s63, s31, s51
	s_cselect_b32 s51, s29, s53
	s_cselect_b32 s50, s96, s52
	s_add_u32 s52, s62, 0x8000
	s_addc_u32 s53, s63, 0
	s_add_u32 s54, s50, 0x8000
	s_addc_u32 s55, s51, 0
	ds_read_b128 v[178:181], v139
	ds_read_b128 v[182:185], v139 offset:1024
	ds_read_b128 v[186:189], v139 offset:2048
	ds_read_b128 v[190:193], v139 offset:3072
	ds_read_b128 v[198:201], v139 offset:4096
	ds_read_b128 v[202:205], v139 offset:5120
	ds_read_b128 v[206:209], v139 offset:6144
	ds_read_b128 v[212:215], v139 offset:7168
	s_add_u32 s0, s0, 0x1c000
	s_addc_u32 s1, s1, 0
	s_mov_b32 m0, s78
	s_nop 0
	global_load_lds_dwordx4 v134, s[0:1]
	s_add_u32 m0, s78, 0x2000
	s_nop 0
	global_load_lds_dwordx4 v135, s[0:1]
	s_waitcnt vmcnt(8)
	s_waitcnt lgkmcnt(0)
	s_setprio 1
	s_barrier
	v_mfma_f32_16x16x32_bf16 v[122:125], v[146:149], v[178:181], v[122:125]
	v_mfma_f32_16x16x32_bf16 v[122:125], v[150:153], v[182:185], v[122:125]
	s_waitcnt lgkmcnt(5)
	v_mfma_f32_16x16x32_bf16 v[114:117], v[154:157], v[178:181], v[114:117]
	v_mfma_f32_16x16x32_bf16 v[114:117], v[158:161], v[182:185], v[114:117]
	s_waitcnt lgkmcnt(3)
	s_setprio 0
	s_setprio 1
	v_mfma_f32_16x16x32_bf16 v[106:109], v[146:149], v[186:189], v[106:109]
	v_mfma_f32_16x16x32_bf16 v[106:109], v[150:153], v[190:193], v[106:109]
	s_waitcnt lgkmcnt(1)
	v_mfma_f32_16x16x32_bf16 v[98:101], v[154:157], v[186:189], v[98:101]
	v_mfma_f32_16x16x32_bf16 v[98:101], v[158:161], v[190:193], v[98:101]
	s_setprio 0
	s_setprio 1
	v_mfma_f32_16x16x32_bf16 v[90:93], v[146:149], v[198:201], v[90:93]
	v_mfma_f32_16x16x32_bf16 v[90:93], v[150:153], v[202:205], v[90:93]
	v_mfma_f32_16x16x32_bf16 v[82:85], v[154:157], v[198:201], v[82:85]
	v_mfma_f32_16x16x32_bf16 v[82:85], v[158:161], v[202:205], v[82:85]
	s_setprio 0
	s_setprio 1
	v_mfma_f32_16x16x32_bf16 v[74:77], v[146:149], v[206:209], v[74:77]
	v_mfma_f32_16x16x32_bf16 v[74:77], v[150:153], v[212:215], v[74:77]
	s_waitcnt lgkmcnt(0)
	v_mfma_f32_16x16x32_bf16 v[66:69], v[154:157], v[206:209], v[66:69]
	v_mfma_f32_16x16x32_bf16 v[66:69], v[158:161], v[212:215], v[66:69]
	s_setprio 0
	s_setprio 1
	v_mfma_f32_16x16x32_bf16 v[126:129], v[162:165], v[178:181], v[126:129]
	v_mfma_f32_16x16x32_bf16 v[126:129], v[166:169], v[182:185], v[126:129]
	v_mfma_f32_16x16x32_bf16 v[118:121], v[170:173], v[178:181], v[118:121]
	v_mfma_f32_16x16x32_bf16 v[118:121], v[174:177], v[182:185], v[118:121]
	s_setprio 0
	s_setprio 1
	v_mfma_f32_16x16x32_bf16 v[110:113], v[162:165], v[186:189], v[110:113]
	v_mfma_f32_16x16x32_bf16 v[110:113], v[166:169], v[190:193], v[110:113]
	v_mfma_f32_16x16x32_bf16 v[102:105], v[170:173], v[186:189], v[102:105]
	v_mfma_f32_16x16x32_bf16 v[102:105], v[174:177], v[190:193], v[102:105]
	s_setprio 0
	s_setprio 1
	v_mfma_f32_16x16x32_bf16 v[94:97], v[162:165], v[198:201], v[94:97]
	v_mfma_f32_16x16x32_bf16 v[94:97], v[166:169], v[202:205], v[94:97]
	v_mfma_f32_16x16x32_bf16 v[86:89], v[170:173], v[198:201], v[86:89]
	v_mfma_f32_16x16x32_bf16 v[86:89], v[174:177], v[202:205], v[86:89]
	s_setprio 0
	s_setprio 1
	v_mfma_f32_16x16x32_bf16 v[78:81], v[162:165], v[206:209], v[78:81]
	v_mfma_f32_16x16x32_bf16 v[78:81], v[166:169], v[212:215], v[78:81]
	s_setprio 2
	s_barrier
	v_mfma_f32_16x16x32_bf16 v[70:73], v[170:173], v[206:209], v[70:73]
	v_mfma_f32_16x16x32_bf16 v[70:73], v[174:177], v[212:215], v[70:73]
	s_setprio 0
	s_nop 0
	ds_read_b128 v[178:181], v139 offset:16384
	ds_read_b128 v[182:185], v139 offset:17408
	ds_read_b128 v[186:189], v139 offset:18432
	ds_read_b128 v[190:193], v139 offset:19456
	ds_read_b128 v[198:201], v139 offset:20480
	ds_read_b128 v[202:205], v139 offset:21504
	ds_read_b128 v[206:209], v139 offset:22528
	ds_read_b128 v[212:215], v139 offset:23552
	s_mov_b32 m0, s11
	s_nop 0
	global_load_lds_dwordx4 v134, s[50:51]
	s_add_u32 m0, s11, 0x2000
	s_nop 0
	global_load_lds_dwordx4 v135, s[50:51]
	s_add_u32 s0, s50, 0x4000
	s_addc_u32 s1, s51, 0
	s_mov_b32 m0, s68
	s_nop 0
	global_load_lds_dwordx4 v134, s[0:1]
	s_add_u32 m0, s68, 0x2000
	s_nop 0
	global_load_lds_dwordx4 v135, s[0:1]
	s_nop 0
	s_mov_b32 m0, s65
	s_nop 0
	global_load_lds_dwordx4 v134, s[62:63]
	s_add_u32 m0, s65, 0x2000
	s_nop 0
	global_load_lds_dwordx4 v135, s[62:63]
	s_waitcnt vmcnt(8)
	s_waitcnt lgkmcnt(0)
	s_setprio 1
	s_barrier
	v_mfma_f32_16x16x32_bf16 v[58:61], v[146:149], v[178:181], v[58:61]
	v_mfma_f32_16x16x32_bf16 v[58:61], v[150:153], v[182:185], v[58:61]
	s_waitcnt lgkmcnt(5)
	v_mfma_f32_16x16x32_bf16 v[50:53], v[154:157], v[178:181], v[50:53]
	v_mfma_f32_16x16x32_bf16 v[50:53], v[158:161], v[182:185], v[50:53]
	s_waitcnt lgkmcnt(3)
	s_setprio 0
	s_setprio 1
	v_mfma_f32_16x16x32_bf16 v[42:45], v[146:149], v[186:189], v[42:45]
	v_mfma_f32_16x16x32_bf16 v[42:45], v[150:153], v[190:193], v[42:45]
	s_waitcnt lgkmcnt(1)
	v_mfma_f32_16x16x32_bf16 v[34:37], v[154:157], v[186:189], v[34:37]
	v_mfma_f32_16x16x32_bf16 v[34:37], v[158:161], v[190:193], v[34:37]
	s_setprio 0
	s_setprio 1
	v_mfma_f32_16x16x32_bf16 v[26:29], v[146:149], v[198:201], v[26:29]
	v_mfma_f32_16x16x32_bf16 v[26:29], v[150:153], v[202:205], v[26:29]
	v_mfma_f32_16x16x32_bf16 v[18:21], v[154:157], v[198:201], v[18:21]
	v_mfma_f32_16x16x32_bf16 v[18:21], v[158:161], v[202:205], v[18:21]
	s_setprio 0
	s_setprio 1
	v_mfma_f32_16x16x32_bf16 v[10:13], v[146:149], v[206:209], v[10:13]
	v_mfma_f32_16x16x32_bf16 v[10:13], v[150:153], v[212:215], v[10:13]
	s_waitcnt lgkmcnt(0)
	v_mfma_f32_16x16x32_bf16 v[2:5], v[154:157], v[206:209], v[2:5]
	v_mfma_f32_16x16x32_bf16 v[2:5], v[158:161], v[212:215], v[2:5]
	s_setprio 0
	s_setprio 1
	v_mfma_f32_16x16x32_bf16 v[62:65], v[162:165], v[178:181], v[62:65]
	v_mfma_f32_16x16x32_bf16 v[62:65], v[166:169], v[182:185], v[62:65]
	v_mfma_f32_16x16x32_bf16 v[54:57], v[170:173], v[178:181], v[54:57]
	v_mfma_f32_16x16x32_bf16 v[54:57], v[174:177], v[182:185], v[54:57]
	s_setprio 0
	s_setprio 1
	v_mfma_f32_16x16x32_bf16 v[46:49], v[162:165], v[186:189], v[46:49]
	v_mfma_f32_16x16x32_bf16 v[46:49], v[166:169], v[190:193], v[46:49]
	v_mfma_f32_16x16x32_bf16 v[38:41], v[170:173], v[186:189], v[38:41]
	v_mfma_f32_16x16x32_bf16 v[38:41], v[174:177], v[190:193], v[38:41]
	s_setprio 0
	s_setprio 1
	v_mfma_f32_16x16x32_bf16 v[30:33], v[162:165], v[198:201], v[30:33]
	v_mfma_f32_16x16x32_bf16 v[30:33], v[166:169], v[202:205], v[30:33]
	v_mfma_f32_16x16x32_bf16 v[22:25], v[170:173], v[198:201], v[22:25]
	v_mfma_f32_16x16x32_bf16 v[22:25], v[174:177], v[202:205], v[22:25]
	s_setprio 0
	s_setprio 1
	v_mfma_f32_16x16x32_bf16 v[14:17], v[162:165], v[206:209], v[14:17]
	v_mfma_f32_16x16x32_bf16 v[14:17], v[166:169], v[212:215], v[14:17]
	s_setprio 2
	s_barrier
	v_mfma_f32_16x16x32_bf16 v[6:9], v[170:173], v[206:209], v[6:9]
	v_mfma_f32_16x16x32_bf16 v[6:9], v[174:177], v[212:215], v[6:9]
	s_setprio 0
	s_nop 0
	ds_read_b128 v[146:149], v140
	ds_read_b128 v[150:153], v140 offset:1024
	ds_read_b128 v[154:157], v140 offset:2048
	ds_read_b128 v[158:161], v140 offset:3072
	ds_read_b128 v[162:165], v141
	ds_read_b128 v[166:169], v141 offset:1024
	ds_read_b128 v[170:173], v141 offset:2048
	ds_read_b128 v[174:177], v141 offset:3072
	ds_read_b128 v[178:181], v139 offset:32768
	ds_read_b128 v[182:185], v139 offset:33792
	ds_read_b128 v[186:189], v139 offset:34816
	ds_read_b128 v[190:193], v139 offset:35840
	ds_read_b128 v[198:201], v139 offset:36864
	ds_read_b128 v[202:205], v139 offset:37888
	ds_read_b128 v[206:209], v139 offset:38912
	ds_read_b128 v[212:215], v139 offset:39936
	s_add_u32 s0, s62, 0x4000
	s_addc_u32 s1, s63, 0
	s_mov_b32 m0, s69
	s_nop 0
	global_load_lds_dwordx4 v134, s[0:1]
	s_add_u32 m0, s69, 0x2000
	s_nop 0
	global_load_lds_dwordx4 v135, s[0:1]
	s_waitcnt vmcnt(8)
	s_waitcnt lgkmcnt(0)
	s_setprio 1
	s_barrier
	v_mfma_f32_16x16x32_bf16 v[122:125], v[146:149], v[178:181], v[122:125]
	v_mfma_f32_16x16x32_bf16 v[122:125], v[150:153], v[182:185], v[122:125]
	s_waitcnt lgkmcnt(5)
	v_mfma_f32_16x16x32_bf16 v[114:117], v[154:157], v[178:181], v[114:117]
	v_mfma_f32_16x16x32_bf16 v[114:117], v[158:161], v[182:185], v[114:117]
	s_waitcnt lgkmcnt(3)
	s_setprio 0
	s_setprio 1
	v_mfma_f32_16x16x32_bf16 v[106:109], v[146:149], v[186:189], v[106:109]
	v_mfma_f32_16x16x32_bf16 v[106:109], v[150:153], v[190:193], v[106:109]
	s_waitcnt lgkmcnt(1)
	v_mfma_f32_16x16x32_bf16 v[98:101], v[154:157], v[186:189], v[98:101]
	v_mfma_f32_16x16x32_bf16 v[98:101], v[158:161], v[190:193], v[98:101]
	s_setprio 0
	s_setprio 1
	v_mfma_f32_16x16x32_bf16 v[90:93], v[146:149], v[198:201], v[90:93]
	v_mfma_f32_16x16x32_bf16 v[90:93], v[150:153], v[202:205], v[90:93]
	v_mfma_f32_16x16x32_bf16 v[82:85], v[154:157], v[198:201], v[82:85]
	v_mfma_f32_16x16x32_bf16 v[82:85], v[158:161], v[202:205], v[82:85]
	s_setprio 0
	s_setprio 1
	v_mfma_f32_16x16x32_bf16 v[74:77], v[146:149], v[206:209], v[74:77]
	v_mfma_f32_16x16x32_bf16 v[74:77], v[150:153], v[212:215], v[74:77]
	s_waitcnt lgkmcnt(0)
	v_mfma_f32_16x16x32_bf16 v[66:69], v[154:157], v[206:209], v[66:69]
	v_mfma_f32_16x16x32_bf16 v[66:69], v[158:161], v[212:215], v[66:69]
	s_setprio 0
	s_setprio 1
	v_mfma_f32_16x16x32_bf16 v[126:129], v[162:165], v[178:181], v[126:129]
	v_mfma_f32_16x16x32_bf16 v[126:129], v[166:169], v[182:185], v[126:129]
	v_mfma_f32_16x16x32_bf16 v[118:121], v[170:173], v[178:181], v[118:121]
	v_mfma_f32_16x16x32_bf16 v[118:121], v[174:177], v[182:185], v[118:121]
	s_setprio 0
	s_setprio 1
	v_mfma_f32_16x16x32_bf16 v[110:113], v[162:165], v[186:189], v[110:113]
	v_mfma_f32_16x16x32_bf16 v[110:113], v[166:169], v[190:193], v[110:113]
	v_mfma_f32_16x16x32_bf16 v[102:105], v[170:173], v[186:189], v[102:105]
	v_mfma_f32_16x16x32_bf16 v[102:105], v[174:177], v[190:193], v[102:105]
	s_setprio 0
	s_setprio 1
	v_mfma_f32_16x16x32_bf16 v[94:97], v[162:165], v[198:201], v[94:97]
	v_mfma_f32_16x16x32_bf16 v[94:97], v[166:169], v[202:205], v[94:97]
	v_mfma_f32_16x16x32_bf16 v[86:89], v[170:173], v[198:201], v[86:89]
	v_mfma_f32_16x16x32_bf16 v[86:89], v[174:177], v[202:205], v[86:89]
	s_setprio 0
	s_setprio 1
	v_mfma_f32_16x16x32_bf16 v[78:81], v[162:165], v[206:209], v[78:81]
	v_mfma_f32_16x16x32_bf16 v[78:81], v[166:169], v[212:215], v[78:81]
	s_setprio 2
	s_barrier
	v_mfma_f32_16x16x32_bf16 v[70:73], v[170:173], v[206:209], v[70:73]
	v_mfma_f32_16x16x32_bf16 v[70:73], v[174:177], v[212:215], v[70:73]
	s_setprio 0
	s_nop 0
	ds_read_b128 v[178:181], v139 offset:49152
	ds_read_b128 v[182:185], v139 offset:50176
	ds_read_b128 v[186:189], v139 offset:51200
	ds_read_b128 v[190:193], v139 offset:52224
	ds_read_b128 v[198:201], v139 offset:53248
	ds_read_b128 v[202:205], v139 offset:54272
	ds_read_b128 v[206:209], v139 offset:55296
	ds_read_b128 v[212:215], v139 offset:56320
	s_mov_b32 m0, s74
	s_nop 0
	global_load_lds_dwordx4 v134, s[54:55]
	s_add_u32 m0, s74, 0x2000
	s_nop 0
	global_load_lds_dwordx4 v135, s[54:55]
	s_add_u32 s0, s50, 0xc000
	s_addc_u32 s1, s51, 0
	s_mov_b32 m0, s77
	s_nop 0
	global_load_lds_dwordx4 v134, s[0:1]
	s_add_u32 m0, s77, 0x2000
	s_nop 0
	global_load_lds_dwordx4 v135, s[0:1]
	s_nop 0
	s_mov_b32 m0, s76
	s_nop 0
	global_load_lds_dwordx4 v134, s[52:53]
	s_add_u32 m0, s76, 0x2000
	s_nop 0
	global_load_lds_dwordx4 v135, s[52:53]
	s_waitcnt vmcnt(8)
	s_waitcnt lgkmcnt(0)
	s_setprio 1
	s_barrier
	v_mfma_f32_16x16x32_bf16 v[58:61], v[146:149], v[178:181], v[58:61]
	v_mfma_f32_16x16x32_bf16 v[58:61], v[150:153], v[182:185], v[58:61]
	s_waitcnt lgkmcnt(5)
	v_mfma_f32_16x16x32_bf16 v[50:53], v[154:157], v[178:181], v[50:53]
	v_mfma_f32_16x16x32_bf16 v[50:53], v[158:161], v[182:185], v[50:53]
	s_waitcnt lgkmcnt(3)
	s_setprio 0
	s_setprio 1
	v_mfma_f32_16x16x32_bf16 v[42:45], v[146:149], v[186:189], v[42:45]
	v_mfma_f32_16x16x32_bf16 v[42:45], v[150:153], v[190:193], v[42:45]
	s_waitcnt lgkmcnt(1)
	v_mfma_f32_16x16x32_bf16 v[34:37], v[154:157], v[186:189], v[34:37]
	v_mfma_f32_16x16x32_bf16 v[34:37], v[158:161], v[190:193], v[34:37]
	s_setprio 0
	s_setprio 1
	v_mfma_f32_16x16x32_bf16 v[26:29], v[146:149], v[198:201], v[26:29]
	v_mfma_f32_16x16x32_bf16 v[26:29], v[150:153], v[202:205], v[26:29]
	v_mfma_f32_16x16x32_bf16 v[18:21], v[154:157], v[198:201], v[18:21]
	v_mfma_f32_16x16x32_bf16 v[18:21], v[158:161], v[202:205], v[18:21]
	s_setprio 0
	s_setprio 1
	v_mfma_f32_16x16x32_bf16 v[10:13], v[146:149], v[206:209], v[10:13]
	v_mfma_f32_16x16x32_bf16 v[10:13], v[150:153], v[212:215], v[10:13]
	s_waitcnt lgkmcnt(0)
	v_mfma_f32_16x16x32_bf16 v[2:5], v[154:157], v[206:209], v[2:5]
	v_mfma_f32_16x16x32_bf16 v[2:5], v[158:161], v[212:215], v[2:5]
	s_setprio 0
	s_setprio 1
	v_mfma_f32_16x16x32_bf16 v[62:65], v[162:165], v[178:181], v[62:65]
	v_mfma_f32_16x16x32_bf16 v[62:65], v[166:169], v[182:185], v[62:65]
	v_mfma_f32_16x16x32_bf16 v[54:57], v[170:173], v[178:181], v[54:57]
	v_mfma_f32_16x16x32_bf16 v[54:57], v[174:177], v[182:185], v[54:57]
	s_setprio 0
	s_setprio 1
	v_mfma_f32_16x16x32_bf16 v[46:49], v[162:165], v[186:189], v[46:49]
	v_mfma_f32_16x16x32_bf16 v[46:49], v[166:169], v[190:193], v[46:49]
	v_mfma_f32_16x16x32_bf16 v[38:41], v[170:173], v[186:189], v[38:41]
	v_mfma_f32_16x16x32_bf16 v[38:41], v[174:177], v[190:193], v[38:41]
	s_setprio 0
	s_setprio 1
	v_mfma_f32_16x16x32_bf16 v[30:33], v[162:165], v[198:201], v[30:33]
	v_mfma_f32_16x16x32_bf16 v[30:33], v[166:169], v[202:205], v[30:33]
	v_mfma_f32_16x16x32_bf16 v[22:25], v[170:173], v[198:201], v[22:25]
	v_mfma_f32_16x16x32_bf16 v[22:25], v[174:177], v[202:205], v[22:25]
	s_setprio 0
	s_setprio 1
	v_mfma_f32_16x16x32_bf16 v[14:17], v[162:165], v[206:209], v[14:17]
	v_mfma_f32_16x16x32_bf16 v[14:17], v[166:169], v[212:215], v[14:17]
	s_setprio 2
	s_barrier
	v_mfma_f32_16x16x32_bf16 v[6:9], v[170:173], v[206:209], v[6:9]
	v_mfma_f32_16x16x32_bf16 v[6:9], v[174:177], v[212:215], v[6:9]
	s_setprio 0
	s_nop 0
	s_add_i32 s97, s97, 2
	s_add_u32 s6, s6, 0x10000
	s_addc_u32 s7, s7, 0
	s_cmp_gt_u32 s97, 13
	s_cbranch_scc1 .LBB0_259
	v_mov_b32_e32 v145, v130
	s_branch .LBB0_255

.LBB0_364:
	s_add_i32 s26, s93, 2
	s_lshl_b64 s[62:63], s[26:27], 15
	s_add_u32 s64, s18, s62
	s_addc_u32 s65, s19, s63
	s_and_b64 s[52:53], s[50:51], exec
	s_cselect_b32 s53, s65, s39
	s_cselect_b32 s52, s64, s38
	s_add_u32 s62, s20, s62
	s_waitcnt vmcnt(8)
	s_addc_u32 s63, s21, s63
	s_waitcnt lgkmcnt(0)
	s_and_b64 s[50:51], s[50:51], exec
	s_cselect_b32 s51, s63, s49
	s_cselect_b32 s50, s62, s48
	s_setprio 1
	s_barrier
	v_mfma_f32_16x16x32_bf16 v[126:129], v[146:149], v[186:189], v[126:129]
	v_mfma_f32_16x16x32_bf16 v[126:129], v[150:153], v[190:193], v[126:129]
	s_waitcnt lgkmcnt(5)
	v_mfma_f32_16x16x32_bf16 v[122:125], v[154:157], v[186:189], v[122:125]
	v_mfma_f32_16x16x32_bf16 v[122:125], v[158:161], v[190:193], v[122:125]
	s_waitcnt lgkmcnt(3)
	s_setprio 0
	s_setprio 1
	v_mfma_f32_16x16x32_bf16 v[118:121], v[146:149], v[178:181], v[118:121]
	v_mfma_f32_16x16x32_bf16 v[118:121], v[150:153], v[182:185], v[118:121]
	s_waitcnt lgkmcnt(1)
	v_mfma_f32_16x16x32_bf16 v[114:117], v[154:157], v[178:181], v[114:117]
	v_mfma_f32_16x16x32_bf16 v[114:117], v[158:161], v[182:185], v[114:117]
	s_setprio 0
	s_setprio 1
	v_mfma_f32_16x16x32_bf16 v[110:113], v[146:149], v[170:173], v[110:113]
	v_mfma_f32_16x16x32_bf16 v[110:113], v[150:153], v[174:177], v[110:113]
	v_mfma_f32_16x16x32_bf16 v[106:109], v[154:157], v[170:173], v[106:109]
	v_mfma_f32_16x16x32_bf16 v[106:109], v[158:161], v[174:177], v[106:109]
	s_setprio 0
	s_setprio 1
	v_mfma_f32_16x16x32_bf16 v[102:105], v[146:149], v[162:165], v[102:105]
	v_mfma_f32_16x16x32_bf16 v[102:105], v[150:153], v[166:169], v[102:105]
	s_waitcnt lgkmcnt(0)
	v_mfma_f32_16x16x32_bf16 v[98:101], v[154:157], v[162:165], v[98:101]
	v_mfma_f32_16x16x32_bf16 v[98:101], v[158:161], v[166:169], v[98:101]
	s_setprio 0
	s_setprio 1
	v_mfma_f32_16x16x32_bf16 v[94:97], v[130:133], v[186:189], v[94:97]
	v_mfma_f32_16x16x32_bf16 v[94:97], v[134:137], v[190:193], v[94:97]
	v_mfma_f32_16x16x32_bf16 v[90:93], v[138:141], v[186:189], v[90:93]
	v_mfma_f32_16x16x32_bf16 v[90:93], v[142:145], v[190:193], v[90:93]
	s_setprio 0
	s_setprio 1
	v_mfma_f32_16x16x32_bf16 v[86:89], v[130:133], v[178:181], v[86:89]
	v_mfma_f32_16x16x32_bf16 v[86:89], v[134:137], v[182:185], v[86:89]
	v_mfma_f32_16x16x32_bf16 v[82:85], v[138:141], v[178:181], v[82:85]
	v_mfma_f32_16x16x32_bf16 v[82:85], v[142:145], v[182:185], v[82:85]
	s_setprio 0
	s_setprio 1
	v_mfma_f32_16x16x32_bf16 v[78:81], v[130:133], v[170:173], v[78:81]
	v_mfma_f32_16x16x32_bf16 v[78:81], v[134:137], v[174:177], v[78:81]
	v_mfma_f32_16x16x32_bf16 v[74:77], v[138:141], v[170:173], v[74:77]
	v_mfma_f32_16x16x32_bf16 v[74:77], v[142:145], v[174:177], v[74:77]
	s_setprio 0
	s_setprio 1
	v_mfma_f32_16x16x32_bf16 v[70:73], v[130:133], v[162:165], v[70:73]
	v_mfma_f32_16x16x32_bf16 v[70:73], v[134:137], v[166:169], v[70:73]
	s_setprio 2
	s_barrier
	v_mfma_f32_16x16x32_bf16 v[66:69], v[138:141], v[162:165], v[66:69]
	v_mfma_f32_16x16x32_bf16 v[66:69], v[142:145], v[166:169], v[66:69]
	s_setprio 0
	s_nop 0
	ds_read_b128 v[186:189], v219 offset:16384
	ds_read_b128 v[190:193], v219 offset:17408
	ds_read_b128 v[178:181], v219 offset:18432
	ds_read_b128 v[182:185], v219 offset:19456
	ds_read_b128 v[170:173], v219 offset:20480
	ds_read_b128 v[174:177], v219 offset:21504
	ds_read_b128 v[162:165], v219 offset:22528
	ds_read_b128 v[166:169], v219 offset:23552
	s_mov_b32 m0, s74
	s_nop 0
	global_load_lds_dwordx4 v195, s[50:51]
	s_add_u32 m0, s74, 0x2000
	s_nop 0
	global_load_lds_dwordx4 v212, s[50:51]
	s_add_u32 s62, s50, 0x4000
	s_addc_u32 s63, s51, 0
	s_mov_b32 m0, s75
	s_nop 0
	global_load_lds_dwordx4 v195, s[62:63]
	s_add_u32 m0, s75, 0x2000
	s_nop 0
	global_load_lds_dwordx4 v212, s[62:63]
	s_andn2_b64 vcc, exec, s[54:55]
	s_mov_b32 m0, s73
	s_nop 0
	global_load_lds_dwordx4 v195, s[52:53]
	s_add_u32 m0, s73, 0x2000
	s_nop 0
	global_load_lds_dwordx4 v212, s[52:53]
	s_cbranch_vccnz .LBB0_366
	v_mov_b32_e32 v2, 0
	v_mov_b32_e32 v3, v2
	v_mov_b32_e32 v4, v2
	v_mov_b32_e32 v5, v2
	v_mov_b32_e32 v6, v2
	v_mov_b32_e32 v7, v2
	v_mov_b32_e32 v8, v2
	v_mov_b32_e32 v9, v2
	v_mov_b32_e32 v10, v2
	v_mov_b32_e32 v11, v2
	v_mov_b32_e32 v12, v2
	v_mov_b32_e32 v13, v2
	v_mov_b32_e32 v14, v2
	v_mov_b32_e32 v15, v2
	v_mov_b32_e32 v16, v2
	v_mov_b32_e32 v17, v2
	v_mov_b32_e32 v18, v2
	v_mov_b32_e32 v19, v2
	v_mov_b32_e32 v20, v2
	v_mov_b32_e32 v21, v2
	v_mov_b32_e32 v22, v2
	v_mov_b32_e32 v23, v2
	v_mov_b32_e32 v24, v2
	v_mov_b32_e32 v25, v2
	v_mov_b32_e32 v26, v2
	v_mov_b32_e32 v27, v2
	v_mov_b32_e32 v28, v2
	v_mov_b32_e32 v29, v2
	v_mov_b32_e32 v30, v2
	v_mov_b32_e32 v31, v2
	v_mov_b32_e32 v32, v2
	v_mov_b32_e32 v33, v2
	v_mov_b32_e32 v34, v2
	v_mov_b32_e32 v35, v2
	v_mov_b32_e32 v36, v2
	v_mov_b32_e32 v37, v2
	v_mov_b32_e32 v38, v2
	v_mov_b32_e32 v39, v2
	v_mov_b32_e32 v40, v2
	v_mov_b32_e32 v41, v2
	v_mov_b32_e32 v42, v2
	v_mov_b32_e32 v43, v2
	v_mov_b32_e32 v44, v2
	v_mov_b32_e32 v45, v2
	v_mov_b32_e32 v46, v2
	v_mov_b32_e32 v47, v2
	v_mov_b32_e32 v48, v2
	v_mov_b32_e32 v49, v2
	v_mov_b32_e32 v50, v2
	v_mov_b32_e32 v51, v2
	v_mov_b32_e32 v52, v2
	v_mov_b32_e32 v53, v2
	v_mov_b32_e32 v54, v2
	v_mov_b32_e32 v55, v2
	v_mov_b32_e32 v56, v2
	v_mov_b32_e32 v57, v2
	v_mov_b32_e32 v58, v2
	v_mov_b32_e32 v59, v2
	v_mov_b32_e32 v60, v2
	v_mov_b32_e32 v61, v2
	v_mov_b32_e32 v62, v2
	v_mov_b32_e32 v63, v2
	v_mov_b32_e32 v64, v2
	v_mov_b32_e32 v65, v2
.LBB0_366:
	s_waitcnt vmcnt(8)
	s_add_u32 s54, s52, 0x8000
	s_waitcnt lgkmcnt(0)
	s_addc_u32 s55, s53, 0
	s_add_u32 s62, s50, 0x8000
	s_addc_u32 s63, s51, 0
	s_setprio 1
	s_barrier
	v_mfma_f32_16x16x32_bf16 v[62:65], v[146:149], v[186:189], v[62:65]
	v_mfma_f32_16x16x32_bf16 v[62:65], v[150:153], v[190:193], v[62:65]
	s_waitcnt lgkmcnt(5)
	v_mfma_f32_16x16x32_bf16 v[58:61], v[154:157], v[186:189], v[58:61]
	v_mfma_f32_16x16x32_bf16 v[58:61], v[158:161], v[190:193], v[58:61]
	s_waitcnt lgkmcnt(3)
	s_setprio 0
	s_setprio 1
	v_mfma_f32_16x16x32_bf16 v[54:57], v[146:149], v[178:181], v[54:57]
	v_mfma_f32_16x16x32_bf16 v[54:57], v[150:153], v[182:185], v[54:57]
	s_waitcnt lgkmcnt(1)
	v_mfma_f32_16x16x32_bf16 v[50:53], v[154:157], v[178:181], v[50:53]
	v_mfma_f32_16x16x32_bf16 v[50:53], v[158:161], v[182:185], v[50:53]
	s_setprio 0
	s_setprio 1
	v_mfma_f32_16x16x32_bf16 v[46:49], v[146:149], v[170:173], v[46:49]
	v_mfma_f32_16x16x32_bf16 v[46:49], v[150:153], v[174:177], v[46:49]
	v_mfma_f32_16x16x32_bf16 v[42:45], v[154:157], v[170:173], v[42:45]
	v_mfma_f32_16x16x32_bf16 v[42:45], v[158:161], v[174:177], v[42:45]
	s_setprio 0
	s_setprio 1
	v_mfma_f32_16x16x32_bf16 v[38:41], v[146:149], v[162:165], v[38:41]
	v_mfma_f32_16x16x32_bf16 v[38:41], v[150:153], v[166:169], v[38:41]
	s_waitcnt lgkmcnt(0)
	v_mfma_f32_16x16x32_bf16 v[34:37], v[154:157], v[162:165], v[34:37]
	v_mfma_f32_16x16x32_bf16 v[34:37], v[158:161], v[166:169], v[34:37]
	s_setprio 0
	s_setprio 1
	v_mfma_f32_16x16x32_bf16 v[30:33], v[130:133], v[186:189], v[30:33]
	v_mfma_f32_16x16x32_bf16 v[30:33], v[134:137], v[190:193], v[30:33]
	v_mfma_f32_16x16x32_bf16 v[26:29], v[138:141], v[186:189], v[26:29]
	v_mfma_f32_16x16x32_bf16 v[26:29], v[142:145], v[190:193], v[26:29]
	s_setprio 0
	s_setprio 1
	v_mfma_f32_16x16x32_bf16 v[22:25], v[130:133], v[178:181], v[22:25]
	v_mfma_f32_16x16x32_bf16 v[22:25], v[134:137], v[182:185], v[22:25]
	v_mfma_f32_16x16x32_bf16 v[18:21], v[138:141], v[178:181], v[18:21]
	v_mfma_f32_16x16x32_bf16 v[18:21], v[142:145], v[182:185], v[18:21]
	s_setprio 0
	s_setprio 1
	v_mfma_f32_16x16x32_bf16 v[14:17], v[130:133], v[170:173], v[14:17]
	v_mfma_f32_16x16x32_bf16 v[14:17], v[134:137], v[174:177], v[14:17]
	v_mfma_f32_16x16x32_bf16 v[10:13], v[138:141], v[170:173], v[10:13]
	v_mfma_f32_16x16x32_bf16 v[10:13], v[142:145], v[174:177], v[10:13]
	s_setprio 0
	s_setprio 1
	v_mfma_f32_16x16x32_bf16 v[6:9], v[130:133], v[162:165], v[6:9]
	v_mfma_f32_16x16x32_bf16 v[6:9], v[134:137], v[166:169], v[6:9]
	s_setprio 2
	s_barrier
	v_mfma_f32_16x16x32_bf16 v[2:5], v[138:141], v[162:165], v[2:5]
	v_mfma_f32_16x16x32_bf16 v[2:5], v[142:145], v[166:169], v[2:5]
	s_setprio 0
	s_nop 0
	v_add_u32_e32 v142, 0x18000, v218
	v_add_u32_e32 v158, 0x1c000, v218
	ds_read_b128 v[130:133], v142
	ds_read_b128 v[134:137], v142 offset:1024
	ds_read_b128 v[138:141], v142 offset:2048
	ds_read_b128 v[142:145], v142 offset:3072
	ds_read_b128 v[146:149], v158
	ds_read_b128 v[150:153], v158 offset:1024
	ds_read_b128 v[154:157], v158 offset:2048
	ds_read_b128 v[158:161], v158 offset:3072
	ds_read_b128 v[162:165], v219 offset:32768
	ds_read_b128 v[166:169], v219 offset:33792
	ds_read_b128 v[170:173], v219 offset:34816
	ds_read_b128 v[174:177], v219 offset:35840
	ds_read_b128 v[178:181], v219 offset:36864
	ds_read_b128 v[182:185], v219 offset:37888
	ds_read_b128 v[186:189], v219 offset:38912
	ds_read_b128 v[190:193], v219 offset:39936
	s_add_u32 s52, s52, 0x4000
	s_addc_u32 s53, s53, 0
	s_mov_b32 m0, s76
	s_nop 0
	global_load_lds_dwordx4 v195, s[52:53]
	s_add_u32 m0, s76, 0x2000
	s_nop 0
	global_load_lds_dwordx4 v212, s[52:53]
	s_waitcnt vmcnt(8)
	s_waitcnt lgkmcnt(0)
	s_setprio 1
	s_barrier
	v_mfma_f32_16x16x32_bf16 v[126:129], v[130:133], v[162:165], v[126:129]
	v_mfma_f32_16x16x32_bf16 v[126:129], v[134:137], v[166:169], v[126:129]
	s_waitcnt lgkmcnt(5)
	v_mfma_f32_16x16x32_bf16 v[122:125], v[138:141], v[162:165], v[122:125]
	v_mfma_f32_16x16x32_bf16 v[122:125], v[142:145], v[166:169], v[122:125]
	s_waitcnt lgkmcnt(3)
	s_setprio 0
	s_setprio 1
	v_mfma_f32_16x16x32_bf16 v[118:121], v[130:133], v[170:173], v[118:121]
	v_mfma_f32_16x16x32_bf16 v[118:121], v[134:137], v[174:177], v[118:121]
	s_waitcnt lgkmcnt(1)
	v_mfma_f32_16x16x32_bf16 v[114:117], v[138:141], v[170:173], v[114:117]
	v_mfma_f32_16x16x32_bf16 v[114:117], v[142:145], v[174:177], v[114:117]
	s_setprio 0
	s_setprio 1
	v_mfma_f32_16x16x32_bf16 v[110:113], v[130:133], v[178:181], v[110:113]
	v_mfma_f32_16x16x32_bf16 v[110:113], v[134:137], v[182:185], v[110:113]
	v_mfma_f32_16x16x32_bf16 v[106:109], v[138:141], v[178:181], v[106:109]
	v_mfma_f32_16x16x32_bf16 v[106:109], v[142:145], v[182:185], v[106:109]
	s_setprio 0
	s_setprio 1
	v_mfma_f32_16x16x32_bf16 v[102:105], v[130:133], v[186:189], v[102:105]
	v_mfma_f32_16x16x32_bf16 v[102:105], v[134:137], v[190:193], v[102:105]
	s_waitcnt lgkmcnt(0)
	v_mfma_f32_16x16x32_bf16 v[98:101], v[138:141], v[186:189], v[98:101]
	v_mfma_f32_16x16x32_bf16 v[98:101], v[142:145], v[190:193], v[98:101]
	s_setprio 0
	s_setprio 1
	v_mfma_f32_16x16x32_bf16 v[94:97], v[146:149], v[162:165], v[94:97]
	v_mfma_f32_16x16x32_bf16 v[94:97], v[150:153], v[166:169], v[94:97]
	v_mfma_f32_16x16x32_bf16 v[90:93], v[154:157], v[162:165], v[90:93]
	v_mfma_f32_16x16x32_bf16 v[90:93], v[158:161], v[166:169], v[90:93]
	s_setprio 0
	s_setprio 1
	v_mfma_f32_16x16x32_bf16 v[86:89], v[146:149], v[170:173], v[86:89]
	v_mfma_f32_16x16x32_bf16 v[86:89], v[150:153], v[174:177], v[86:89]
	v_mfma_f32_16x16x32_bf16 v[82:85], v[154:157], v[170:173], v[82:85]
	v_mfma_f32_16x16x32_bf16 v[82:85], v[158:161], v[174:177], v[82:85]
	s_setprio 0
	s_setprio 1
	v_mfma_f32_16x16x32_bf16 v[78:81], v[146:149], v[178:181], v[78:81]
	v_mfma_f32_16x16x32_bf16 v[78:81], v[150:153], v[182:185], v[78:81]
	v_mfma_f32_16x16x32_bf16 v[74:77], v[154:157], v[178:181], v[74:77]
	v_mfma_f32_16x16x32_bf16 v[74:77], v[158:161], v[182:185], v[74:77]
	s_setprio 0
	s_setprio 1
	v_mfma_f32_16x16x32_bf16 v[70:73], v[146:149], v[186:189], v[70:73]
	v_mfma_f32_16x16x32_bf16 v[70:73], v[150:153], v[190:193], v[70:73]
	s_setprio 2
	s_barrier
	v_mfma_f32_16x16x32_bf16 v[66:69], v[154:157], v[186:189], v[66:69]
	v_mfma_f32_16x16x32_bf16 v[66:69], v[158:161], v[190:193], v[66:69]
	s_setprio 0
	s_nop 0
	ds_read_b128 v[162:165], v219 offset:49152
	ds_read_b128 v[166:169], v219 offset:50176
	ds_read_b128 v[170:173], v219 offset:51200
	ds_read_b128 v[174:177], v219 offset:52224
	ds_read_b128 v[178:181], v219 offset:53248
	ds_read_b128 v[182:185], v219 offset:54272
	ds_read_b128 v[186:189], v219 offset:55296
	ds_read_b128 v[190:193], v219 offset:56320
	s_mov_b32 m0, s80
	s_nop 0
	global_load_lds_dwordx4 v195, s[62:63]
	s_add_u32 m0, s80, 0x2000
	s_nop 0
	global_load_lds_dwordx4 v212, s[62:63]
	s_add_u32 s50, s50, 0xc000
	s_addc_u32 s51, s51, 0
	s_mov_b32 m0, s82
	s_nop 0
	global_load_lds_dwordx4 v195, s[50:51]
	s_add_u32 m0, s82, 0x2000
	s_nop 0
	global_load_lds_dwordx4 v212, s[50:51]
	s_nop 0
	s_mov_b32 m0, s81
	s_nop 0
	global_load_lds_dwordx4 v195, s[54:55]
	s_add_u32 m0, s81, 0x2000
	s_nop 0
	global_load_lds_dwordx4 v212, s[54:55]
	s_waitcnt vmcnt(8)
	s_waitcnt lgkmcnt(0)
	s_setprio 1
	s_barrier
	v_mfma_f32_16x16x32_bf16 v[62:65], v[130:133], v[162:165], v[62:65]
	v_mfma_f32_16x16x32_bf16 v[62:65], v[134:137], v[166:169], v[62:65]
	s_waitcnt lgkmcnt(5)
	v_mfma_f32_16x16x32_bf16 v[58:61], v[138:141], v[162:165], v[58:61]
	v_mfma_f32_16x16x32_bf16 v[58:61], v[142:145], v[166:169], v[58:61]
	s_waitcnt lgkmcnt(3)
	s_setprio 0
	s_setprio 1
	v_mfma_f32_16x16x32_bf16 v[54:57], v[130:133], v[170:173], v[54:57]
	v_mfma_f32_16x16x32_bf16 v[54:57], v[134:137], v[174:177], v[54:57]
	s_waitcnt lgkmcnt(1)
	v_mfma_f32_16x16x32_bf16 v[50:53], v[138:141], v[170:173], v[50:53]
	v_mfma_f32_16x16x32_bf16 v[50:53], v[142:145], v[174:177], v[50:53]
	s_setprio 0
	s_setprio 1
	v_mfma_f32_16x16x32_bf16 v[46:49], v[130:133], v[178:181], v[46:49]
	v_mfma_f32_16x16x32_bf16 v[46:49], v[134:137], v[182:185], v[46:49]
	v_mfma_f32_16x16x32_bf16 v[42:45], v[138:141], v[178:181], v[42:45]
	v_mfma_f32_16x16x32_bf16 v[42:45], v[142:145], v[182:185], v[42:45]
	s_setprio 0
	s_setprio 1
	v_mfma_f32_16x16x32_bf16 v[38:41], v[130:133], v[186:189], v[38:41]
	v_mfma_f32_16x16x32_bf16 v[38:41], v[134:137], v[190:193], v[38:41]
	s_waitcnt lgkmcnt(0)
	v_mfma_f32_16x16x32_bf16 v[34:37], v[138:141], v[186:189], v[34:37]
	v_mfma_f32_16x16x32_bf16 v[34:37], v[142:145], v[190:193], v[34:37]
	s_setprio 0
	s_setprio 1
	v_mfma_f32_16x16x32_bf16 v[30:33], v[146:149], v[162:165], v[30:33]
	v_mfma_f32_16x16x32_bf16 v[30:33], v[150:153], v[166:169], v[30:33]
	v_mfma_f32_16x16x32_bf16 v[26:29], v[154:157], v[162:165], v[26:29]
	v_mfma_f32_16x16x32_bf16 v[26:29], v[158:161], v[166:169], v[26:29]
	s_setprio 0
	s_setprio 1
	v_mfma_f32_16x16x32_bf16 v[22:25], v[146:149], v[170:173], v[22:25]
	v_mfma_f32_16x16x32_bf16 v[22:25], v[150:153], v[174:177], v[22:25]
	v_mfma_f32_16x16x32_bf16 v[18:21], v[154:157], v[170:173], v[18:21]
	v_mfma_f32_16x16x32_bf16 v[18:21], v[158:161], v[174:177], v[18:21]
	s_setprio 0
	s_setprio 1
	v_mfma_f32_16x16x32_bf16 v[14:17], v[146:149], v[178:181], v[14:17]
	v_mfma_f32_16x16x32_bf16 v[14:17], v[150:153], v[182:185], v[14:17]
	v_mfma_f32_16x16x32_bf16 v[10:13], v[154:157], v[178:181], v[10:13]
	v_mfma_f32_16x16x32_bf16 v[10:13], v[158:161], v[182:185], v[10:13]
	s_setprio 0
	s_setprio 1
	v_mfma_f32_16x16x32_bf16 v[6:9], v[146:149], v[186:189], v[6:9]
	v_mfma_f32_16x16x32_bf16 v[6:9], v[150:153], v[190:193], v[6:9]
	s_setprio 2
	s_barrier
	v_mfma_f32_16x16x32_bf16 v[2:5], v[154:157], v[186:189], v[2:5]
	v_mfma_f32_16x16x32_bf16 v[2:5], v[158:161], v[190:193], v[2:5]
	s_setprio 0
	s_nop 0
	s_cmp_gt_u32 s93, 41
	s_cbranch_scc1 .LBB0_368
	v_mov_b32_e32 v130, v198
	s_mov_b32 s93, s26
	s_branch .LBB0_343

.LBB0_519:
	ds_read_b128 v[130:133], v141
	ds_read_b128 v[134:137], v141 offset:1024
	ds_read_b128 v[146:149], v141 offset:2048
	ds_read_b128 v[150:153], v141 offset:3072
	ds_read_b128 v[154:157], v142
	ds_read_b128 v[158:161], v142 offset:1024
	ds_read_b128 v[162:165], v142 offset:2048
	ds_read_b128 v[166:169], v142 offset:3072
	s_add_u32 s24, s26, 0x10000
	s_addc_u32 s25, s27, 0
	s_cmp_eq_u32 s77, 12
	s_cselect_b32 s48, s17, s24
	s_cselect_b32 s49, s1, s25
	s_cselect_b32 s30, s23, s75
	s_cselect_b32 s31, s15, s76
	s_add_u32 s28, s48, 0x8000
	s_addc_u32 s29, s49, 0
	ds_read_b128 v[170:173], v143
	ds_read_b128 v[174:177], v143 offset:1024
	ds_read_b128 v[178:181], v143 offset:2048
	ds_read_b128 v[182:185], v143 offset:3072
	ds_read_b128 v[186:189], v143 offset:4096
	ds_read_b128 v[190:193], v143 offset:5120
	ds_read_b128 v[198:201], v143 offset:6144
	ds_read_b128 v[202:205], v143 offset:7168
	s_add_u32 s38, s30, 0x8000
	s_addc_u32 s39, s31, 0
	s_add_u32 s26, s26, 0xc000
	s_addc_u32 s27, s27, 0
	s_mov_b32 m0, s72
	s_nop 0
	global_load_lds_dwordx4 v195, s[26:27]
	s_add_u32 m0, s72, 0x2000
	s_nop 0
	global_load_lds_dwordx4 v212, s[26:27]
	s_waitcnt vmcnt(8)
	s_waitcnt lgkmcnt(0)
	s_setprio 1
	s_barrier
	v_mfma_f32_16x16x32_bf16 v[122:125], v[130:133], v[170:173], v[122:125]
	v_mfma_f32_16x16x32_bf16 v[122:125], v[134:137], v[174:177], v[122:125]
	s_waitcnt lgkmcnt(5)
	v_mfma_f32_16x16x32_bf16 v[126:129], v[146:149], v[170:173], v[126:129]
	v_mfma_f32_16x16x32_bf16 v[126:129], v[150:153], v[174:177], v[126:129]
	s_waitcnt lgkmcnt(3)
	s_setprio 0
	s_setprio 1
	v_mfma_f32_16x16x32_bf16 v[110:113], v[130:133], v[178:181], v[110:113]
	v_mfma_f32_16x16x32_bf16 v[110:113], v[134:137], v[182:185], v[110:113]
	s_waitcnt lgkmcnt(1)
	v_mfma_f32_16x16x32_bf16 v[106:109], v[146:149], v[178:181], v[106:109]
	v_mfma_f32_16x16x32_bf16 v[106:109], v[150:153], v[182:185], v[106:109]
	s_setprio 0
	s_setprio 1
	v_mfma_f32_16x16x32_bf16 v[94:97], v[130:133], v[186:189], v[94:97]
	v_mfma_f32_16x16x32_bf16 v[94:97], v[134:137], v[190:193], v[94:97]
	v_mfma_f32_16x16x32_bf16 v[90:93], v[146:149], v[186:189], v[90:93]
	v_mfma_f32_16x16x32_bf16 v[90:93], v[150:153], v[190:193], v[90:93]
	s_setprio 0
	s_setprio 1
	v_mfma_f32_16x16x32_bf16 v[78:81], v[130:133], v[198:201], v[78:81]
	v_mfma_f32_16x16x32_bf16 v[78:81], v[134:137], v[202:205], v[78:81]
	s_waitcnt lgkmcnt(0)
	v_mfma_f32_16x16x32_bf16 v[74:77], v[146:149], v[198:201], v[74:77]
	v_mfma_f32_16x16x32_bf16 v[74:77], v[150:153], v[202:205], v[74:77]
	s_setprio 0
	s_setprio 1
	v_mfma_f32_16x16x32_bf16 v[114:117], v[154:157], v[170:173], v[114:117]
	v_mfma_f32_16x16x32_bf16 v[114:117], v[158:161], v[174:177], v[114:117]
	v_mfma_f32_16x16x32_bf16 v[118:121], v[162:165], v[170:173], v[118:121]
	v_mfma_f32_16x16x32_bf16 v[118:121], v[166:169], v[174:177], v[118:121]
	s_setprio 0
	s_setprio 1
	v_mfma_f32_16x16x32_bf16 v[98:101], v[154:157], v[178:181], v[98:101]
	v_mfma_f32_16x16x32_bf16 v[98:101], v[158:161], v[182:185], v[98:101]
	v_mfma_f32_16x16x32_bf16 v[102:105], v[162:165], v[178:181], v[102:105]
	v_mfma_f32_16x16x32_bf16 v[102:105], v[166:169], v[182:185], v[102:105]
	s_setprio 0
	s_setprio 1
	v_mfma_f32_16x16x32_bf16 v[82:85], v[154:157], v[186:189], v[82:85]
	v_mfma_f32_16x16x32_bf16 v[82:85], v[158:161], v[190:193], v[82:85]
	v_mfma_f32_16x16x32_bf16 v[86:89], v[162:165], v[186:189], v[86:89]
	v_mfma_f32_16x16x32_bf16 v[86:89], v[166:169], v[190:193], v[86:89]
	s_setprio 0
	s_setprio 1
	v_mfma_f32_16x16x32_bf16 v[66:69], v[154:157], v[198:201], v[66:69]
	v_mfma_f32_16x16x32_bf16 v[66:69], v[158:161], v[202:205], v[66:69]
	s_setprio 2
	s_barrier
	v_mfma_f32_16x16x32_bf16 v[70:73], v[162:165], v[198:201], v[70:73]
	v_mfma_f32_16x16x32_bf16 v[70:73], v[166:169], v[202:205], v[70:73]
	s_setprio 0
	s_nop 0
	ds_read_b128 v[170:173], v143 offset:16384
	ds_read_b128 v[174:177], v143 offset:17408
	ds_read_b128 v[178:181], v143 offset:18432
	ds_read_b128 v[182:185], v143 offset:19456
	ds_read_b128 v[186:189], v143 offset:20480
	ds_read_b128 v[190:193], v143 offset:21504
	ds_read_b128 v[198:201], v143 offset:22528
	ds_read_b128 v[202:205], v143 offset:23552
	s_mov_b32 m0, s55
	s_nop 0
	global_load_lds_dwordx4 v195, s[30:31]
	s_add_u32 m0, s55, 0x2000
	s_nop 0
	global_load_lds_dwordx4 v212, s[30:31]
	s_add_u32 s26, s30, 0x4000
	s_addc_u32 s27, s31, 0
	s_mov_b32 m0, s62
	s_nop 0
	global_load_lds_dwordx4 v195, s[26:27]
	s_add_u32 m0, s62, 0x2000
	s_nop 0
	global_load_lds_dwordx4 v212, s[26:27]
	s_nop 0
	s_mov_b32 m0, s54
	s_nop 0
	global_load_lds_dwordx4 v195, s[48:49]
	s_add_u32 m0, s54, 0x2000
	s_nop 0
	global_load_lds_dwordx4 v212, s[48:49]
	s_waitcnt vmcnt(8)
	s_waitcnt lgkmcnt(0)
	s_setprio 1
	s_barrier
	v_mfma_f32_16x16x32_bf16 v[62:65], v[130:133], v[170:173], v[62:65]
	v_mfma_f32_16x16x32_bf16 v[62:65], v[134:137], v[174:177], v[62:65]
	s_waitcnt lgkmcnt(5)
	v_mfma_f32_16x16x32_bf16 v[58:61], v[146:149], v[170:173], v[58:61]
	v_mfma_f32_16x16x32_bf16 v[58:61], v[150:153], v[174:177], v[58:61]
	s_waitcnt lgkmcnt(3)
	s_setprio 0
	s_setprio 1
	v_mfma_f32_16x16x32_bf16 v[46:49], v[130:133], v[178:181], v[46:49]
	v_mfma_f32_16x16x32_bf16 v[46:49], v[134:137], v[182:185], v[46:49]
	s_waitcnt lgkmcnt(1)
	v_mfma_f32_16x16x32_bf16 v[42:45], v[146:149], v[178:181], v[42:45]
	v_mfma_f32_16x16x32_bf16 v[42:45], v[150:153], v[182:185], v[42:45]
	s_setprio 0
	s_setprio 1
	v_mfma_f32_16x16x32_bf16 v[30:33], v[130:133], v[186:189], v[30:33]
	v_mfma_f32_16x16x32_bf16 v[30:33], v[134:137], v[190:193], v[30:33]
	v_mfma_f32_16x16x32_bf16 v[26:29], v[146:149], v[186:189], v[26:29]
	v_mfma_f32_16x16x32_bf16 v[26:29], v[150:153], v[190:193], v[26:29]
	s_setprio 0
	s_setprio 1
	v_mfma_f32_16x16x32_bf16 v[14:17], v[130:133], v[198:201], v[14:17]
	v_mfma_f32_16x16x32_bf16 v[14:17], v[134:137], v[202:205], v[14:17]
	s_waitcnt lgkmcnt(0)
	v_mfma_f32_16x16x32_bf16 v[10:13], v[146:149], v[198:201], v[10:13]
	v_mfma_f32_16x16x32_bf16 v[10:13], v[150:153], v[202:205], v[10:13]
	s_setprio 0
	s_setprio 1
	v_mfma_f32_16x16x32_bf16 v[50:53], v[154:157], v[170:173], v[50:53]
	v_mfma_f32_16x16x32_bf16 v[50:53], v[158:161], v[174:177], v[50:53]
	v_mfma_f32_16x16x32_bf16 v[54:57], v[162:165], v[170:173], v[54:57]
	v_mfma_f32_16x16x32_bf16 v[54:57], v[166:169], v[174:177], v[54:57]
	s_setprio 0
	s_setprio 1
	v_mfma_f32_16x16x32_bf16 v[34:37], v[154:157], v[178:181], v[34:37]
	v_mfma_f32_16x16x32_bf16 v[34:37], v[158:161], v[182:185], v[34:37]
	v_mfma_f32_16x16x32_bf16 v[38:41], v[162:165], v[178:181], v[38:41]
	v_mfma_f32_16x16x32_bf16 v[38:41], v[166:169], v[182:185], v[38:41]
	s_setprio 0
	s_setprio 1
	v_mfma_f32_16x16x32_bf16 v[18:21], v[154:157], v[186:189], v[18:21]
	v_mfma_f32_16x16x32_bf16 v[18:21], v[158:161], v[190:193], v[18:21]
	v_mfma_f32_16x16x32_bf16 v[22:25], v[162:165], v[186:189], v[22:25]
	v_mfma_f32_16x16x32_bf16 v[22:25], v[166:169], v[190:193], v[22:25]
	s_setprio 0
	s_setprio 1
	v_mfma_f32_16x16x32_bf16 v[2:5], v[154:157], v[198:201], v[2:5]
	v_mfma_f32_16x16x32_bf16 v[2:5], v[158:161], v[202:205], v[2:5]
	s_setprio 2
	s_barrier
	v_mfma_f32_16x16x32_bf16 v[6:9], v[162:165], v[198:201], v[6:9]
	v_mfma_f32_16x16x32_bf16 v[6:9], v[166:169], v[202:205], v[6:9]
	s_setprio 0
	s_nop 0
	ds_read_b128 v[130:133], v144
	ds_read_b128 v[134:137], v144 offset:1024
	ds_read_b128 v[146:149], v144 offset:2048
	ds_read_b128 v[150:153], v144 offset:3072
	ds_read_b128 v[154:157], v145
	ds_read_b128 v[158:161], v145 offset:1024
	ds_read_b128 v[162:165], v145 offset:2048
	ds_read_b128 v[166:169], v145 offset:3072
	ds_read_b128 v[170:173], v143 offset:32768
	ds_read_b128 v[174:177], v143 offset:33792
	ds_read_b128 v[178:181], v143 offset:34816
	ds_read_b128 v[182:185], v143 offset:35840
	ds_read_b128 v[186:189], v143 offset:36864
	ds_read_b128 v[190:193], v143 offset:37888
	ds_read_b128 v[198:201], v143 offset:38912
	ds_read_b128 v[202:205], v143 offset:39936
	s_add_u32 s26, s48, 0x4000
	s_addc_u32 s27, s49, 0
	s_mov_b32 m0, s63
	s_nop 0
	global_load_lds_dwordx4 v195, s[26:27]
	s_add_u32 m0, s63, 0x2000
	s_nop 0
	global_load_lds_dwordx4 v212, s[26:27]
	s_waitcnt vmcnt(8)
	s_waitcnt lgkmcnt(0)
	s_setprio 1
	s_barrier
	v_mfma_f32_16x16x32_bf16 v[122:125], v[130:133], v[170:173], v[122:125]
	v_mfma_f32_16x16x32_bf16 v[122:125], v[134:137], v[174:177], v[122:125]
	s_waitcnt lgkmcnt(5)
	v_mfma_f32_16x16x32_bf16 v[126:129], v[146:149], v[170:173], v[126:129]
	v_mfma_f32_16x16x32_bf16 v[126:129], v[150:153], v[174:177], v[126:129]
	s_waitcnt lgkmcnt(3)
	s_setprio 0
	s_setprio 1
	v_mfma_f32_16x16x32_bf16 v[110:113], v[130:133], v[178:181], v[110:113]
	v_mfma_f32_16x16x32_bf16 v[110:113], v[134:137], v[182:185], v[110:113]
	s_waitcnt lgkmcnt(1)
	v_mfma_f32_16x16x32_bf16 v[106:109], v[146:149], v[178:181], v[106:109]
	v_mfma_f32_16x16x32_bf16 v[106:109], v[150:153], v[182:185], v[106:109]
	s_setprio 0
	s_setprio 1
	v_mfma_f32_16x16x32_bf16 v[94:97], v[130:133], v[186:189], v[94:97]
	v_mfma_f32_16x16x32_bf16 v[94:97], v[134:137], v[190:193], v[94:97]
	v_mfma_f32_16x16x32_bf16 v[90:93], v[146:149], v[186:189], v[90:93]
	v_mfma_f32_16x16x32_bf16 v[90:93], v[150:153], v[190:193], v[90:93]
	s_setprio 0
	s_setprio 1
	v_mfma_f32_16x16x32_bf16 v[78:81], v[130:133], v[198:201], v[78:81]
	v_mfma_f32_16x16x32_bf16 v[78:81], v[134:137], v[202:205], v[78:81]
	s_waitcnt lgkmcnt(0)
	v_mfma_f32_16x16x32_bf16 v[74:77], v[146:149], v[198:201], v[74:77]
	v_mfma_f32_16x16x32_bf16 v[74:77], v[150:153], v[202:205], v[74:77]
	s_setprio 0
	s_setprio 1
	v_mfma_f32_16x16x32_bf16 v[114:117], v[154:157], v[170:173], v[114:117]
	v_mfma_f32_16x16x32_bf16 v[114:117], v[158:161], v[174:177], v[114:117]
	v_mfma_f32_16x16x32_bf16 v[118:121], v[162:165], v[170:173], v[118:121]
	v_mfma_f32_16x16x32_bf16 v[118:121], v[166:169], v[174:177], v[118:121]
	s_setprio 0
	s_setprio 1
	v_mfma_f32_16x16x32_bf16 v[98:101], v[154:157], v[178:181], v[98:101]
	v_mfma_f32_16x16x32_bf16 v[98:101], v[158:161], v[182:185], v[98:101]
	v_mfma_f32_16x16x32_bf16 v[102:105], v[162:165], v[178:181], v[102:105]
	v_mfma_f32_16x16x32_bf16 v[102:105], v[166:169], v[182:185], v[102:105]
	s_setprio 0
	s_setprio 1
	v_mfma_f32_16x16x32_bf16 v[82:85], v[154:157], v[186:189], v[82:85]
	v_mfma_f32_16x16x32_bf16 v[82:85], v[158:161], v[190:193], v[82:85]
	v_mfma_f32_16x16x32_bf16 v[86:89], v[162:165], v[186:189], v[86:89]
	v_mfma_f32_16x16x32_bf16 v[86:89], v[166:169], v[190:193], v[86:89]
	s_setprio 0
	s_setprio 1
	v_mfma_f32_16x16x32_bf16 v[66:69], v[154:157], v[198:201], v[66:69]
	v_mfma_f32_16x16x32_bf16 v[66:69], v[158:161], v[202:205], v[66:69]
	s_setprio 2
	s_barrier
	v_mfma_f32_16x16x32_bf16 v[70:73], v[162:165], v[198:201], v[70:73]
	v_mfma_f32_16x16x32_bf16 v[70:73], v[166:169], v[202:205], v[70:73]
	s_setprio 0
	s_nop 0
	ds_read_b128 v[170:173], v143 offset:49152
	ds_read_b128 v[174:177], v143 offset:50176
	ds_read_b128 v[178:181], v143 offset:51200
	ds_read_b128 v[182:185], v143 offset:52224
	ds_read_b128 v[186:189], v143 offset:53248
	ds_read_b128 v[190:193], v143 offset:54272
	ds_read_b128 v[198:201], v143 offset:55296
	ds_read_b128 v[202:205], v143 offset:56320
	s_mov_b32 m0, s69
	s_nop 0
	global_load_lds_dwordx4 v195, s[38:39]
	s_add_u32 m0, s69, 0x2000
	s_nop 0
	global_load_lds_dwordx4 v212, s[38:39]
	s_add_u32 s26, s30, 0xc000
	s_addc_u32 s27, s31, 0
	s_mov_b32 m0, s71
	s_nop 0
	global_load_lds_dwordx4 v195, s[26:27]
	s_add_u32 m0, s71, 0x2000
	s_nop 0
	global_load_lds_dwordx4 v212, s[26:27]
	s_nop 0
	s_mov_b32 m0, s70
	s_nop 0
	global_load_lds_dwordx4 v195, s[28:29]
	s_add_u32 m0, s70, 0x2000
	s_nop 0
	global_load_lds_dwordx4 v212, s[28:29]
	s_waitcnt vmcnt(8)
	s_waitcnt lgkmcnt(0)
	s_setprio 1
	s_barrier
	v_mfma_f32_16x16x32_bf16 v[62:65], v[130:133], v[170:173], v[62:65]
	v_mfma_f32_16x16x32_bf16 v[62:65], v[134:137], v[174:177], v[62:65]
	s_waitcnt lgkmcnt(5)
	v_mfma_f32_16x16x32_bf16 v[58:61], v[146:149], v[170:173], v[58:61]
	v_mfma_f32_16x16x32_bf16 v[58:61], v[150:153], v[174:177], v[58:61]
	s_waitcnt lgkmcnt(3)
	s_setprio 0
	s_setprio 1
	v_mfma_f32_16x16x32_bf16 v[46:49], v[130:133], v[178:181], v[46:49]
	v_mfma_f32_16x16x32_bf16 v[46:49], v[134:137], v[182:185], v[46:49]
	s_waitcnt lgkmcnt(1)
	v_mfma_f32_16x16x32_bf16 v[42:45], v[146:149], v[178:181], v[42:45]
	v_mfma_f32_16x16x32_bf16 v[42:45], v[150:153], v[182:185], v[42:45]
	s_setprio 0
	s_setprio 1
	v_mfma_f32_16x16x32_bf16 v[30:33], v[130:133], v[186:189], v[30:33]
	v_mfma_f32_16x16x32_bf16 v[30:33], v[134:137], v[190:193], v[30:33]
	v_mfma_f32_16x16x32_bf16 v[26:29], v[146:149], v[186:189], v[26:29]
	v_mfma_f32_16x16x32_bf16 v[26:29], v[150:153], v[190:193], v[26:29]
	s_setprio 0
	s_setprio 1
	v_mfma_f32_16x16x32_bf16 v[14:17], v[130:133], v[198:201], v[14:17]
	v_mfma_f32_16x16x32_bf16 v[14:17], v[134:137], v[202:205], v[14:17]
	s_waitcnt lgkmcnt(0)
	v_mfma_f32_16x16x32_bf16 v[10:13], v[146:149], v[198:201], v[10:13]
	v_mfma_f32_16x16x32_bf16 v[10:13], v[150:153], v[202:205], v[10:13]
	s_setprio 0
	s_setprio 1
	v_mfma_f32_16x16x32_bf16 v[50:53], v[154:157], v[170:173], v[50:53]
	v_mfma_f32_16x16x32_bf16 v[50:53], v[158:161], v[174:177], v[50:53]
	v_mfma_f32_16x16x32_bf16 v[54:57], v[162:165], v[170:173], v[54:57]
	v_mfma_f32_16x16x32_bf16 v[54:57], v[166:169], v[174:177], v[54:57]
	s_setprio 0
	s_setprio 1
	v_mfma_f32_16x16x32_bf16 v[34:37], v[154:157], v[178:181], v[34:37]
	v_mfma_f32_16x16x32_bf16 v[34:37], v[158:161], v[182:185], v[34:37]
	v_mfma_f32_16x16x32_bf16 v[38:41], v[162:165], v[178:181], v[38:41]
	v_mfma_f32_16x16x32_bf16 v[38:41], v[166:169], v[182:185], v[38:41]
	s_setprio 0
	s_setprio 1
	v_mfma_f32_16x16x32_bf16 v[18:21], v[154:157], v[186:189], v[18:21]
	v_mfma_f32_16x16x32_bf16 v[18:21], v[158:161], v[190:193], v[18:21]
	v_mfma_f32_16x16x32_bf16 v[22:25], v[162:165], v[186:189], v[22:25]
	v_mfma_f32_16x16x32_bf16 v[22:25], v[166:169], v[190:193], v[22:25]
	s_setprio 0
	s_setprio 1
	v_mfma_f32_16x16x32_bf16 v[2:5], v[154:157], v[198:201], v[2:5]
	v_mfma_f32_16x16x32_bf16 v[2:5], v[158:161], v[202:205], v[2:5]
	s_setprio 2
	s_barrier
	v_mfma_f32_16x16x32_bf16 v[6:9], v[162:165], v[198:201], v[6:9]
	v_mfma_f32_16x16x32_bf16 v[6:9], v[166:169], v[202:205], v[6:9]
	s_setprio 0
	s_nop 0
	s_add_i32 s77, s77, 2
	s_add_u32 s75, s75, 0x10000
	s_addc_u32 s76, s76, 0
	s_cmp_gt_u32 s77, 13
	s_mov_b64 s[26:27], s[24:25]
	s_cbranch_scc0 .LBB0_519
	s_and_b64 vcc, exec, s[10:11]
	s_cbranch_vccz .LBB0_522
	s_barrier
	s_setprio 1

.LBB0_635:
	s_add_u32 s28, s24, 0x10000
	s_addc_u32 s29, s25, 0
	s_and_b64 s[24:25], s[22:23], exec
	s_cselect_b32 s25, s29, s15
	s_cselect_b32 s24, s28, s33
	s_add_u32 s3, s52, s3
	s_addc_u32 s28, s53, 0
	s_add_u32 s3, s3, 0x10000
	s_waitcnt vmcnt(8)
	s_addc_u32 s28, s28, 0
	s_waitcnt lgkmcnt(0)
	s_and_b64 s[22:23], s[22:23], exec
	s_cselect_b32 s23, s28, s13
	s_cselect_b32 s22, s3, s70
	s_setprio 1
	s_barrier
	v_mfma_f32_16x16x32_bf16 v[126:129], v[146:149], v[186:189], v[126:129]
	v_mfma_f32_16x16x32_bf16 v[126:129], v[150:153], v[190:193], v[126:129]
	s_waitcnt lgkmcnt(5)
	v_mfma_f32_16x16x32_bf16 v[122:125], v[154:157], v[186:189], v[122:125]
	v_mfma_f32_16x16x32_bf16 v[122:125], v[158:161], v[190:193], v[122:125]
	s_waitcnt lgkmcnt(3)
	s_setprio 0
	s_setprio 1
	v_mfma_f32_16x16x32_bf16 v[118:121], v[146:149], v[178:181], v[118:121]
	v_mfma_f32_16x16x32_bf16 v[118:121], v[150:153], v[182:185], v[118:121]
	s_waitcnt lgkmcnt(1)
	v_mfma_f32_16x16x32_bf16 v[114:117], v[154:157], v[178:181], v[114:117]
	v_mfma_f32_16x16x32_bf16 v[114:117], v[158:161], v[182:185], v[114:117]
	s_setprio 0
	s_setprio 1
	v_mfma_f32_16x16x32_bf16 v[110:113], v[146:149], v[170:173], v[110:113]
	v_mfma_f32_16x16x32_bf16 v[110:113], v[150:153], v[174:177], v[110:113]
	v_mfma_f32_16x16x32_bf16 v[106:109], v[154:157], v[170:173], v[106:109]
	v_mfma_f32_16x16x32_bf16 v[106:109], v[158:161], v[174:177], v[106:109]
	s_setprio 0
	s_setprio 1
	v_mfma_f32_16x16x32_bf16 v[102:105], v[146:149], v[162:165], v[102:105]
	v_mfma_f32_16x16x32_bf16 v[102:105], v[150:153], v[166:169], v[102:105]
	s_waitcnt lgkmcnt(0)
	v_mfma_f32_16x16x32_bf16 v[98:101], v[154:157], v[162:165], v[98:101]
	v_mfma_f32_16x16x32_bf16 v[98:101], v[158:161], v[166:169], v[98:101]
	s_setprio 0
	s_setprio 1
	v_mfma_f32_16x16x32_bf16 v[94:97], v[130:133], v[186:189], v[94:97]
	v_mfma_f32_16x16x32_bf16 v[94:97], v[134:137], v[190:193], v[94:97]
	v_mfma_f32_16x16x32_bf16 v[90:93], v[138:141], v[186:189], v[90:93]
	v_mfma_f32_16x16x32_bf16 v[90:93], v[142:145], v[190:193], v[90:93]
	s_setprio 0
	s_setprio 1
	v_mfma_f32_16x16x32_bf16 v[86:89], v[130:133], v[178:181], v[86:89]
	v_mfma_f32_16x16x32_bf16 v[86:89], v[134:137], v[182:185], v[86:89]
	v_mfma_f32_16x16x32_bf16 v[82:85], v[138:141], v[178:181], v[82:85]
	v_mfma_f32_16x16x32_bf16 v[82:85], v[142:145], v[182:185], v[82:85]
	s_setprio 0
	s_setprio 1
	v_mfma_f32_16x16x32_bf16 v[78:81], v[130:133], v[170:173], v[78:81]
	v_mfma_f32_16x16x32_bf16 v[78:81], v[134:137], v[174:177], v[78:81]
	v_mfma_f32_16x16x32_bf16 v[74:77], v[138:141], v[170:173], v[74:77]
	v_mfma_f32_16x16x32_bf16 v[74:77], v[142:145], v[174:177], v[74:77]
	s_setprio 0
	s_setprio 1
	v_mfma_f32_16x16x32_bf16 v[70:73], v[130:133], v[162:165], v[70:73]
	v_mfma_f32_16x16x32_bf16 v[70:73], v[134:137], v[166:169], v[70:73]
	s_setprio 2
	s_barrier
	v_mfma_f32_16x16x32_bf16 v[66:69], v[138:141], v[162:165], v[66:69]
	v_mfma_f32_16x16x32_bf16 v[66:69], v[142:145], v[166:169], v[66:69]
	s_setprio 0
	s_nop 0
	ds_read_b128 v[186:189], v219 offset:16384
	ds_read_b128 v[190:193], v219 offset:17408
	ds_read_b128 v[178:181], v219 offset:18432
	ds_read_b128 v[182:185], v219 offset:19456
	ds_read_b128 v[170:173], v219 offset:20480
	ds_read_b128 v[174:177], v219 offset:21504
	ds_read_b128 v[162:165], v219 offset:22528
	ds_read_b128 v[166:169], v219 offset:23552
	s_mov_b32 m0, s89
	s_nop 0
	global_load_lds_dwordx4 v195, s[22:23]
	s_add_u32 m0, s89, 0x2000
	s_nop 0
	global_load_lds_dwordx4 v213, s[22:23]
	s_add_u32 s28, s22, 0x4000
	s_addc_u32 s29, s23, 0
	s_mov_b32 m0, s54
	s_nop 0
	global_load_lds_dwordx4 v195, s[28:29]
	s_add_u32 m0, s54, 0x2000
	s_nop 0
	global_load_lds_dwordx4 v213, s[28:29]
	s_andn2_b64 vcc, exec, s[26:27]
	s_mov_b32 m0, s39
	s_nop 0
	global_load_lds_dwordx4 v195, s[24:25]
	s_add_u32 m0, s39, 0x2000
	s_nop 0
	global_load_lds_dwordx4 v213, s[24:25]
	s_cbranch_vccnz .LBB0_637
	v_mov_b32_e32 v2, 0
	v_mov_b32_e32 v3, v2
	v_mov_b32_e32 v4, v2
	v_mov_b32_e32 v5, v2
	v_mov_b32_e32 v6, v2
	v_mov_b32_e32 v7, v2
	v_mov_b32_e32 v8, v2
	v_mov_b32_e32 v9, v2
	v_mov_b32_e32 v10, v2
	v_mov_b32_e32 v11, v2
	v_mov_b32_e32 v12, v2
	v_mov_b32_e32 v13, v2
	v_mov_b32_e32 v14, v2
	v_mov_b32_e32 v15, v2
	v_mov_b32_e32 v16, v2
	v_mov_b32_e32 v17, v2
	v_mov_b32_e32 v18, v2
	v_mov_b32_e32 v19, v2
	v_mov_b32_e32 v20, v2
	v_mov_b32_e32 v21, v2
	v_mov_b32_e32 v22, v2
	v_mov_b32_e32 v23, v2
	v_mov_b32_e32 v24, v2
	v_mov_b32_e32 v25, v2
	v_mov_b32_e32 v26, v2
	v_mov_b32_e32 v27, v2
	v_mov_b32_e32 v28, v2
	v_mov_b32_e32 v29, v2
	v_mov_b32_e32 v30, v2
	v_mov_b32_e32 v31, v2
	v_mov_b32_e32 v32, v2
	v_mov_b32_e32 v33, v2
	v_mov_b32_e32 v34, v2
	v_mov_b32_e32 v35, v2
	v_mov_b32_e32 v36, v2
	v_mov_b32_e32 v37, v2
	v_mov_b32_e32 v38, v2
	v_mov_b32_e32 v39, v2
	v_mov_b32_e32 v40, v2
	v_mov_b32_e32 v41, v2
	v_mov_b32_e32 v42, v2
	v_mov_b32_e32 v43, v2
	v_mov_b32_e32 v44, v2
	v_mov_b32_e32 v45, v2
	v_mov_b32_e32 v46, v2
	v_mov_b32_e32 v47, v2
	v_mov_b32_e32 v48, v2
	v_mov_b32_e32 v49, v2
	v_mov_b32_e32 v50, v2
	v_mov_b32_e32 v51, v2
	v_mov_b32_e32 v52, v2
	v_mov_b32_e32 v53, v2
	v_mov_b32_e32 v54, v2
	v_mov_b32_e32 v55, v2
	v_mov_b32_e32 v56, v2
	v_mov_b32_e32 v57, v2
	v_mov_b32_e32 v58, v2
	v_mov_b32_e32 v59, v2
	v_mov_b32_e32 v60, v2
	v_mov_b32_e32 v61, v2
	v_mov_b32_e32 v62, v2
	v_mov_b32_e32 v63, v2
	v_mov_b32_e32 v64, v2
	v_mov_b32_e32 v65, v2
.LBB0_637:
	s_waitcnt vmcnt(8)
	s_add_u32 s26, s24, 0x8000
	s_waitcnt lgkmcnt(0)
	s_addc_u32 s27, s25, 0
	s_add_u32 s28, s22, 0x8000
	s_addc_u32 s29, s23, 0
	s_setprio 1
	s_barrier
	v_mfma_f32_16x16x32_bf16 v[62:65], v[146:149], v[186:189], v[62:65]
	v_mfma_f32_16x16x32_bf16 v[62:65], v[150:153], v[190:193], v[62:65]
	s_waitcnt lgkmcnt(5)
	v_mfma_f32_16x16x32_bf16 v[58:61], v[154:157], v[186:189], v[58:61]
	v_mfma_f32_16x16x32_bf16 v[58:61], v[158:161], v[190:193], v[58:61]
	s_waitcnt lgkmcnt(3)
	s_setprio 0
	s_setprio 1
	v_mfma_f32_16x16x32_bf16 v[54:57], v[146:149], v[178:181], v[54:57]
	v_mfma_f32_16x16x32_bf16 v[54:57], v[150:153], v[182:185], v[54:57]
	s_waitcnt lgkmcnt(1)
	v_mfma_f32_16x16x32_bf16 v[50:53], v[154:157], v[178:181], v[50:53]
	v_mfma_f32_16x16x32_bf16 v[50:53], v[158:161], v[182:185], v[50:53]
	s_setprio 0
	s_setprio 1
	v_mfma_f32_16x16x32_bf16 v[46:49], v[146:149], v[170:173], v[46:49]
	v_mfma_f32_16x16x32_bf16 v[46:49], v[150:153], v[174:177], v[46:49]
	v_mfma_f32_16x16x32_bf16 v[42:45], v[154:157], v[170:173], v[42:45]
	v_mfma_f32_16x16x32_bf16 v[42:45], v[158:161], v[174:177], v[42:45]
	s_setprio 0
	s_setprio 1
	v_mfma_f32_16x16x32_bf16 v[38:41], v[146:149], v[162:165], v[38:41]
	v_mfma_f32_16x16x32_bf16 v[38:41], v[150:153], v[166:169], v[38:41]
	s_waitcnt lgkmcnt(0)
	v_mfma_f32_16x16x32_bf16 v[34:37], v[154:157], v[162:165], v[34:37]
	v_mfma_f32_16x16x32_bf16 v[34:37], v[158:161], v[166:169], v[34:37]
	s_setprio 0
	s_setprio 1
	v_mfma_f32_16x16x32_bf16 v[30:33], v[130:133], v[186:189], v[30:33]
	v_mfma_f32_16x16x32_bf16 v[30:33], v[134:137], v[190:193], v[30:33]
	v_mfma_f32_16x16x32_bf16 v[26:29], v[138:141], v[186:189], v[26:29]
	v_mfma_f32_16x16x32_bf16 v[26:29], v[142:145], v[190:193], v[26:29]
	s_setprio 0
	s_setprio 1
	v_mfma_f32_16x16x32_bf16 v[22:25], v[130:133], v[178:181], v[22:25]
	v_mfma_f32_16x16x32_bf16 v[22:25], v[134:137], v[182:185], v[22:25]
	v_mfma_f32_16x16x32_bf16 v[18:21], v[138:141], v[178:181], v[18:21]
	v_mfma_f32_16x16x32_bf16 v[18:21], v[142:145], v[182:185], v[18:21]
	s_setprio 0
	s_setprio 1
	v_mfma_f32_16x16x32_bf16 v[14:17], v[130:133], v[170:173], v[14:17]
	v_mfma_f32_16x16x32_bf16 v[14:17], v[134:137], v[174:177], v[14:17]
	v_mfma_f32_16x16x32_bf16 v[10:13], v[138:141], v[170:173], v[10:13]
	v_mfma_f32_16x16x32_bf16 v[10:13], v[142:145], v[174:177], v[10:13]
	s_setprio 0
	s_setprio 1
	v_mfma_f32_16x16x32_bf16 v[6:9], v[130:133], v[162:165], v[6:9]
	v_mfma_f32_16x16x32_bf16 v[6:9], v[134:137], v[166:169], v[6:9]
	s_setprio 2
	s_barrier
	v_mfma_f32_16x16x32_bf16 v[2:5], v[138:141], v[162:165], v[2:5]
	v_mfma_f32_16x16x32_bf16 v[2:5], v[142:145], v[166:169], v[2:5]
	s_setprio 0
	s_nop 0
	v_add_u32_e32 v142, 0x18000, v218
	v_add_u32_e32 v158, 0x1c000, v218
	ds_read_b128 v[130:133], v142
	ds_read_b128 v[134:137], v142 offset:1024
	ds_read_b128 v[138:141], v142 offset:2048
	ds_read_b128 v[142:145], v142 offset:3072
	ds_read_b128 v[146:149], v158
	ds_read_b128 v[150:153], v158 offset:1024
	ds_read_b128 v[154:157], v158 offset:2048
	ds_read_b128 v[158:161], v158 offset:3072
	ds_read_b128 v[162:165], v219 offset:32768
	ds_read_b128 v[166:169], v219 offset:33792
	ds_read_b128 v[170:173], v219 offset:34816
	ds_read_b128 v[174:177], v219 offset:35840
	ds_read_b128 v[178:181], v219 offset:36864
	ds_read_b128 v[182:185], v219 offset:37888
	ds_read_b128 v[186:189], v219 offset:38912
	ds_read_b128 v[190:193], v219 offset:39936
	s_add_u32 s24, s24, 0x4000
	s_addc_u32 s25, s25, 0
	s_mov_b32 m0, s55
	s_nop 0
	global_load_lds_dwordx4 v195, s[24:25]
	s_add_u32 m0, s55, 0x2000
	s_nop 0
	global_load_lds_dwordx4 v213, s[24:25]
	s_waitcnt vmcnt(8)
	s_waitcnt lgkmcnt(0)
	s_setprio 1
	s_barrier
	v_mfma_f32_16x16x32_bf16 v[126:129], v[130:133], v[162:165], v[126:129]
	v_mfma_f32_16x16x32_bf16 v[126:129], v[134:137], v[166:169], v[126:129]
	s_waitcnt lgkmcnt(5)
	v_mfma_f32_16x16x32_bf16 v[122:125], v[138:141], v[162:165], v[122:125]
	v_mfma_f32_16x16x32_bf16 v[122:125], v[142:145], v[166:169], v[122:125]
	s_waitcnt lgkmcnt(3)
	s_setprio 0
	s_setprio 1
	v_mfma_f32_16x16x32_bf16 v[118:121], v[130:133], v[170:173], v[118:121]
	v_mfma_f32_16x16x32_bf16 v[118:121], v[134:137], v[174:177], v[118:121]
	s_waitcnt lgkmcnt(1)
	v_mfma_f32_16x16x32_bf16 v[114:117], v[138:141], v[170:173], v[114:117]
	v_mfma_f32_16x16x32_bf16 v[114:117], v[142:145], v[174:177], v[114:117]
	s_setprio 0
	s_setprio 1
	v_mfma_f32_16x16x32_bf16 v[110:113], v[130:133], v[178:181], v[110:113]
	v_mfma_f32_16x16x32_bf16 v[110:113], v[134:137], v[182:185], v[110:113]
	v_mfma_f32_16x16x32_bf16 v[106:109], v[138:141], v[178:181], v[106:109]
	v_mfma_f32_16x16x32_bf16 v[106:109], v[142:145], v[182:185], v[106:109]
	s_setprio 0
	s_setprio 1
	v_mfma_f32_16x16x32_bf16 v[102:105], v[130:133], v[186:189], v[102:105]
	v_mfma_f32_16x16x32_bf16 v[102:105], v[134:137], v[190:193], v[102:105]
	s_waitcnt lgkmcnt(0)
	v_mfma_f32_16x16x32_bf16 v[98:101], v[138:141], v[186:189], v[98:101]
	v_mfma_f32_16x16x32_bf16 v[98:101], v[142:145], v[190:193], v[98:101]
	s_setprio 0
	s_setprio 1
	v_mfma_f32_16x16x32_bf16 v[94:97], v[146:149], v[162:165], v[94:97]
	v_mfma_f32_16x16x32_bf16 v[94:97], v[150:153], v[166:169], v[94:97]
	v_mfma_f32_16x16x32_bf16 v[90:93], v[154:157], v[162:165], v[90:93]
	v_mfma_f32_16x16x32_bf16 v[90:93], v[158:161], v[166:169], v[90:93]
	s_setprio 0
	s_setprio 1
	v_mfma_f32_16x16x32_bf16 v[86:89], v[146:149], v[170:173], v[86:89]
	v_mfma_f32_16x16x32_bf16 v[86:89], v[150:153], v[174:177], v[86:89]
	v_mfma_f32_16x16x32_bf16 v[82:85], v[154:157], v[170:173], v[82:85]
	v_mfma_f32_16x16x32_bf16 v[82:85], v[158:161], v[174:177], v[82:85]
	s_setprio 0
	s_setprio 1
	v_mfma_f32_16x16x32_bf16 v[78:81], v[146:149], v[178:181], v[78:81]
	v_mfma_f32_16x16x32_bf16 v[78:81], v[150:153], v[182:185], v[78:81]
	v_mfma_f32_16x16x32_bf16 v[74:77], v[154:157], v[178:181], v[74:77]
	v_mfma_f32_16x16x32_bf16 v[74:77], v[158:161], v[182:185], v[74:77]
	s_setprio 0
	s_setprio 1
	v_mfma_f32_16x16x32_bf16 v[70:73], v[146:149], v[186:189], v[70:73]
	v_mfma_f32_16x16x32_bf16 v[70:73], v[150:153], v[190:193], v[70:73]
	s_setprio 2
	s_barrier
	v_mfma_f32_16x16x32_bf16 v[66:69], v[154:157], v[186:189], v[66:69]
	v_mfma_f32_16x16x32_bf16 v[66:69], v[158:161], v[190:193], v[66:69]
	s_setprio 0
	s_nop 0
	ds_read_b128 v[162:165], v219 offset:49152
	ds_read_b128 v[166:169], v219 offset:50176
	ds_read_b128 v[170:173], v219 offset:51200
	ds_read_b128 v[174:177], v219 offset:52224
	ds_read_b128 v[178:181], v219 offset:53248
	ds_read_b128 v[182:185], v219 offset:54272
	ds_read_b128 v[186:189], v219 offset:55296
	ds_read_b128 v[190:193], v219 offset:56320
	s_mov_b32 m0, s83
	s_nop 0
	global_load_lds_dwordx4 v195, s[28:29]
	s_add_u32 m0, s83, 0x2000
	s_nop 0
	global_load_lds_dwordx4 v213, s[28:29]
	s_add_u32 s22, s22, 0xc000
	s_addc_u32 s23, s23, 0
	s_mov_b32 m0, s91
	s_nop 0
	global_load_lds_dwordx4 v195, s[22:23]
	s_add_u32 m0, s91, 0x2000
	s_nop 0
	global_load_lds_dwordx4 v213, s[22:23]
	s_nop 0
	s_mov_b32 m0, s90
	s_nop 0
	global_load_lds_dwordx4 v195, s[26:27]
	s_add_u32 m0, s90, 0x2000
	s_nop 0
	global_load_lds_dwordx4 v213, s[26:27]
	s_waitcnt vmcnt(8)
	s_waitcnt lgkmcnt(0)
	s_setprio 1
	s_barrier
	v_mfma_f32_16x16x32_bf16 v[62:65], v[130:133], v[162:165], v[62:65]
	v_mfma_f32_16x16x32_bf16 v[62:65], v[134:137], v[166:169], v[62:65]
	s_waitcnt lgkmcnt(5)
	v_mfma_f32_16x16x32_bf16 v[58:61], v[138:141], v[162:165], v[58:61]
	v_mfma_f32_16x16x32_bf16 v[58:61], v[142:145], v[166:169], v[58:61]
	s_waitcnt lgkmcnt(3)
	s_setprio 0
	s_setprio 1
	v_mfma_f32_16x16x32_bf16 v[54:57], v[130:133], v[170:173], v[54:57]
	v_mfma_f32_16x16x32_bf16 v[54:57], v[134:137], v[174:177], v[54:57]
	s_waitcnt lgkmcnt(1)
	v_mfma_f32_16x16x32_bf16 v[50:53], v[138:141], v[170:173], v[50:53]
	v_mfma_f32_16x16x32_bf16 v[50:53], v[142:145], v[174:177], v[50:53]
	s_setprio 0
	s_setprio 1
	v_mfma_f32_16x16x32_bf16 v[46:49], v[130:133], v[178:181], v[46:49]
	v_mfma_f32_16x16x32_bf16 v[46:49], v[134:137], v[182:185], v[46:49]
	v_mfma_f32_16x16x32_bf16 v[42:45], v[138:141], v[178:181], v[42:45]
	v_mfma_f32_16x16x32_bf16 v[42:45], v[142:145], v[182:185], v[42:45]
	s_setprio 0
	s_setprio 1
	v_mfma_f32_16x16x32_bf16 v[38:41], v[130:133], v[186:189], v[38:41]
	v_mfma_f32_16x16x32_bf16 v[38:41], v[134:137], v[190:193], v[38:41]
	s_waitcnt lgkmcnt(0)
	v_mfma_f32_16x16x32_bf16 v[34:37], v[138:141], v[186:189], v[34:37]
	v_mfma_f32_16x16x32_bf16 v[34:37], v[142:145], v[190:193], v[34:37]
	s_setprio 0
	s_setprio 1
	v_mfma_f32_16x16x32_bf16 v[30:33], v[146:149], v[162:165], v[30:33]
	v_mfma_f32_16x16x32_bf16 v[30:33], v[150:153], v[166:169], v[30:33]
	v_mfma_f32_16x16x32_bf16 v[26:29], v[154:157], v[162:165], v[26:29]
	v_mfma_f32_16x16x32_bf16 v[26:29], v[158:161], v[166:169], v[26:29]
	s_setprio 0
	s_setprio 1
	v_mfma_f32_16x16x32_bf16 v[22:25], v[146:149], v[170:173], v[22:25]
	v_mfma_f32_16x16x32_bf16 v[22:25], v[150:153], v[174:177], v[22:25]
	v_mfma_f32_16x16x32_bf16 v[18:21], v[154:157], v[170:173], v[18:21]
	v_mfma_f32_16x16x32_bf16 v[18:21], v[158:161], v[174:177], v[18:21]
	s_setprio 0
	s_setprio 1
	v_mfma_f32_16x16x32_bf16 v[14:17], v[146:149], v[178:181], v[14:17]
	v_mfma_f32_16x16x32_bf16 v[14:17], v[150:153], v[182:185], v[14:17]
	v_mfma_f32_16x16x32_bf16 v[10:13], v[154:157], v[178:181], v[10:13]
	v_mfma_f32_16x16x32_bf16 v[10:13], v[158:161], v[182:185], v[10:13]
	s_setprio 0
	s_setprio 1
	v_mfma_f32_16x16x32_bf16 v[6:9], v[146:149], v[186:189], v[6:9]
	v_mfma_f32_16x16x32_bf16 v[6:9], v[150:153], v[190:193], v[6:9]
	s_setprio 2
	s_barrier
	v_mfma_f32_16x16x32_bf16 v[2:5], v[154:157], v[186:189], v[2:5]
	v_mfma_f32_16x16x32_bf16 v[2:5], v[158:161], v[190:193], v[2:5]
	s_setprio 0
	s_nop 0
	s_add_i32 s3, s71, 2
	s_cmp_gt_u32 s71, 13
	s_cbranch_scc1 .LBB0_639
	s_mov_b32 s71, s3
	s_branch .LBB0_616

.LBB0_1068:
	s_or_b64 exec, exec, s[62:63]
	s_add_u32 s88, s12, s0
	ds_read_b128 v[132:135], v214
	ds_read_b128 v[136:139], v214 offset:1024
	ds_read_b128 v[140:143], v214 offset:2048
	ds_read_b128 v[144:147], v214 offset:3072
	ds_read_b128 v[154:157], v215
	ds_read_b128 v[158:161], v215 offset:1024
	ds_read_b128 v[162:165], v215 offset:2048
	ds_read_b128 v[166:169], v215 offset:3072
	s_addc_u32 s89, s13, s1
	s_add_u32 s62, s88, 0x20000
	s_addc_u32 s63, s89, 0
	s_add_u32 s64, s94, s0
	s_addc_u32 s65, s96, s1
	s_cmp_eq_u32 s0, 0x60000
	s_cselect_b32 s68, s53, s62
	s_cselect_b32 s69, s33, s63
	s_cselect_b32 s63, s51, s65
	s_cselect_b32 s62, s95, s64
	s_add_u32 s64, s68, 0x8000
	s_addc_u32 s65, s69, 0
	s_add_u32 s66, s62, 0x8000
	s_addc_u32 s67, s63, 0
	ds_read_b128 v[170:173], v216
	ds_read_b128 v[174:177], v216 offset:1024
	ds_read_b128 v[178:181], v216 offset:2048
	ds_read_b128 v[182:185], v216 offset:3072
	ds_read_b128 v[186:189], v216 offset:4096
	ds_read_b128 v[190:193], v216 offset:5120
	ds_read_b128 v[198:201], v216 offset:6144
	ds_read_b128 v[202:205], v216 offset:7168
	s_add_u32 s88, s88, 0x1c000
	s_addc_u32 s89, s89, 0
	s_mov_b32 m0, s79
	s_nop 0
	global_load_lds_dwordx4 v195, s[88:89]
	s_add_u32 m0, s79, 0x2000
	s_nop 0
	global_load_lds_dwordx4 v212, s[88:89]
	s_waitcnt vmcnt(8)
	s_waitcnt lgkmcnt(0)
	s_setprio 1
	s_barrier
	v_mfma_f32_16x16x32_bf16 v[126:129], v[132:135], v[170:173], v[126:129]
	v_mfma_f32_16x16x32_bf16 v[126:129], v[136:139], v[174:177], v[126:129]
	s_waitcnt lgkmcnt(5)
	v_mfma_f32_16x16x32_bf16 v[122:125], v[140:143], v[170:173], v[122:125]
	v_mfma_f32_16x16x32_bf16 v[122:125], v[144:147], v[174:177], v[122:125]
	s_waitcnt lgkmcnt(3)
	s_setprio 0
	s_setprio 1
	v_mfma_f32_16x16x32_bf16 v[110:113], v[132:135], v[178:181], v[110:113]
	v_mfma_f32_16x16x32_bf16 v[110:113], v[136:139], v[182:185], v[110:113]
	s_waitcnt lgkmcnt(1)
	v_mfma_f32_16x16x32_bf16 v[106:109], v[140:143], v[178:181], v[106:109]
	v_mfma_f32_16x16x32_bf16 v[106:109], v[144:147], v[182:185], v[106:109]
	s_setprio 0
	s_setprio 1
	v_mfma_f32_16x16x32_bf16 v[94:97], v[132:135], v[186:189], v[94:97]
	v_mfma_f32_16x16x32_bf16 v[94:97], v[136:139], v[190:193], v[94:97]
	v_mfma_f32_16x16x32_bf16 v[90:93], v[140:143], v[186:189], v[90:93]
	v_mfma_f32_16x16x32_bf16 v[90:93], v[144:147], v[190:193], v[90:93]
	s_setprio 0
	s_setprio 1
	v_mfma_f32_16x16x32_bf16 v[78:81], v[132:135], v[198:201], v[78:81]
	v_mfma_f32_16x16x32_bf16 v[78:81], v[136:139], v[202:205], v[78:81]
	s_waitcnt lgkmcnt(0)
	v_mfma_f32_16x16x32_bf16 v[74:77], v[140:143], v[198:201], v[74:77]
	v_mfma_f32_16x16x32_bf16 v[74:77], v[144:147], v[202:205], v[74:77]
	s_setprio 0
	s_setprio 1
	v_mfma_f32_16x16x32_bf16 v[118:121], v[154:157], v[170:173], v[118:121]
	v_mfma_f32_16x16x32_bf16 v[118:121], v[158:161], v[174:177], v[118:121]
	v_mfma_f32_16x16x32_bf16 v[114:117], v[162:165], v[170:173], v[114:117]
	v_mfma_f32_16x16x32_bf16 v[114:117], v[166:169], v[174:177], v[114:117]
	s_setprio 0
	s_setprio 1
	v_mfma_f32_16x16x32_bf16 v[102:105], v[154:157], v[178:181], v[102:105]
	v_mfma_f32_16x16x32_bf16 v[102:105], v[158:161], v[182:185], v[102:105]
	v_mfma_f32_16x16x32_bf16 v[98:101], v[162:165], v[178:181], v[98:101]
	v_mfma_f32_16x16x32_bf16 v[98:101], v[166:169], v[182:185], v[98:101]
	s_setprio 0
	s_setprio 1
	v_mfma_f32_16x16x32_bf16 v[86:89], v[154:157], v[186:189], v[86:89]
	v_mfma_f32_16x16x32_bf16 v[86:89], v[158:161], v[190:193], v[86:89]
	v_mfma_f32_16x16x32_bf16 v[82:85], v[162:165], v[186:189], v[82:85]
	v_mfma_f32_16x16x32_bf16 v[82:85], v[166:169], v[190:193], v[82:85]
	s_setprio 0
	s_setprio 1
	v_mfma_f32_16x16x32_bf16 v[70:73], v[154:157], v[198:201], v[70:73]
	v_mfma_f32_16x16x32_bf16 v[70:73], v[158:161], v[202:205], v[70:73]
	s_setprio 2
	s_barrier
	v_mfma_f32_16x16x32_bf16 v[66:69], v[162:165], v[198:201], v[66:69]
	v_mfma_f32_16x16x32_bf16 v[66:69], v[166:169], v[202:205], v[66:69]
	s_setprio 0
	s_nop 0
	ds_read_b128 v[170:173], v216 offset:16384
	ds_read_b128 v[174:177], v216 offset:17408
	ds_read_b128 v[178:181], v216 offset:18432
	ds_read_b128 v[182:185], v216 offset:19456
	ds_read_b128 v[186:189], v216 offset:20480
	ds_read_b128 v[190:193], v216 offset:21504
	ds_read_b128 v[198:201], v216 offset:22528
	ds_read_b128 v[202:205], v216 offset:23552
	s_mov_b32 m0, s3
	s_nop 0
	global_load_lds_dwordx4 v195, s[62:63]
	s_add_u32 m0, s3, 0x2000
	s_nop 0
	global_load_lds_dwordx4 v212, s[62:63]
	s_add_u32 s88, s62, 0x4000
	s_addc_u32 s89, s63, 0
	s_mov_b32 m0, s71
	s_nop 0
	global_load_lds_dwordx4 v195, s[88:89]
	s_add_u32 m0, s71, 0x2000
	s_nop 0
	global_load_lds_dwordx4 v212, s[88:89]
	s_nop 0
	s_mov_b32 m0, s70
	s_nop 0
	global_load_lds_dwordx4 v195, s[68:69]
	s_add_u32 m0, s70, 0x2000
	s_nop 0
	global_load_lds_dwordx4 v212, s[68:69]
	s_waitcnt vmcnt(8)
	s_waitcnt lgkmcnt(0)
	s_setprio 1
	s_barrier
	v_mfma_f32_16x16x32_bf16 v[62:65], v[132:135], v[170:173], v[62:65]
	v_mfma_f32_16x16x32_bf16 v[62:65], v[136:139], v[174:177], v[62:65]
	s_waitcnt lgkmcnt(5)
	v_mfma_f32_16x16x32_bf16 v[58:61], v[140:143], v[170:173], v[58:61]
	v_mfma_f32_16x16x32_bf16 v[58:61], v[144:147], v[174:177], v[58:61]
	s_waitcnt lgkmcnt(3)
	s_setprio 0
	s_setprio 1
	v_mfma_f32_16x16x32_bf16 v[46:49], v[132:135], v[178:181], v[46:49]
	v_mfma_f32_16x16x32_bf16 v[46:49], v[136:139], v[182:185], v[46:49]
	s_waitcnt lgkmcnt(1)
	v_mfma_f32_16x16x32_bf16 v[42:45], v[140:143], v[178:181], v[42:45]
	v_mfma_f32_16x16x32_bf16 v[42:45], v[144:147], v[182:185], v[42:45]
	s_setprio 0
	s_setprio 1
	v_mfma_f32_16x16x32_bf16 v[30:33], v[132:135], v[186:189], v[30:33]
	v_mfma_f32_16x16x32_bf16 v[30:33], v[136:139], v[190:193], v[30:33]
	v_mfma_f32_16x16x32_bf16 v[26:29], v[140:143], v[186:189], v[26:29]
	v_mfma_f32_16x16x32_bf16 v[26:29], v[144:147], v[190:193], v[26:29]
	s_setprio 0
	s_setprio 1
	v_mfma_f32_16x16x32_bf16 v[14:17], v[132:135], v[198:201], v[14:17]
	v_mfma_f32_16x16x32_bf16 v[14:17], v[136:139], v[202:205], v[14:17]
	s_waitcnt lgkmcnt(0)
	v_mfma_f32_16x16x32_bf16 v[10:13], v[140:143], v[198:201], v[10:13]
	v_mfma_f32_16x16x32_bf16 v[10:13], v[144:147], v[202:205], v[10:13]
	s_setprio 0
	s_setprio 1
	v_mfma_f32_16x16x32_bf16 v[54:57], v[154:157], v[170:173], v[54:57]
	v_mfma_f32_16x16x32_bf16 v[54:57], v[158:161], v[174:177], v[54:57]
	v_mfma_f32_16x16x32_bf16 v[50:53], v[162:165], v[170:173], v[50:53]
	v_mfma_f32_16x16x32_bf16 v[50:53], v[166:169], v[174:177], v[50:53]
	s_setprio 0
	s_setprio 1
	v_mfma_f32_16x16x32_bf16 v[38:41], v[154:157], v[178:181], v[38:41]
	v_mfma_f32_16x16x32_bf16 v[38:41], v[158:161], v[182:185], v[38:41]
	v_mfma_f32_16x16x32_bf16 v[34:37], v[162:165], v[178:181], v[34:37]
	v_mfma_f32_16x16x32_bf16 v[34:37], v[166:169], v[182:185], v[34:37]
	s_setprio 0
	s_setprio 1
	v_mfma_f32_16x16x32_bf16 v[22:25], v[154:157], v[186:189], v[22:25]
	v_mfma_f32_16x16x32_bf16 v[22:25], v[158:161], v[190:193], v[22:25]
	v_mfma_f32_16x16x32_bf16 v[18:21], v[162:165], v[186:189], v[18:21]
	v_mfma_f32_16x16x32_bf16 v[18:21], v[166:169], v[190:193], v[18:21]
	s_setprio 0
	s_setprio 1
	v_mfma_f32_16x16x32_bf16 v[6:9], v[154:157], v[198:201], v[6:9]
	v_mfma_f32_16x16x32_bf16 v[6:9], v[158:161], v[202:205], v[6:9]
	s_setprio 2
	s_barrier
	v_mfma_f32_16x16x32_bf16 v[2:5], v[162:165], v[198:201], v[2:5]
	v_mfma_f32_16x16x32_bf16 v[2:5], v[166:169], v[202:205], v[2:5]
	s_setprio 0
	s_nop 0
	ds_read_b128 v[132:135], v217
	ds_read_b128 v[136:139], v217 offset:1024
	ds_read_b128 v[140:143], v217 offset:2048
	ds_read_b128 v[144:147], v217 offset:3072
	ds_read_b128 v[154:157], v218
	ds_read_b128 v[158:161], v218 offset:1024
	ds_read_b128 v[162:165], v218 offset:2048
	ds_read_b128 v[166:169], v218 offset:3072
	ds_read_b128 v[170:173], v216 offset:32768
	ds_read_b128 v[174:177], v216 offset:33792
	ds_read_b128 v[178:181], v216 offset:34816
	ds_read_b128 v[182:185], v216 offset:35840
	ds_read_b128 v[186:189], v216 offset:36864
	ds_read_b128 v[190:193], v216 offset:37888
	ds_read_b128 v[198:201], v216 offset:38912
	ds_read_b128 v[202:205], v216 offset:39936
	s_add_u32 s68, s68, 0x4000
	s_addc_u32 s69, s69, 0
	s_mov_b32 m0, s72
	s_nop 0
	global_load_lds_dwordx4 v195, s[68:69]
	s_add_u32 m0, s72, 0x2000
	s_nop 0
	global_load_lds_dwordx4 v212, s[68:69]
	s_waitcnt vmcnt(8)
	s_waitcnt lgkmcnt(0)
	s_setprio 1
	s_barrier
	v_mfma_f32_16x16x32_bf16 v[126:129], v[132:135], v[170:173], v[126:129]
	v_mfma_f32_16x16x32_bf16 v[126:129], v[136:139], v[174:177], v[126:129]
	s_waitcnt lgkmcnt(5)
	v_mfma_f32_16x16x32_bf16 v[122:125], v[140:143], v[170:173], v[122:125]
	v_mfma_f32_16x16x32_bf16 v[122:125], v[144:147], v[174:177], v[122:125]
	s_waitcnt lgkmcnt(3)
	s_setprio 0
	s_setprio 1
	v_mfma_f32_16x16x32_bf16 v[110:113], v[132:135], v[178:181], v[110:113]
	v_mfma_f32_16x16x32_bf16 v[110:113], v[136:139], v[182:185], v[110:113]
	s_waitcnt lgkmcnt(1)
	v_mfma_f32_16x16x32_bf16 v[106:109], v[140:143], v[178:181], v[106:109]
	v_mfma_f32_16x16x32_bf16 v[106:109], v[144:147], v[182:185], v[106:109]
	s_setprio 0
	s_setprio 1
	v_mfma_f32_16x16x32_bf16 v[94:97], v[132:135], v[186:189], v[94:97]
	v_mfma_f32_16x16x32_bf16 v[94:97], v[136:139], v[190:193], v[94:97]
	v_mfma_f32_16x16x32_bf16 v[90:93], v[140:143], v[186:189], v[90:93]
	v_mfma_f32_16x16x32_bf16 v[90:93], v[144:147], v[190:193], v[90:93]
	s_setprio 0
	s_setprio 1
	v_mfma_f32_16x16x32_bf16 v[78:81], v[132:135], v[198:201], v[78:81]
	v_mfma_f32_16x16x32_bf16 v[78:81], v[136:139], v[202:205], v[78:81]
	s_waitcnt lgkmcnt(0)
	v_mfma_f32_16x16x32_bf16 v[74:77], v[140:143], v[198:201], v[74:77]
	v_mfma_f32_16x16x32_bf16 v[74:77], v[144:147], v[202:205], v[74:77]
	s_setprio 0
	s_setprio 1
	v_mfma_f32_16x16x32_bf16 v[118:121], v[154:157], v[170:173], v[118:121]
	v_mfma_f32_16x16x32_bf16 v[118:121], v[158:161], v[174:177], v[118:121]
	v_mfma_f32_16x16x32_bf16 v[114:117], v[162:165], v[170:173], v[114:117]
	v_mfma_f32_16x16x32_bf16 v[114:117], v[166:169], v[174:177], v[114:117]
	s_setprio 0
	s_setprio 1
	v_mfma_f32_16x16x32_bf16 v[102:105], v[154:157], v[178:181], v[102:105]
	v_mfma_f32_16x16x32_bf16 v[102:105], v[158:161], v[182:185], v[102:105]
	v_mfma_f32_16x16x32_bf16 v[98:101], v[162:165], v[178:181], v[98:101]
	v_mfma_f32_16x16x32_bf16 v[98:101], v[166:169], v[182:185], v[98:101]
	s_setprio 0
	s_setprio 1
	v_mfma_f32_16x16x32_bf16 v[86:89], v[154:157], v[186:189], v[86:89]
	v_mfma_f32_16x16x32_bf16 v[86:89], v[158:161], v[190:193], v[86:89]
	v_mfma_f32_16x16x32_bf16 v[82:85], v[162:165], v[186:189], v[82:85]
	v_mfma_f32_16x16x32_bf16 v[82:85], v[166:169], v[190:193], v[82:85]
	s_setprio 0
	s_setprio 1
	v_mfma_f32_16x16x32_bf16 v[70:73], v[154:157], v[198:201], v[70:73]
	v_mfma_f32_16x16x32_bf16 v[70:73], v[158:161], v[202:205], v[70:73]
	s_setprio 2
	s_barrier
	v_mfma_f32_16x16x32_bf16 v[66:69], v[162:165], v[198:201], v[66:69]
	v_mfma_f32_16x16x32_bf16 v[66:69], v[166:169], v[202:205], v[66:69]
	s_setprio 0
	s_nop 0
	ds_read_b128 v[170:173], v216 offset:49152
	ds_read_b128 v[174:177], v216 offset:50176
	ds_read_b128 v[178:181], v216 offset:51200
	ds_read_b128 v[182:185], v216 offset:52224
	ds_read_b128 v[186:189], v216 offset:53248
	ds_read_b128 v[190:193], v216 offset:54272
	ds_read_b128 v[198:201], v216 offset:55296
	ds_read_b128 v[202:205], v216 offset:56320
	s_mov_b32 m0, s76
	s_nop 0
	global_load_lds_dwordx4 v195, s[66:67]
	s_add_u32 m0, s76, 0x2000
	s_nop 0
	global_load_lds_dwordx4 v212, s[66:67]
	s_add_u32 s62, s62, 0xc000
	s_addc_u32 s63, s63, 0
	s_mov_b32 m0, s78
	s_nop 0
	global_load_lds_dwordx4 v195, s[62:63]
	s_add_u32 m0, s78, 0x2000
	s_nop 0
	global_load_lds_dwordx4 v212, s[62:63]
	s_nop 0
	s_mov_b32 m0, s77
	s_nop 0
	global_load_lds_dwordx4 v195, s[64:65]
	s_add_u32 m0, s77, 0x2000
	s_nop 0
	global_load_lds_dwordx4 v212, s[64:65]
	s_waitcnt vmcnt(8)
	s_waitcnt lgkmcnt(0)
	s_setprio 1
	s_barrier
	v_mfma_f32_16x16x32_bf16 v[62:65], v[132:135], v[170:173], v[62:65]
	v_mfma_f32_16x16x32_bf16 v[62:65], v[136:139], v[174:177], v[62:65]
	s_waitcnt lgkmcnt(5)
	v_mfma_f32_16x16x32_bf16 v[58:61], v[140:143], v[170:173], v[58:61]
	v_mfma_f32_16x16x32_bf16 v[58:61], v[144:147], v[174:177], v[58:61]
	s_waitcnt lgkmcnt(3)
	s_setprio 0
	s_setprio 1
	v_mfma_f32_16x16x32_bf16 v[46:49], v[132:135], v[178:181], v[46:49]
	v_mfma_f32_16x16x32_bf16 v[46:49], v[136:139], v[182:185], v[46:49]
	s_waitcnt lgkmcnt(1)
	v_mfma_f32_16x16x32_bf16 v[42:45], v[140:143], v[178:181], v[42:45]
	v_mfma_f32_16x16x32_bf16 v[42:45], v[144:147], v[182:185], v[42:45]
	s_setprio 0
	s_setprio 1
	v_mfma_f32_16x16x32_bf16 v[30:33], v[132:135], v[186:189], v[30:33]
	v_mfma_f32_16x16x32_bf16 v[30:33], v[136:139], v[190:193], v[30:33]
	v_mfma_f32_16x16x32_bf16 v[26:29], v[140:143], v[186:189], v[26:29]
	v_mfma_f32_16x16x32_bf16 v[26:29], v[144:147], v[190:193], v[26:29]
	s_setprio 0
	s_setprio 1
	v_mfma_f32_16x16x32_bf16 v[14:17], v[132:135], v[198:201], v[14:17]
	v_mfma_f32_16x16x32_bf16 v[14:17], v[136:139], v[202:205], v[14:17]
	s_waitcnt lgkmcnt(0)
	v_mfma_f32_16x16x32_bf16 v[10:13], v[140:143], v[198:201], v[10:13]
	v_mfma_f32_16x16x32_bf16 v[10:13], v[144:147], v[202:205], v[10:13]
	s_setprio 0
	s_setprio 1
	v_mfma_f32_16x16x32_bf16 v[54:57], v[154:157], v[170:173], v[54:57]
	v_mfma_f32_16x16x32_bf16 v[54:57], v[158:161], v[174:177], v[54:57]
	v_mfma_f32_16x16x32_bf16 v[50:53], v[162:165], v[170:173], v[50:53]
	v_mfma_f32_16x16x32_bf16 v[50:53], v[166:169], v[174:177], v[50:53]
	s_setprio 0
	s_setprio 1
	v_mfma_f32_16x16x32_bf16 v[38:41], v[154:157], v[178:181], v[38:41]
	v_mfma_f32_16x16x32_bf16 v[38:41], v[158:161], v[182:185], v[38:41]
	v_mfma_f32_16x16x32_bf16 v[34:37], v[162:165], v[178:181], v[34:37]
	v_mfma_f32_16x16x32_bf16 v[34:37], v[166:169], v[182:185], v[34:37]
	s_setprio 0
	s_setprio 1
	v_mfma_f32_16x16x32_bf16 v[22:25], v[154:157], v[186:189], v[22:25]
	v_mfma_f32_16x16x32_bf16 v[22:25], v[158:161], v[190:193], v[22:25]
	v_mfma_f32_16x16x32_bf16 v[18:21], v[162:165], v[186:189], v[18:21]
	v_mfma_f32_16x16x32_bf16 v[18:21], v[166:169], v[190:193], v[18:21]
	s_setprio 0
	s_setprio 1
	v_mfma_f32_16x16x32_bf16 v[6:9], v[154:157], v[198:201], v[6:9]
	v_mfma_f32_16x16x32_bf16 v[6:9], v[158:161], v[202:205], v[6:9]
	s_setprio 2
	s_barrier
	v_mfma_f32_16x16x32_bf16 v[2:5], v[162:165], v[198:201], v[2:5]
	v_mfma_f32_16x16x32_bf16 v[2:5], v[166:169], v[202:205], v[2:5]
	s_setprio 0
	s_nop 0
	s_add_i32 s97, s97, 2
	s_add_u32 s0, s0, 0x10000
	s_addc_u32 s1, s1, 0
	s_cmp_gt_u32 s97, 13
	s_cbranch_scc1 .LBB0_1070
	v_mov_b32_e32 v131, v130
	s_branch .LBB0_1066

.LBB0_1336:
	s_add_u32 s50, s46, 0x10000
	s_addc_u32 s51, s47, 0
	s_and_b64 s[46:47], s[42:43], exec
	s_cselect_b32 s47, s51, s23
	s_cselect_b32 s46, s50, s75
	s_add_u32 s13, s16, s13
	s_addc_u32 s50, s17, 0
	s_add_u32 s13, s13, 0x10000
	s_waitcnt vmcnt(8)
	s_addc_u32 s50, s50, 0
	s_waitcnt lgkmcnt(0)
	s_and_b64 s[42:43], s[42:43], exec
	s_cselect_b32 s43, s50, s25
	s_cselect_b32 s42, s13, s76
	s_setprio 1
	s_barrier
	v_mfma_f32_16x16x32_bf16 v[126:129], v[146:149], v[186:189], v[126:129]
	v_mfma_f32_16x16x32_bf16 v[126:129], v[150:153], v[190:193], v[126:129]
	s_waitcnt lgkmcnt(5)
	v_mfma_f32_16x16x32_bf16 v[122:125], v[154:157], v[186:189], v[122:125]
	v_mfma_f32_16x16x32_bf16 v[122:125], v[158:161], v[190:193], v[122:125]
	s_waitcnt lgkmcnt(3)
	s_setprio 0
	s_setprio 1
	v_mfma_f32_16x16x32_bf16 v[118:121], v[146:149], v[178:181], v[118:121]
	v_mfma_f32_16x16x32_bf16 v[118:121], v[150:153], v[182:185], v[118:121]
	s_waitcnt lgkmcnt(1)
	v_mfma_f32_16x16x32_bf16 v[114:117], v[154:157], v[178:181], v[114:117]
	v_mfma_f32_16x16x32_bf16 v[114:117], v[158:161], v[182:185], v[114:117]
	s_setprio 0
	s_setprio 1
	v_mfma_f32_16x16x32_bf16 v[110:113], v[146:149], v[170:173], v[110:113]
	v_mfma_f32_16x16x32_bf16 v[110:113], v[150:153], v[174:177], v[110:113]
	v_mfma_f32_16x16x32_bf16 v[106:109], v[154:157], v[170:173], v[106:109]
	v_mfma_f32_16x16x32_bf16 v[106:109], v[158:161], v[174:177], v[106:109]
	s_setprio 0
	s_setprio 1
	v_mfma_f32_16x16x32_bf16 v[102:105], v[146:149], v[162:165], v[102:105]
	v_mfma_f32_16x16x32_bf16 v[102:105], v[150:153], v[166:169], v[102:105]
	s_waitcnt lgkmcnt(0)
	v_mfma_f32_16x16x32_bf16 v[98:101], v[154:157], v[162:165], v[98:101]
	v_mfma_f32_16x16x32_bf16 v[98:101], v[158:161], v[166:169], v[98:101]
	s_setprio 0
	s_setprio 1
	v_mfma_f32_16x16x32_bf16 v[94:97], v[130:133], v[186:189], v[94:97]
	v_mfma_f32_16x16x32_bf16 v[94:97], v[134:137], v[190:193], v[94:97]
	v_mfma_f32_16x16x32_bf16 v[90:93], v[138:141], v[186:189], v[90:93]
	v_mfma_f32_16x16x32_bf16 v[90:93], v[142:145], v[190:193], v[90:93]
	s_setprio 0
	s_setprio 1
	v_mfma_f32_16x16x32_bf16 v[86:89], v[130:133], v[178:181], v[86:89]
	v_mfma_f32_16x16x32_bf16 v[86:89], v[134:137], v[182:185], v[86:89]
	v_mfma_f32_16x16x32_bf16 v[82:85], v[138:141], v[178:181], v[82:85]
	v_mfma_f32_16x16x32_bf16 v[82:85], v[142:145], v[182:185], v[82:85]
	s_setprio 0
	s_setprio 1
	v_mfma_f32_16x16x32_bf16 v[78:81], v[130:133], v[170:173], v[78:81]
	v_mfma_f32_16x16x32_bf16 v[78:81], v[134:137], v[174:177], v[78:81]
	v_mfma_f32_16x16x32_bf16 v[74:77], v[138:141], v[170:173], v[74:77]
	v_mfma_f32_16x16x32_bf16 v[74:77], v[142:145], v[174:177], v[74:77]
	s_setprio 0
	s_setprio 1
	v_mfma_f32_16x16x32_bf16 v[70:73], v[130:133], v[162:165], v[70:73]
	v_mfma_f32_16x16x32_bf16 v[70:73], v[134:137], v[166:169], v[70:73]
	s_setprio 2
	s_barrier
	v_mfma_f32_16x16x32_bf16 v[66:69], v[138:141], v[162:165], v[66:69]
	v_mfma_f32_16x16x32_bf16 v[66:69], v[142:145], v[166:169], v[66:69]
	s_setprio 0
	s_nop 0
	ds_read_b128 v[186:189], v208 offset:16384
	ds_read_b128 v[190:193], v208 offset:17408
	ds_read_b128 v[178:181], v208 offset:18432
	ds_read_b128 v[182:185], v208 offset:19456
	ds_read_b128 v[170:173], v208 offset:20480
	ds_read_b128 v[174:177], v208 offset:21504
	ds_read_b128 v[162:165], v208 offset:22528
	ds_read_b128 v[166:169], v208 offset:23552
	s_mov_b32 m0, s58
	s_nop 0
	global_load_lds_dwordx4 v202, s[42:43]
	s_add_u32 m0, s58, 0x2000
	s_nop 0
	global_load_lds_dwordx4 v203, s[42:43]
	s_add_u32 s50, s42, 0x4000
	s_addc_u32 s51, s43, 0
	s_mov_b32 m0, s59
	s_nop 0
	global_load_lds_dwordx4 v202, s[50:51]
	s_add_u32 m0, s59, 0x2000
	s_nop 0
	global_load_lds_dwordx4 v203, s[50:51]
	s_andn2_b64 vcc, exec, s[48:49]
	s_mov_b32 m0, s7
	s_nop 0
	global_load_lds_dwordx4 v202, s[46:47]
	s_add_u32 m0, s7, 0x2000
	s_nop 0
	global_load_lds_dwordx4 v203, s[46:47]
	s_cbranch_vccnz .LBB0_1338
	v_mov_b32_e32 v2, 0
	v_mov_b32_e32 v3, v2
	v_mov_b32_e32 v4, v2
	v_mov_b32_e32 v5, v2
	v_mov_b32_e32 v6, v2
	v_mov_b32_e32 v7, v2
	v_mov_b32_e32 v8, v2
	v_mov_b32_e32 v9, v2
	v_mov_b32_e32 v10, v2
	v_mov_b32_e32 v11, v2
	v_mov_b32_e32 v12, v2
	v_mov_b32_e32 v13, v2
	v_mov_b32_e32 v14, v2
	v_mov_b32_e32 v15, v2
	v_mov_b32_e32 v16, v2
	v_mov_b32_e32 v17, v2
	v_mov_b32_e32 v18, v2
	v_mov_b32_e32 v19, v2
	v_mov_b32_e32 v20, v2
	v_mov_b32_e32 v21, v2
	v_mov_b32_e32 v22, v2
	v_mov_b32_e32 v23, v2
	v_mov_b32_e32 v24, v2
	v_mov_b32_e32 v25, v2
	v_mov_b32_e32 v26, v2
	v_mov_b32_e32 v27, v2
	v_mov_b32_e32 v28, v2
	v_mov_b32_e32 v29, v2
	v_mov_b32_e32 v30, v2
	v_mov_b32_e32 v31, v2
	v_mov_b32_e32 v32, v2
	v_mov_b32_e32 v33, v2
	v_mov_b32_e32 v34, v2
	v_mov_b32_e32 v35, v2
	v_mov_b32_e32 v36, v2
	v_mov_b32_e32 v37, v2
	v_mov_b32_e32 v38, v2
	v_mov_b32_e32 v39, v2
	v_mov_b32_e32 v40, v2
	v_mov_b32_e32 v41, v2
	v_mov_b32_e32 v42, v2
	v_mov_b32_e32 v43, v2
	v_mov_b32_e32 v44, v2
	v_mov_b32_e32 v45, v2
	v_mov_b32_e32 v46, v2
	v_mov_b32_e32 v47, v2
	v_mov_b32_e32 v48, v2
	v_mov_b32_e32 v49, v2
	v_mov_b32_e32 v50, v2
	v_mov_b32_e32 v51, v2
	v_mov_b32_e32 v52, v2
	v_mov_b32_e32 v53, v2
	v_mov_b32_e32 v54, v2
	v_mov_b32_e32 v55, v2
	v_mov_b32_e32 v56, v2
	v_mov_b32_e32 v57, v2
	v_mov_b32_e32 v58, v2
	v_mov_b32_e32 v59, v2
	v_mov_b32_e32 v60, v2
	v_mov_b32_e32 v61, v2
	v_mov_b32_e32 v62, v2
	v_mov_b32_e32 v63, v2
	v_mov_b32_e32 v64, v2
	v_mov_b32_e32 v65, v2
.LBB0_1338:
	s_waitcnt vmcnt(8)
	s_add_u32 s48, s46, 0x8000
	s_waitcnt lgkmcnt(0)
	s_addc_u32 s49, s47, 0
	s_add_u32 s50, s42, 0x8000
	s_addc_u32 s51, s43, 0
	s_setprio 1
	s_barrier
	v_mfma_f32_16x16x32_bf16 v[62:65], v[146:149], v[186:189], v[62:65]
	v_mfma_f32_16x16x32_bf16 v[62:65], v[150:153], v[190:193], v[62:65]
	s_waitcnt lgkmcnt(5)
	v_mfma_f32_16x16x32_bf16 v[58:61], v[154:157], v[186:189], v[58:61]
	v_mfma_f32_16x16x32_bf16 v[58:61], v[158:161], v[190:193], v[58:61]
	s_waitcnt lgkmcnt(3)
	s_setprio 0
	s_setprio 1
	v_mfma_f32_16x16x32_bf16 v[54:57], v[146:149], v[178:181], v[54:57]
	v_mfma_f32_16x16x32_bf16 v[54:57], v[150:153], v[182:185], v[54:57]
	s_waitcnt lgkmcnt(1)
	v_mfma_f32_16x16x32_bf16 v[50:53], v[154:157], v[178:181], v[50:53]
	v_mfma_f32_16x16x32_bf16 v[50:53], v[158:161], v[182:185], v[50:53]
	s_setprio 0
	s_setprio 1
	v_mfma_f32_16x16x32_bf16 v[46:49], v[146:149], v[170:173], v[46:49]
	v_mfma_f32_16x16x32_bf16 v[46:49], v[150:153], v[174:177], v[46:49]
	v_mfma_f32_16x16x32_bf16 v[42:45], v[154:157], v[170:173], v[42:45]
	v_mfma_f32_16x16x32_bf16 v[42:45], v[158:161], v[174:177], v[42:45]
	s_setprio 0
	s_setprio 1
	v_mfma_f32_16x16x32_bf16 v[38:41], v[146:149], v[162:165], v[38:41]
	v_mfma_f32_16x16x32_bf16 v[38:41], v[150:153], v[166:169], v[38:41]
	s_waitcnt lgkmcnt(0)
	v_mfma_f32_16x16x32_bf16 v[34:37], v[154:157], v[162:165], v[34:37]
	v_mfma_f32_16x16x32_bf16 v[34:37], v[158:161], v[166:169], v[34:37]
	s_setprio 0
	s_setprio 1
	v_mfma_f32_16x16x32_bf16 v[30:33], v[130:133], v[186:189], v[30:33]
	v_mfma_f32_16x16x32_bf16 v[30:33], v[134:137], v[190:193], v[30:33]
	v_mfma_f32_16x16x32_bf16 v[26:29], v[138:141], v[186:189], v[26:29]
	v_mfma_f32_16x16x32_bf16 v[26:29], v[142:145], v[190:193], v[26:29]
	s_setprio 0
	s_setprio 1
	v_mfma_f32_16x16x32_bf16 v[22:25], v[130:133], v[178:181], v[22:25]
	v_mfma_f32_16x16x32_bf16 v[22:25], v[134:137], v[182:185], v[22:25]
	v_mfma_f32_16x16x32_bf16 v[18:21], v[138:141], v[178:181], v[18:21]
	v_mfma_f32_16x16x32_bf16 v[18:21], v[142:145], v[182:185], v[18:21]
	s_setprio 0
	s_setprio 1
	v_mfma_f32_16x16x32_bf16 v[14:17], v[130:133], v[170:173], v[14:17]
	v_mfma_f32_16x16x32_bf16 v[14:17], v[134:137], v[174:177], v[14:17]
	v_mfma_f32_16x16x32_bf16 v[10:13], v[138:141], v[170:173], v[10:13]
	v_mfma_f32_16x16x32_bf16 v[10:13], v[142:145], v[174:177], v[10:13]
	s_setprio 0
	s_setprio 1
	v_mfma_f32_16x16x32_bf16 v[6:9], v[130:133], v[162:165], v[6:9]
	v_mfma_f32_16x16x32_bf16 v[6:9], v[134:137], v[166:169], v[6:9]
	s_setprio 2
	s_barrier
	v_mfma_f32_16x16x32_bf16 v[2:5], v[138:141], v[162:165], v[2:5]
	v_mfma_f32_16x16x32_bf16 v[2:5], v[142:145], v[166:169], v[2:5]
	s_setprio 0
	s_nop 0
	v_add_u32_e32 v142, 0x18000, v207
	v_add_u32_e32 v158, 0x1c000, v207
	ds_read_b128 v[130:133], v142
	ds_read_b128 v[134:137], v142 offset:1024
	ds_read_b128 v[138:141], v142 offset:2048
	ds_read_b128 v[142:145], v142 offset:3072
	ds_read_b128 v[146:149], v158
	ds_read_b128 v[150:153], v158 offset:1024
	ds_read_b128 v[154:157], v158 offset:2048
	ds_read_b128 v[158:161], v158 offset:3072
	ds_read_b128 v[162:165], v208 offset:32768
	ds_read_b128 v[166:169], v208 offset:33792
	ds_read_b128 v[170:173], v208 offset:34816
	ds_read_b128 v[174:177], v208 offset:35840
	ds_read_b128 v[178:181], v208 offset:36864
	ds_read_b128 v[182:185], v208 offset:37888
	ds_read_b128 v[186:189], v208 offset:38912
	ds_read_b128 v[190:193], v208 offset:39936
	s_add_u32 s46, s46, 0x4000
	s_addc_u32 s47, s47, 0
	s_mov_b32 m0, s60
	s_nop 0
	global_load_lds_dwordx4 v202, s[46:47]
	s_add_u32 m0, s60, 0x2000
	s_nop 0
	global_load_lds_dwordx4 v203, s[46:47]
	s_waitcnt vmcnt(8)
	s_waitcnt lgkmcnt(0)
	s_setprio 1
	s_barrier
	v_mfma_f32_16x16x32_bf16 v[126:129], v[130:133], v[162:165], v[126:129]
	v_mfma_f32_16x16x32_bf16 v[126:129], v[134:137], v[166:169], v[126:129]
	s_waitcnt lgkmcnt(5)
	v_mfma_f32_16x16x32_bf16 v[122:125], v[138:141], v[162:165], v[122:125]
	v_mfma_f32_16x16x32_bf16 v[122:125], v[142:145], v[166:169], v[122:125]
	s_waitcnt lgkmcnt(3)
	s_setprio 0
	s_setprio 1
	v_mfma_f32_16x16x32_bf16 v[118:121], v[130:133], v[170:173], v[118:121]
	v_mfma_f32_16x16x32_bf16 v[118:121], v[134:137], v[174:177], v[118:121]
	s_waitcnt lgkmcnt(1)
	v_mfma_f32_16x16x32_bf16 v[114:117], v[138:141], v[170:173], v[114:117]
	v_mfma_f32_16x16x32_bf16 v[114:117], v[142:145], v[174:177], v[114:117]
	s_setprio 0
	s_setprio 1
	v_mfma_f32_16x16x32_bf16 v[110:113], v[130:133], v[178:181], v[110:113]
	v_mfma_f32_16x16x32_bf16 v[110:113], v[134:137], v[182:185], v[110:113]
	v_mfma_f32_16x16x32_bf16 v[106:109], v[138:141], v[178:181], v[106:109]
	v_mfma_f32_16x16x32_bf16 v[106:109], v[142:145], v[182:185], v[106:109]
	s_setprio 0
	s_setprio 1
	v_mfma_f32_16x16x32_bf16 v[102:105], v[130:133], v[186:189], v[102:105]
	v_mfma_f32_16x16x32_bf16 v[102:105], v[134:137], v[190:193], v[102:105]
	s_waitcnt lgkmcnt(0)
	v_mfma_f32_16x16x32_bf16 v[98:101], v[138:141], v[186:189], v[98:101]
	v_mfma_f32_16x16x32_bf16 v[98:101], v[142:145], v[190:193], v[98:101]
	s_setprio 0
	s_setprio 1
	v_mfma_f32_16x16x32_bf16 v[94:97], v[146:149], v[162:165], v[94:97]
	v_mfma_f32_16x16x32_bf16 v[94:97], v[150:153], v[166:169], v[94:97]
	v_mfma_f32_16x16x32_bf16 v[90:93], v[154:157], v[162:165], v[90:93]
	v_mfma_f32_16x16x32_bf16 v[90:93], v[158:161], v[166:169], v[90:93]
	s_setprio 0
	s_setprio 1
	v_mfma_f32_16x16x32_bf16 v[86:89], v[146:149], v[170:173], v[86:89]
	v_mfma_f32_16x16x32_bf16 v[86:89], v[150:153], v[174:177], v[86:89]
	v_mfma_f32_16x16x32_bf16 v[82:85], v[154:157], v[170:173], v[82:85]
	v_mfma_f32_16x16x32_bf16 v[82:85], v[158:161], v[174:177], v[82:85]
	s_setprio 0
	s_setprio 1
	v_mfma_f32_16x16x32_bf16 v[78:81], v[146:149], v[178:181], v[78:81]
	v_mfma_f32_16x16x32_bf16 v[78:81], v[150:153], v[182:185], v[78:81]
	v_mfma_f32_16x16x32_bf16 v[74:77], v[154:157], v[178:181], v[74:77]
	v_mfma_f32_16x16x32_bf16 v[74:77], v[158:161], v[182:185], v[74:77]
	s_setprio 0
	s_setprio 1
	v_mfma_f32_16x16x32_bf16 v[70:73], v[146:149], v[186:189], v[70:73]
	v_mfma_f32_16x16x32_bf16 v[70:73], v[150:153], v[190:193], v[70:73]
	s_setprio 2
	s_barrier
	v_mfma_f32_16x16x32_bf16 v[66:69], v[154:157], v[186:189], v[66:69]
	v_mfma_f32_16x16x32_bf16 v[66:69], v[158:161], v[190:193], v[66:69]
	s_setprio 0
	s_nop 0
	ds_read_b128 v[162:165], v208 offset:49152
	ds_read_b128 v[166:169], v208 offset:50176
	ds_read_b128 v[170:173], v208 offset:51200
	ds_read_b128 v[174:177], v208 offset:52224
	ds_read_b128 v[178:181], v208 offset:53248
	ds_read_b128 v[182:185], v208 offset:54272
	ds_read_b128 v[186:189], v208 offset:55296
	ds_read_b128 v[190:193], v208 offset:56320
	s_mov_b32 m0, s64
	s_nop 0
	global_load_lds_dwordx4 v202, s[50:51]
	s_add_u32 m0, s64, 0x2000
	s_nop 0
	global_load_lds_dwordx4 v203, s[50:51]
	s_add_u32 s42, s42, 0xc000
	s_addc_u32 s43, s43, 0
	s_mov_b32 m0, s66
	s_nop 0
	global_load_lds_dwordx4 v202, s[42:43]
	s_add_u32 m0, s66, 0x2000
	s_nop 0
	global_load_lds_dwordx4 v203, s[42:43]
	s_nop 0
	s_mov_b32 m0, s65
	s_nop 0
	global_load_lds_dwordx4 v202, s[48:49]
	s_add_u32 m0, s65, 0x2000
	s_nop 0
	global_load_lds_dwordx4 v203, s[48:49]
	s_waitcnt vmcnt(8)
	s_waitcnt lgkmcnt(0)
	s_setprio 1
	s_barrier
	v_mfma_f32_16x16x32_bf16 v[62:65], v[130:133], v[162:165], v[62:65]
	v_mfma_f32_16x16x32_bf16 v[62:65], v[134:137], v[166:169], v[62:65]
	s_waitcnt lgkmcnt(5)
	v_mfma_f32_16x16x32_bf16 v[58:61], v[138:141], v[162:165], v[58:61]
	v_mfma_f32_16x16x32_bf16 v[58:61], v[142:145], v[166:169], v[58:61]
	s_waitcnt lgkmcnt(3)
	s_setprio 0
	s_setprio 1
	v_mfma_f32_16x16x32_bf16 v[54:57], v[130:133], v[170:173], v[54:57]
	v_mfma_f32_16x16x32_bf16 v[54:57], v[134:137], v[174:177], v[54:57]
	s_waitcnt lgkmcnt(1)
	v_mfma_f32_16x16x32_bf16 v[50:53], v[138:141], v[170:173], v[50:53]
	v_mfma_f32_16x16x32_bf16 v[50:53], v[142:145], v[174:177], v[50:53]
	s_setprio 0
	s_setprio 1
	v_mfma_f32_16x16x32_bf16 v[46:49], v[130:133], v[178:181], v[46:49]
	v_mfma_f32_16x16x32_bf16 v[46:49], v[134:137], v[182:185], v[46:49]
	v_mfma_f32_16x16x32_bf16 v[42:45], v[138:141], v[178:181], v[42:45]
	v_mfma_f32_16x16x32_bf16 v[42:45], v[142:145], v[182:185], v[42:45]
	s_setprio 0
	s_setprio 1
	v_mfma_f32_16x16x32_bf16 v[38:41], v[130:133], v[186:189], v[38:41]
	v_mfma_f32_16x16x32_bf16 v[38:41], v[134:137], v[190:193], v[38:41]
	s_waitcnt lgkmcnt(0)
	v_mfma_f32_16x16x32_bf16 v[34:37], v[138:141], v[186:189], v[34:37]
	v_mfma_f32_16x16x32_bf16 v[34:37], v[142:145], v[190:193], v[34:37]
	s_setprio 0
	s_setprio 1
	v_mfma_f32_16x16x32_bf16 v[30:33], v[146:149], v[162:165], v[30:33]
	v_mfma_f32_16x16x32_bf16 v[30:33], v[150:153], v[166:169], v[30:33]
	v_mfma_f32_16x16x32_bf16 v[26:29], v[154:157], v[162:165], v[26:29]
	v_mfma_f32_16x16x32_bf16 v[26:29], v[158:161], v[166:169], v[26:29]
	s_setprio 0
	s_setprio 1
	v_mfma_f32_16x16x32_bf16 v[22:25], v[146:149], v[170:173], v[22:25]
	v_mfma_f32_16x16x32_bf16 v[22:25], v[150:153], v[174:177], v[22:25]
	v_mfma_f32_16x16x32_bf16 v[18:21], v[154:157], v[170:173], v[18:21]
	v_mfma_f32_16x16x32_bf16 v[18:21], v[158:161], v[174:177], v[18:21]
	s_setprio 0
	s_setprio 1
	v_mfma_f32_16x16x32_bf16 v[14:17], v[146:149], v[178:181], v[14:17]
	v_mfma_f32_16x16x32_bf16 v[14:17], v[150:153], v[182:185], v[14:17]
	v_mfma_f32_16x16x32_bf16 v[10:13], v[154:157], v[178:181], v[10:13]
	v_mfma_f32_16x16x32_bf16 v[10:13], v[158:161], v[182:185], v[10:13]
	s_setprio 0
	s_setprio 1
	v_mfma_f32_16x16x32_bf16 v[6:9], v[146:149], v[186:189], v[6:9]
	v_mfma_f32_16x16x32_bf16 v[6:9], v[150:153], v[190:193], v[6:9]
	s_setprio 2
	s_barrier
	v_mfma_f32_16x16x32_bf16 v[2:5], v[154:157], v[186:189], v[2:5]
	v_mfma_f32_16x16x32_bf16 v[2:5], v[158:161], v[190:193], v[2:5]
	s_setprio 0
	s_nop 0
	s_add_i32 s13, s77, 2
	s_cmp_gt_u32 s77, 5
	s_cbranch_scc1 .LBB0_1340
	s_mov_b32 s77, s13
	s_branch .LBB0_1317

.LBB0_1374:
	s_or_b64 exec, exec, s[40:41]
	s_add_u32 s76, s16, s6
	ds_read_b128 v[132:135], v168
	ds_read_b128 v[136:139], v168 offset:1024
	ds_read_b128 v[140:143], v168 offset:2048
	ds_read_b128 v[144:147], v168 offset:3072
	ds_read_b128 v[148:151], v169
	ds_read_b128 v[158:161], v169 offset:1024
	ds_read_b128 v[162:165], v169 offset:2048
	ds_read_b128 v[174:177], v169 offset:3072
	s_addc_u32 s77, s17, s7
	s_add_u32 s40, s76, 0x20000
	s_addc_u32 s41, s77, 0
	s_add_u32 s42, s71, s6
	s_addc_u32 s43, s72, s7
	s_cmp_eq_u32 s6, 0x20000
	s_cselect_b32 s48, s73, s40
	s_cselect_b32 s49, s27, s41
	s_cselect_b32 s41, s25, s43
	s_cselect_b32 s40, s74, s42
	s_add_u32 s42, s48, 0x8000
	s_addc_u32 s43, s49, 0
	s_add_u32 s46, s40, 0x8000
	s_addc_u32 s47, s41, 0
	ds_read_b128 v[178:181], v170
	ds_read_b128 v[182:185], v170 offset:1024
	ds_read_b128 v[186:189], v170 offset:2048
	ds_read_b128 v[190:193], v170 offset:3072
	ds_read_b128 v[198:201], v170 offset:4096
	ds_read_b128 v[204:207], v170 offset:5120
	ds_read_b128 v[212:215], v170 offset:6144
	ds_read_b128 v[216:219], v170 offset:7168
	s_add_u32 s76, s76, 0x1c000
	s_addc_u32 s77, s77, 0
	s_mov_b32 m0, s63
	s_nop 0
	global_load_lds_dwordx4 v202, s[76:77]
	s_add_u32 m0, s63, 0x2000
	s_nop 0
	global_load_lds_dwordx4 v203, s[76:77]
	s_waitcnt vmcnt(8)
	s_waitcnt lgkmcnt(0)
	s_setprio 1
	s_barrier
	v_mfma_f32_16x16x32_bf16 v[126:129], v[132:135], v[178:181], v[126:129]
	v_mfma_f32_16x16x32_bf16 v[126:129], v[136:139], v[182:185], v[126:129]
	s_waitcnt lgkmcnt(5)
	v_mfma_f32_16x16x32_bf16 v[122:125], v[140:143], v[178:181], v[122:125]
	v_mfma_f32_16x16x32_bf16 v[122:125], v[144:147], v[182:185], v[122:125]
	s_waitcnt lgkmcnt(3)
	s_setprio 0
	s_setprio 1
	v_mfma_f32_16x16x32_bf16 v[110:113], v[132:135], v[186:189], v[110:113]
	v_mfma_f32_16x16x32_bf16 v[110:113], v[136:139], v[190:193], v[110:113]
	s_waitcnt lgkmcnt(1)
	v_mfma_f32_16x16x32_bf16 v[106:109], v[140:143], v[186:189], v[106:109]
	v_mfma_f32_16x16x32_bf16 v[106:109], v[144:147], v[190:193], v[106:109]
	s_setprio 0
	s_setprio 1
	v_mfma_f32_16x16x32_bf16 v[94:97], v[132:135], v[198:201], v[94:97]
	v_mfma_f32_16x16x32_bf16 v[94:97], v[136:139], v[204:207], v[94:97]
	v_mfma_f32_16x16x32_bf16 v[90:93], v[140:143], v[198:201], v[90:93]
	v_mfma_f32_16x16x32_bf16 v[90:93], v[144:147], v[204:207], v[90:93]
	s_setprio 0
	s_setprio 1
	v_mfma_f32_16x16x32_bf16 v[78:81], v[132:135], v[212:215], v[78:81]
	v_mfma_f32_16x16x32_bf16 v[78:81], v[136:139], v[216:219], v[78:81]
	s_waitcnt lgkmcnt(0)
	v_mfma_f32_16x16x32_bf16 v[74:77], v[140:143], v[212:215], v[74:77]
	v_mfma_f32_16x16x32_bf16 v[74:77], v[144:147], v[216:219], v[74:77]
	s_setprio 0
	s_setprio 1
	v_mfma_f32_16x16x32_bf16 v[118:121], v[148:151], v[178:181], v[118:121]
	v_mfma_f32_16x16x32_bf16 v[118:121], v[158:161], v[182:185], v[118:121]
	v_mfma_f32_16x16x32_bf16 v[114:117], v[162:165], v[178:181], v[114:117]
	v_mfma_f32_16x16x32_bf16 v[114:117], v[174:177], v[182:185], v[114:117]
	s_setprio 0
	s_setprio 1
	v_mfma_f32_16x16x32_bf16 v[102:105], v[148:151], v[186:189], v[102:105]
	v_mfma_f32_16x16x32_bf16 v[102:105], v[158:161], v[190:193], v[102:105]
	v_mfma_f32_16x16x32_bf16 v[98:101], v[162:165], v[186:189], v[98:101]
	v_mfma_f32_16x16x32_bf16 v[98:101], v[174:177], v[190:193], v[98:101]
	s_setprio 0
	s_setprio 1
	v_mfma_f32_16x16x32_bf16 v[86:89], v[148:151], v[198:201], v[86:89]
	v_mfma_f32_16x16x32_bf16 v[86:89], v[158:161], v[204:207], v[86:89]
	v_mfma_f32_16x16x32_bf16 v[82:85], v[162:165], v[198:201], v[82:85]
	v_mfma_f32_16x16x32_bf16 v[82:85], v[174:177], v[204:207], v[82:85]
	s_setprio 0
	s_setprio 1
	v_mfma_f32_16x16x32_bf16 v[70:73], v[148:151], v[212:215], v[70:73]
	v_mfma_f32_16x16x32_bf16 v[70:73], v[158:161], v[216:219], v[70:73]
	s_setprio 2
	s_barrier
	v_mfma_f32_16x16x32_bf16 v[66:69], v[162:165], v[212:215], v[66:69]
	v_mfma_f32_16x16x32_bf16 v[66:69], v[174:177], v[216:219], v[66:69]
	s_setprio 0
	s_nop 0
	ds_read_b128 v[178:181], v170 offset:16384
	ds_read_b128 v[182:185], v170 offset:17408
	ds_read_b128 v[186:189], v170 offset:18432
	ds_read_b128 v[190:193], v170 offset:19456
	ds_read_b128 v[198:201], v170 offset:20480
	ds_read_b128 v[204:207], v170 offset:21504
	ds_read_b128 v[212:215], v170 offset:22528
	ds_read_b128 v[216:219], v170 offset:23552
	s_mov_b32 m0, s13
	s_nop 0
	global_load_lds_dwordx4 v202, s[40:41]
	s_add_u32 m0, s13, 0x2000
	s_nop 0
	global_load_lds_dwordx4 v203, s[40:41]
	s_add_u32 s76, s40, 0x4000
	s_addc_u32 s77, s41, 0
	s_mov_b32 m0, s55
	s_nop 0
	global_load_lds_dwordx4 v202, s[76:77]
	s_add_u32 m0, s55, 0x2000
	s_nop 0
	global_load_lds_dwordx4 v203, s[76:77]
	s_nop 0
	s_mov_b32 m0, s54
	s_nop 0
	global_load_lds_dwordx4 v202, s[48:49]
	s_add_u32 m0, s54, 0x2000
	s_nop 0
	global_load_lds_dwordx4 v203, s[48:49]
	s_waitcnt vmcnt(8)
	s_waitcnt lgkmcnt(0)
	s_setprio 1
	s_barrier
	v_mfma_f32_16x16x32_bf16 v[62:65], v[132:135], v[178:181], v[62:65]
	v_mfma_f32_16x16x32_bf16 v[62:65], v[136:139], v[182:185], v[62:65]
	s_waitcnt lgkmcnt(5)
	v_mfma_f32_16x16x32_bf16 v[58:61], v[140:143], v[178:181], v[58:61]
	v_mfma_f32_16x16x32_bf16 v[58:61], v[144:147], v[182:185], v[58:61]
	s_waitcnt lgkmcnt(3)
	s_setprio 0
	s_setprio 1
	v_mfma_f32_16x16x32_bf16 v[46:49], v[132:135], v[186:189], v[46:49]
	v_mfma_f32_16x16x32_bf16 v[46:49], v[136:139], v[190:193], v[46:49]
	s_waitcnt lgkmcnt(1)
	v_mfma_f32_16x16x32_bf16 v[42:45], v[140:143], v[186:189], v[42:45]
	v_mfma_f32_16x16x32_bf16 v[42:45], v[144:147], v[190:193], v[42:45]
	s_setprio 0
	s_setprio 1
	v_mfma_f32_16x16x32_bf16 v[30:33], v[132:135], v[198:201], v[30:33]
	v_mfma_f32_16x16x32_bf16 v[30:33], v[136:139], v[204:207], v[30:33]
	v_mfma_f32_16x16x32_bf16 v[26:29], v[140:143], v[198:201], v[26:29]
	v_mfma_f32_16x16x32_bf16 v[26:29], v[144:147], v[204:207], v[26:29]
	s_setprio 0
	s_setprio 1
	v_mfma_f32_16x16x32_bf16 v[14:17], v[132:135], v[212:215], v[14:17]
	v_mfma_f32_16x16x32_bf16 v[14:17], v[136:139], v[216:219], v[14:17]
	s_waitcnt lgkmcnt(0)
	v_mfma_f32_16x16x32_bf16 v[10:13], v[140:143], v[212:215], v[10:13]
	v_mfma_f32_16x16x32_bf16 v[10:13], v[144:147], v[216:219], v[10:13]
	s_setprio 0
	s_setprio 1
	v_mfma_f32_16x16x32_bf16 v[54:57], v[148:151], v[178:181], v[54:57]
	v_mfma_f32_16x16x32_bf16 v[54:57], v[158:161], v[182:185], v[54:57]
	v_mfma_f32_16x16x32_bf16 v[50:53], v[162:165], v[178:181], v[50:53]
	v_mfma_f32_16x16x32_bf16 v[50:53], v[174:177], v[182:185], v[50:53]
	s_setprio 0
	s_setprio 1
	v_mfma_f32_16x16x32_bf16 v[38:41], v[148:151], v[186:189], v[38:41]
	v_mfma_f32_16x16x32_bf16 v[38:41], v[158:161], v[190:193], v[38:41]
	v_mfma_f32_16x16x32_bf16 v[34:37], v[162:165], v[186:189], v[34:37]
	v_mfma_f32_16x16x32_bf16 v[34:37], v[174:177], v[190:193], v[34:37]
	s_setprio 0
	s_setprio 1
	v_mfma_f32_16x16x32_bf16 v[22:25], v[148:151], v[198:201], v[22:25]
	v_mfma_f32_16x16x32_bf16 v[22:25], v[158:161], v[204:207], v[22:25]
	v_mfma_f32_16x16x32_bf16 v[18:21], v[162:165], v[198:201], v[18:21]
	v_mfma_f32_16x16x32_bf16 v[18:21], v[174:177], v[204:207], v[18:21]
	s_setprio 0
	s_setprio 1
	v_mfma_f32_16x16x32_bf16 v[6:9], v[148:151], v[212:215], v[6:9]
	v_mfma_f32_16x16x32_bf16 v[6:9], v[158:161], v[216:219], v[6:9]
	s_setprio 2
	s_barrier
	v_mfma_f32_16x16x32_bf16 v[2:5], v[162:165], v[212:215], v[2:5]
	v_mfma_f32_16x16x32_bf16 v[2:5], v[174:177], v[216:219], v[2:5]
	s_setprio 0
	s_nop 0
	ds_read_b128 v[132:135], v171
	ds_read_b128 v[136:139], v171 offset:1024
	ds_read_b128 v[140:143], v171 offset:2048
	ds_read_b128 v[144:147], v171 offset:3072
	ds_read_b128 v[148:151], v172
	ds_read_b128 v[158:161], v172 offset:1024
	ds_read_b128 v[162:165], v172 offset:2048
	ds_read_b128 v[174:177], v172 offset:3072
	ds_read_b128 v[178:181], v170 offset:32768
	ds_read_b128 v[182:185], v170 offset:33792
	ds_read_b128 v[186:189], v170 offset:34816
	ds_read_b128 v[190:193], v170 offset:35840
	ds_read_b128 v[198:201], v170 offset:36864
	ds_read_b128 v[204:207], v170 offset:37888
	ds_read_b128 v[212:215], v170 offset:38912
	ds_read_b128 v[216:219], v170 offset:39936
	s_add_u32 s48, s48, 0x4000
	s_addc_u32 s49, s49, 0
	s_mov_b32 m0, s56
	s_nop 0
	global_load_lds_dwordx4 v202, s[48:49]
	s_add_u32 m0, s56, 0x2000
	s_nop 0
	global_load_lds_dwordx4 v203, s[48:49]
	s_waitcnt vmcnt(8)
	s_waitcnt lgkmcnt(0)
	s_setprio 1
	s_barrier
	v_mfma_f32_16x16x32_bf16 v[126:129], v[132:135], v[178:181], v[126:129]
	v_mfma_f32_16x16x32_bf16 v[126:129], v[136:139], v[182:185], v[126:129]
	s_waitcnt lgkmcnt(5)
	v_mfma_f32_16x16x32_bf16 v[122:125], v[140:143], v[178:181], v[122:125]
	v_mfma_f32_16x16x32_bf16 v[122:125], v[144:147], v[182:185], v[122:125]
	s_waitcnt lgkmcnt(3)
	s_setprio 0
	s_setprio 1
	v_mfma_f32_16x16x32_bf16 v[110:113], v[132:135], v[186:189], v[110:113]
	v_mfma_f32_16x16x32_bf16 v[110:113], v[136:139], v[190:193], v[110:113]
	s_waitcnt lgkmcnt(1)
	v_mfma_f32_16x16x32_bf16 v[106:109], v[140:143], v[186:189], v[106:109]
	v_mfma_f32_16x16x32_bf16 v[106:109], v[144:147], v[190:193], v[106:109]
	s_setprio 0
	s_setprio 1
	v_mfma_f32_16x16x32_bf16 v[94:97], v[132:135], v[198:201], v[94:97]
	v_mfma_f32_16x16x32_bf16 v[94:97], v[136:139], v[204:207], v[94:97]
	v_mfma_f32_16x16x32_bf16 v[90:93], v[140:143], v[198:201], v[90:93]
	v_mfma_f32_16x16x32_bf16 v[90:93], v[144:147], v[204:207], v[90:93]
	s_setprio 0
	s_setprio 1
	v_mfma_f32_16x16x32_bf16 v[78:81], v[132:135], v[212:215], v[78:81]
	v_mfma_f32_16x16x32_bf16 v[78:81], v[136:139], v[216:219], v[78:81]
	s_waitcnt lgkmcnt(0)
	v_mfma_f32_16x16x32_bf16 v[74:77], v[140:143], v[212:215], v[74:77]
	v_mfma_f32_16x16x32_bf16 v[74:77], v[144:147], v[216:219], v[74:77]
	s_setprio 0
	s_setprio 1
	v_mfma_f32_16x16x32_bf16 v[118:121], v[148:151], v[178:181], v[118:121]
	v_mfma_f32_16x16x32_bf16 v[118:121], v[158:161], v[182:185], v[118:121]
	v_mfma_f32_16x16x32_bf16 v[114:117], v[162:165], v[178:181], v[114:117]
	v_mfma_f32_16x16x32_bf16 v[114:117], v[174:177], v[182:185], v[114:117]
	s_setprio 0
	s_setprio 1
	v_mfma_f32_16x16x32_bf16 v[102:105], v[148:151], v[186:189], v[102:105]
	v_mfma_f32_16x16x32_bf16 v[102:105], v[158:161], v[190:193], v[102:105]
	v_mfma_f32_16x16x32_bf16 v[98:101], v[162:165], v[186:189], v[98:101]
	v_mfma_f32_16x16x32_bf16 v[98:101], v[174:177], v[190:193], v[98:101]
	s_setprio 0
	s_setprio 1
	v_mfma_f32_16x16x32_bf16 v[86:89], v[148:151], v[198:201], v[86:89]
	v_mfma_f32_16x16x32_bf16 v[86:89], v[158:161], v[204:207], v[86:89]
	v_mfma_f32_16x16x32_bf16 v[82:85], v[162:165], v[198:201], v[82:85]
	v_mfma_f32_16x16x32_bf16 v[82:85], v[174:177], v[204:207], v[82:85]
	s_setprio 0
	s_setprio 1
	v_mfma_f32_16x16x32_bf16 v[70:73], v[148:151], v[212:215], v[70:73]
	v_mfma_f32_16x16x32_bf16 v[70:73], v[158:161], v[216:219], v[70:73]
	s_setprio 2
	s_barrier
	v_mfma_f32_16x16x32_bf16 v[66:69], v[162:165], v[212:215], v[66:69]
	v_mfma_f32_16x16x32_bf16 v[66:69], v[174:177], v[216:219], v[66:69]
	s_setprio 0
	s_nop 0
	ds_read_b128 v[178:181], v170 offset:49152
	ds_read_b128 v[182:185], v170 offset:50176
	ds_read_b128 v[186:189], v170 offset:51200
	ds_read_b128 v[190:193], v170 offset:52224
	ds_read_b128 v[198:201], v170 offset:53248
	ds_read_b128 v[204:207], v170 offset:54272
	ds_read_b128 v[212:215], v170 offset:55296
	ds_read_b128 v[216:219], v170 offset:56320
	s_mov_b32 m0, s59
	s_nop 0
	global_load_lds_dwordx4 v202, s[46:47]
	s_add_u32 m0, s59, 0x2000
	s_nop 0
	global_load_lds_dwordx4 v203, s[46:47]
	s_add_u32 s40, s40, 0xc000
	s_addc_u32 s41, s41, 0
	s_mov_b32 m0, s62
	s_nop 0
	global_load_lds_dwordx4 v202, s[40:41]
	s_add_u32 m0, s62, 0x2000
	s_nop 0
	global_load_lds_dwordx4 v203, s[40:41]
	s_nop 0
	s_mov_b32 m0, s61
	s_nop 0
	global_load_lds_dwordx4 v202, s[42:43]
	s_add_u32 m0, s61, 0x2000
	s_nop 0
	global_load_lds_dwordx4 v203, s[42:43]
	s_waitcnt vmcnt(8)
	s_waitcnt lgkmcnt(0)
	s_setprio 1
	s_barrier
	v_mfma_f32_16x16x32_bf16 v[62:65], v[132:135], v[178:181], v[62:65]
	v_mfma_f32_16x16x32_bf16 v[62:65], v[136:139], v[182:185], v[62:65]
	s_waitcnt lgkmcnt(5)
	v_mfma_f32_16x16x32_bf16 v[58:61], v[140:143], v[178:181], v[58:61]
	v_mfma_f32_16x16x32_bf16 v[58:61], v[144:147], v[182:185], v[58:61]
	s_waitcnt lgkmcnt(3)
	s_setprio 0
	s_setprio 1
	v_mfma_f32_16x16x32_bf16 v[46:49], v[132:135], v[186:189], v[46:49]
	v_mfma_f32_16x16x32_bf16 v[46:49], v[136:139], v[190:193], v[46:49]
	s_waitcnt lgkmcnt(1)
	v_mfma_f32_16x16x32_bf16 v[42:45], v[140:143], v[186:189], v[42:45]
	v_mfma_f32_16x16x32_bf16 v[42:45], v[144:147], v[190:193], v[42:45]
	s_setprio 0
	s_setprio 1
	v_mfma_f32_16x16x32_bf16 v[30:33], v[132:135], v[198:201], v[30:33]
	v_mfma_f32_16x16x32_bf16 v[30:33], v[136:139], v[204:207], v[30:33]
	v_mfma_f32_16x16x32_bf16 v[26:29], v[140:143], v[198:201], v[26:29]
	v_mfma_f32_16x16x32_bf16 v[26:29], v[144:147], v[204:207], v[26:29]
	s_setprio 0
	s_setprio 1
	v_mfma_f32_16x16x32_bf16 v[14:17], v[132:135], v[212:215], v[14:17]
	v_mfma_f32_16x16x32_bf16 v[14:17], v[136:139], v[216:219], v[14:17]
	s_waitcnt lgkmcnt(0)
	v_mfma_f32_16x16x32_bf16 v[10:13], v[140:143], v[212:215], v[10:13]
	v_mfma_f32_16x16x32_bf16 v[10:13], v[144:147], v[216:219], v[10:13]
	s_setprio 0
	s_setprio 1
	v_mfma_f32_16x16x32_bf16 v[54:57], v[148:151], v[178:181], v[54:57]
	v_mfma_f32_16x16x32_bf16 v[54:57], v[158:161], v[182:185], v[54:57]
	v_mfma_f32_16x16x32_bf16 v[50:53], v[162:165], v[178:181], v[50:53]
	v_mfma_f32_16x16x32_bf16 v[50:53], v[174:177], v[182:185], v[50:53]
	s_setprio 0
	s_setprio 1
	v_mfma_f32_16x16x32_bf16 v[38:41], v[148:151], v[186:189], v[38:41]
	v_mfma_f32_16x16x32_bf16 v[38:41], v[158:161], v[190:193], v[38:41]
	v_mfma_f32_16x16x32_bf16 v[34:37], v[162:165], v[186:189], v[34:37]
	v_mfma_f32_16x16x32_bf16 v[34:37], v[174:177], v[190:193], v[34:37]
	s_setprio 0
	s_setprio 1
	v_mfma_f32_16x16x32_bf16 v[22:25], v[148:151], v[198:201], v[22:25]
	v_mfma_f32_16x16x32_bf16 v[22:25], v[158:161], v[204:207], v[22:25]
	v_mfma_f32_16x16x32_bf16 v[18:21], v[162:165], v[198:201], v[18:21]
	v_mfma_f32_16x16x32_bf16 v[18:21], v[174:177], v[204:207], v[18:21]
	s_setprio 0
	s_setprio 1
	v_mfma_f32_16x16x32_bf16 v[6:9], v[148:151], v[212:215], v[6:9]
	v_mfma_f32_16x16x32_bf16 v[6:9], v[158:161], v[216:219], v[6:9]
	s_setprio 2
	s_barrier
	v_mfma_f32_16x16x32_bf16 v[2:5], v[162:165], v[212:215], v[2:5]
	v_mfma_f32_16x16x32_bf16 v[2:5], v[174:177], v[216:219], v[2:5]
	s_setprio 0
	s_nop 0
	s_add_i32 s75, s75, 2
	s_add_u32 s6, s6, 0x10000
	s_addc_u32 s7, s7, 0
	s_cmp_gt_u32 s75, 5
	s_cbranch_scc1 .LBB0_1376
	v_mov_b32_e32 v131, v130
	s_branch .LBB0_1372

.LBB0_1519:
	s_add_i32 s26, s58, 2
	s_lshl_b64 s[54:55], s[26:27], 15
	s_add_u32 s17, s18, s54
	s_addc_u32 s59, s19, s55
	s_and_b64 s[50:51], s[12:13], exec
	s_cselect_b32 s51, s59, s41
	s_cselect_b32 s50, s17, s56
	s_add_u32 s17, s20, s54
	s_waitcnt vmcnt(8)
	s_addc_u32 s54, s21, s55
	s_waitcnt lgkmcnt(0)
	s_and_b64 s[12:13], s[12:13], exec
	s_cselect_b32 s13, s54, s39
	s_cselect_b32 s12, s17, s57
	s_setprio 1
	s_barrier
	v_mfma_f32_16x16x32_bf16 v[126:129], v[146:149], v[186:189], v[126:129]
	v_mfma_f32_16x16x32_bf16 v[126:129], v[150:153], v[190:193], v[126:129]
	s_waitcnt lgkmcnt(5)
	v_mfma_f32_16x16x32_bf16 v[122:125], v[154:157], v[186:189], v[122:125]
	v_mfma_f32_16x16x32_bf16 v[122:125], v[158:161], v[190:193], v[122:125]
	s_waitcnt lgkmcnt(3)
	s_setprio 0
	s_setprio 1
	v_mfma_f32_16x16x32_bf16 v[118:121], v[146:149], v[178:181], v[118:121]
	v_mfma_f32_16x16x32_bf16 v[118:121], v[150:153], v[182:185], v[118:121]
	s_waitcnt lgkmcnt(1)
	v_mfma_f32_16x16x32_bf16 v[114:117], v[154:157], v[178:181], v[114:117]
	v_mfma_f32_16x16x32_bf16 v[114:117], v[158:161], v[182:185], v[114:117]
	s_setprio 0
	s_setprio 1
	v_mfma_f32_16x16x32_bf16 v[110:113], v[146:149], v[170:173], v[110:113]
	v_mfma_f32_16x16x32_bf16 v[110:113], v[150:153], v[174:177], v[110:113]
	v_mfma_f32_16x16x32_bf16 v[106:109], v[154:157], v[170:173], v[106:109]
	v_mfma_f32_16x16x32_bf16 v[106:109], v[158:161], v[174:177], v[106:109]
	s_setprio 0
	s_setprio 1
	v_mfma_f32_16x16x32_bf16 v[102:105], v[146:149], v[162:165], v[102:105]
	v_mfma_f32_16x16x32_bf16 v[102:105], v[150:153], v[166:169], v[102:105]
	s_waitcnt lgkmcnt(0)
	v_mfma_f32_16x16x32_bf16 v[98:101], v[154:157], v[162:165], v[98:101]
	v_mfma_f32_16x16x32_bf16 v[98:101], v[158:161], v[166:169], v[98:101]
	s_setprio 0
	s_setprio 1
	v_mfma_f32_16x16x32_bf16 v[94:97], v[130:133], v[186:189], v[94:97]
	v_mfma_f32_16x16x32_bf16 v[94:97], v[134:137], v[190:193], v[94:97]
	v_mfma_f32_16x16x32_bf16 v[90:93], v[138:141], v[186:189], v[90:93]
	v_mfma_f32_16x16x32_bf16 v[90:93], v[142:145], v[190:193], v[90:93]
	s_setprio 0
	s_setprio 1
	v_mfma_f32_16x16x32_bf16 v[86:89], v[130:133], v[178:181], v[86:89]
	v_mfma_f32_16x16x32_bf16 v[86:89], v[134:137], v[182:185], v[86:89]
	v_mfma_f32_16x16x32_bf16 v[82:85], v[138:141], v[178:181], v[82:85]
	v_mfma_f32_16x16x32_bf16 v[82:85], v[142:145], v[182:185], v[82:85]
	s_setprio 0
	s_setprio 1
	v_mfma_f32_16x16x32_bf16 v[78:81], v[130:133], v[170:173], v[78:81]
	v_mfma_f32_16x16x32_bf16 v[78:81], v[134:137], v[174:177], v[78:81]
	v_mfma_f32_16x16x32_bf16 v[74:77], v[138:141], v[170:173], v[74:77]
	v_mfma_f32_16x16x32_bf16 v[74:77], v[142:145], v[174:177], v[74:77]
	s_setprio 0
	s_setprio 1
	v_mfma_f32_16x16x32_bf16 v[70:73], v[130:133], v[162:165], v[70:73]
	v_mfma_f32_16x16x32_bf16 v[70:73], v[134:137], v[166:169], v[70:73]
	s_setprio 2
	s_barrier
	v_mfma_f32_16x16x32_bf16 v[66:69], v[138:141], v[162:165], v[66:69]
	v_mfma_f32_16x16x32_bf16 v[66:69], v[142:145], v[166:169], v[66:69]
	s_setprio 0
	s_nop 0
	ds_read_b128 v[186:189], v217 offset:16384
	ds_read_b128 v[190:193], v217 offset:17408
	ds_read_b128 v[178:181], v217 offset:18432
	ds_read_b128 v[182:185], v217 offset:19456
	ds_read_b128 v[170:173], v217 offset:20480
	ds_read_b128 v[174:177], v217 offset:21504
	ds_read_b128 v[162:165], v217 offset:22528
	ds_read_b128 v[166:169], v217 offset:23552
	s_mov_b32 m0, s66
	s_nop 0
	global_load_lds_dwordx4 v195, s[12:13]
	s_add_u32 m0, s66, 0x2000
	s_nop 0
	global_load_lds_dwordx4 v212, s[12:13]
	s_add_u32 s54, s12, 0x4000
	s_addc_u32 s55, s13, 0
	s_mov_b32 m0, s67
	s_nop 0
	global_load_lds_dwordx4 v195, s[54:55]
	s_add_u32 m0, s67, 0x2000
	s_nop 0
	global_load_lds_dwordx4 v212, s[54:55]
	s_andn2_b64 vcc, exec, s[52:53]
	s_mov_b32 m0, s15
	s_nop 0
	global_load_lds_dwordx4 v195, s[50:51]
	s_add_u32 m0, s15, 0x2000
	s_nop 0
	global_load_lds_dwordx4 v212, s[50:51]
	s_cbranch_vccnz .LBB0_1521
	v_mov_b32_e32 v2, 0
	v_mov_b32_e32 v3, v2
	v_mov_b32_e32 v4, v2
	v_mov_b32_e32 v5, v2
	v_mov_b32_e32 v6, v2
	v_mov_b32_e32 v7, v2
	v_mov_b32_e32 v8, v2
	v_mov_b32_e32 v9, v2
	v_mov_b32_e32 v10, v2
	v_mov_b32_e32 v11, v2
	v_mov_b32_e32 v12, v2
	v_mov_b32_e32 v13, v2
	v_mov_b32_e32 v14, v2
	v_mov_b32_e32 v15, v2
	v_mov_b32_e32 v16, v2
	v_mov_b32_e32 v17, v2
	v_mov_b32_e32 v18, v2
	v_mov_b32_e32 v19, v2
	v_mov_b32_e32 v20, v2
	v_mov_b32_e32 v21, v2
	v_mov_b32_e32 v22, v2
	v_mov_b32_e32 v23, v2
	v_mov_b32_e32 v24, v2
	v_mov_b32_e32 v25, v2
	v_mov_b32_e32 v26, v2
	v_mov_b32_e32 v27, v2
	v_mov_b32_e32 v28, v2
	v_mov_b32_e32 v29, v2
	v_mov_b32_e32 v30, v2
	v_mov_b32_e32 v31, v2
	v_mov_b32_e32 v32, v2
	v_mov_b32_e32 v33, v2
	v_mov_b32_e32 v34, v2
	v_mov_b32_e32 v35, v2
	v_mov_b32_e32 v36, v2
	v_mov_b32_e32 v37, v2
	v_mov_b32_e32 v38, v2
	v_mov_b32_e32 v39, v2
	v_mov_b32_e32 v40, v2
	v_mov_b32_e32 v41, v2
	v_mov_b32_e32 v42, v2
	v_mov_b32_e32 v43, v2
	v_mov_b32_e32 v44, v2
	v_mov_b32_e32 v45, v2
	v_mov_b32_e32 v46, v2
	v_mov_b32_e32 v47, v2
	v_mov_b32_e32 v48, v2
	v_mov_b32_e32 v49, v2
	v_mov_b32_e32 v50, v2
	v_mov_b32_e32 v51, v2
	v_mov_b32_e32 v52, v2
	v_mov_b32_e32 v53, v2
	v_mov_b32_e32 v54, v2
	v_mov_b32_e32 v55, v2
	v_mov_b32_e32 v56, v2
	v_mov_b32_e32 v57, v2
	v_mov_b32_e32 v58, v2
	v_mov_b32_e32 v59, v2
	v_mov_b32_e32 v60, v2
	v_mov_b32_e32 v61, v2
	v_mov_b32_e32 v62, v2
	v_mov_b32_e32 v63, v2
	v_mov_b32_e32 v64, v2
	v_mov_b32_e32 v65, v2
.LBB0_1521:
	s_waitcnt vmcnt(8)
	s_add_u32 s52, s50, 0x8000
	s_waitcnt lgkmcnt(0)
	s_addc_u32 s53, s51, 0
	s_add_u32 s54, s12, 0x8000
	s_addc_u32 s55, s13, 0
	s_setprio 1
	s_barrier
	v_mfma_f32_16x16x32_bf16 v[62:65], v[146:149], v[186:189], v[62:65]
	v_mfma_f32_16x16x32_bf16 v[62:65], v[150:153], v[190:193], v[62:65]
	s_waitcnt lgkmcnt(5)
	v_mfma_f32_16x16x32_bf16 v[58:61], v[154:157], v[186:189], v[58:61]
	v_mfma_f32_16x16x32_bf16 v[58:61], v[158:161], v[190:193], v[58:61]
	s_waitcnt lgkmcnt(3)
	s_setprio 0
	s_setprio 1
	v_mfma_f32_16x16x32_bf16 v[54:57], v[146:149], v[178:181], v[54:57]
	v_mfma_f32_16x16x32_bf16 v[54:57], v[150:153], v[182:185], v[54:57]
	s_waitcnt lgkmcnt(1)
	v_mfma_f32_16x16x32_bf16 v[50:53], v[154:157], v[178:181], v[50:53]
	v_mfma_f32_16x16x32_bf16 v[50:53], v[158:161], v[182:185], v[50:53]
	s_setprio 0
	s_setprio 1
	v_mfma_f32_16x16x32_bf16 v[46:49], v[146:149], v[170:173], v[46:49]
	v_mfma_f32_16x16x32_bf16 v[46:49], v[150:153], v[174:177], v[46:49]
	v_mfma_f32_16x16x32_bf16 v[42:45], v[154:157], v[170:173], v[42:45]
	v_mfma_f32_16x16x32_bf16 v[42:45], v[158:161], v[174:177], v[42:45]
	s_setprio 0
	s_setprio 1
	v_mfma_f32_16x16x32_bf16 v[38:41], v[146:149], v[162:165], v[38:41]
	v_mfma_f32_16x16x32_bf16 v[38:41], v[150:153], v[166:169], v[38:41]
	s_waitcnt lgkmcnt(0)
	v_mfma_f32_16x16x32_bf16 v[34:37], v[154:157], v[162:165], v[34:37]
	v_mfma_f32_16x16x32_bf16 v[34:37], v[158:161], v[166:169], v[34:37]
	s_setprio 0
	s_setprio 1
	v_mfma_f32_16x16x32_bf16 v[30:33], v[130:133], v[186:189], v[30:33]
	v_mfma_f32_16x16x32_bf16 v[30:33], v[134:137], v[190:193], v[30:33]
	v_mfma_f32_16x16x32_bf16 v[26:29], v[138:141], v[186:189], v[26:29]
	v_mfma_f32_16x16x32_bf16 v[26:29], v[142:145], v[190:193], v[26:29]
	s_setprio 0
	s_setprio 1
	v_mfma_f32_16x16x32_bf16 v[22:25], v[130:133], v[178:181], v[22:25]
	v_mfma_f32_16x16x32_bf16 v[22:25], v[134:137], v[182:185], v[22:25]
	v_mfma_f32_16x16x32_bf16 v[18:21], v[138:141], v[178:181], v[18:21]
	v_mfma_f32_16x16x32_bf16 v[18:21], v[142:145], v[182:185], v[18:21]
	s_setprio 0
	s_setprio 1
	v_mfma_f32_16x16x32_bf16 v[14:17], v[130:133], v[170:173], v[14:17]
	v_mfma_f32_16x16x32_bf16 v[14:17], v[134:137], v[174:177], v[14:17]
	v_mfma_f32_16x16x32_bf16 v[10:13], v[138:141], v[170:173], v[10:13]
	v_mfma_f32_16x16x32_bf16 v[10:13], v[142:145], v[174:177], v[10:13]
	s_setprio 0
	s_setprio 1
	v_mfma_f32_16x16x32_bf16 v[6:9], v[130:133], v[162:165], v[6:9]
	v_mfma_f32_16x16x32_bf16 v[6:9], v[134:137], v[166:169], v[6:9]
	s_setprio 2
	s_barrier
	v_mfma_f32_16x16x32_bf16 v[2:5], v[138:141], v[162:165], v[2:5]
	v_mfma_f32_16x16x32_bf16 v[2:5], v[142:145], v[166:169], v[2:5]
	s_setprio 0
	s_nop 0
	v_add_u32_e32 v142, 0x18000, v216
	v_add_u32_e32 v158, 0x1c000, v216
	ds_read_b128 v[130:133], v142
	ds_read_b128 v[134:137], v142 offset:1024
	ds_read_b128 v[138:141], v142 offset:2048
	ds_read_b128 v[142:145], v142 offset:3072
	ds_read_b128 v[146:149], v158
	ds_read_b128 v[150:153], v158 offset:1024
	ds_read_b128 v[154:157], v158 offset:2048
	ds_read_b128 v[158:161], v158 offset:3072
	ds_read_b128 v[162:165], v217 offset:32768
	ds_read_b128 v[166:169], v217 offset:33792
	ds_read_b128 v[170:173], v217 offset:34816
	ds_read_b128 v[174:177], v217 offset:35840
	ds_read_b128 v[178:181], v217 offset:36864
	ds_read_b128 v[182:185], v217 offset:37888
	ds_read_b128 v[186:189], v217 offset:38912
	ds_read_b128 v[190:193], v217 offset:39936
	s_add_u32 s50, s50, 0x4000
	s_addc_u32 s51, s51, 0
	s_mov_b32 m0, s68
	s_nop 0
	global_load_lds_dwordx4 v195, s[50:51]
	s_add_u32 m0, s68, 0x2000
	s_nop 0
	global_load_lds_dwordx4 v212, s[50:51]
	s_waitcnt vmcnt(8)
	s_waitcnt lgkmcnt(0)
	s_setprio 1
	s_barrier
	v_mfma_f32_16x16x32_bf16 v[126:129], v[130:133], v[162:165], v[126:129]
	v_mfma_f32_16x16x32_bf16 v[126:129], v[134:137], v[166:169], v[126:129]
	s_waitcnt lgkmcnt(5)
	v_mfma_f32_16x16x32_bf16 v[122:125], v[138:141], v[162:165], v[122:125]
	v_mfma_f32_16x16x32_bf16 v[122:125], v[142:145], v[166:169], v[122:125]
	s_waitcnt lgkmcnt(3)
	s_setprio 0
	s_setprio 1
	v_mfma_f32_16x16x32_bf16 v[118:121], v[130:133], v[170:173], v[118:121]
	v_mfma_f32_16x16x32_bf16 v[118:121], v[134:137], v[174:177], v[118:121]
	s_waitcnt lgkmcnt(1)
	v_mfma_f32_16x16x32_bf16 v[114:117], v[138:141], v[170:173], v[114:117]
	v_mfma_f32_16x16x32_bf16 v[114:117], v[142:145], v[174:177], v[114:117]
	s_setprio 0
	s_setprio 1
	v_mfma_f32_16x16x32_bf16 v[110:113], v[130:133], v[178:181], v[110:113]
	v_mfma_f32_16x16x32_bf16 v[110:113], v[134:137], v[182:185], v[110:113]
	v_mfma_f32_16x16x32_bf16 v[106:109], v[138:141], v[178:181], v[106:109]
	v_mfma_f32_16x16x32_bf16 v[106:109], v[142:145], v[182:185], v[106:109]
	s_setprio 0
	s_setprio 1
	v_mfma_f32_16x16x32_bf16 v[102:105], v[130:133], v[186:189], v[102:105]
	v_mfma_f32_16x16x32_bf16 v[102:105], v[134:137], v[190:193], v[102:105]
	s_waitcnt lgkmcnt(0)
	v_mfma_f32_16x16x32_bf16 v[98:101], v[138:141], v[186:189], v[98:101]
	v_mfma_f32_16x16x32_bf16 v[98:101], v[142:145], v[190:193], v[98:101]
	s_setprio 0
	s_setprio 1
	v_mfma_f32_16x16x32_bf16 v[94:97], v[146:149], v[162:165], v[94:97]
	v_mfma_f32_16x16x32_bf16 v[94:97], v[150:153], v[166:169], v[94:97]
	v_mfma_f32_16x16x32_bf16 v[90:93], v[154:157], v[162:165], v[90:93]
	v_mfma_f32_16x16x32_bf16 v[90:93], v[158:161], v[166:169], v[90:93]
	s_setprio 0
	s_setprio 1
	v_mfma_f32_16x16x32_bf16 v[86:89], v[146:149], v[170:173], v[86:89]
	v_mfma_f32_16x16x32_bf16 v[86:89], v[150:153], v[174:177], v[86:89]
	v_mfma_f32_16x16x32_bf16 v[82:85], v[154:157], v[170:173], v[82:85]
	v_mfma_f32_16x16x32_bf16 v[82:85], v[158:161], v[174:177], v[82:85]
	s_setprio 0
	s_setprio 1
	v_mfma_f32_16x16x32_bf16 v[78:81], v[146:149], v[178:181], v[78:81]
	v_mfma_f32_16x16x32_bf16 v[78:81], v[150:153], v[182:185], v[78:81]
	v_mfma_f32_16x16x32_bf16 v[74:77], v[154:157], v[178:181], v[74:77]
	v_mfma_f32_16x16x32_bf16 v[74:77], v[158:161], v[182:185], v[74:77]
	s_setprio 0
	s_setprio 1
	v_mfma_f32_16x16x32_bf16 v[70:73], v[146:149], v[186:189], v[70:73]
	v_mfma_f32_16x16x32_bf16 v[70:73], v[150:153], v[190:193], v[70:73]
	s_setprio 2
	s_barrier
	v_mfma_f32_16x16x32_bf16 v[66:69], v[154:157], v[186:189], v[66:69]
	v_mfma_f32_16x16x32_bf16 v[66:69], v[158:161], v[190:193], v[66:69]
	s_setprio 0
	s_nop 0
	ds_read_b128 v[162:165], v217 offset:49152
	ds_read_b128 v[166:169], v217 offset:50176
	ds_read_b128 v[170:173], v217 offset:51200
	ds_read_b128 v[174:177], v217 offset:52224
	ds_read_b128 v[178:181], v217 offset:53248
	ds_read_b128 v[182:185], v217 offset:54272
	ds_read_b128 v[186:189], v217 offset:55296
	ds_read_b128 v[190:193], v217 offset:56320
	s_mov_b32 m0, s72
	s_nop 0
	global_load_lds_dwordx4 v195, s[54:55]
	s_add_u32 m0, s72, 0x2000
	s_nop 0
	global_load_lds_dwordx4 v212, s[54:55]
	s_add_u32 s12, s12, 0xc000
	s_addc_u32 s13, s13, 0
	s_mov_b32 m0, s74
	s_nop 0
	global_load_lds_dwordx4 v195, s[12:13]
	s_add_u32 m0, s74, 0x2000
	s_nop 0
	global_load_lds_dwordx4 v212, s[12:13]
	s_nop 0
	s_mov_b32 m0, s73
	s_nop 0
	global_load_lds_dwordx4 v195, s[52:53]
	s_add_u32 m0, s73, 0x2000
	s_nop 0
	global_load_lds_dwordx4 v212, s[52:53]
	s_waitcnt vmcnt(8)
	s_waitcnt lgkmcnt(0)
	s_setprio 1
	s_barrier
	v_mfma_f32_16x16x32_bf16 v[62:65], v[130:133], v[162:165], v[62:65]
	v_mfma_f32_16x16x32_bf16 v[62:65], v[134:137], v[166:169], v[62:65]
	s_waitcnt lgkmcnt(5)
	v_mfma_f32_16x16x32_bf16 v[58:61], v[138:141], v[162:165], v[58:61]
	v_mfma_f32_16x16x32_bf16 v[58:61], v[142:145], v[166:169], v[58:61]
	s_waitcnt lgkmcnt(3)
	s_setprio 0
	s_setprio 1
	v_mfma_f32_16x16x32_bf16 v[54:57], v[130:133], v[170:173], v[54:57]
	v_mfma_f32_16x16x32_bf16 v[54:57], v[134:137], v[174:177], v[54:57]
	s_waitcnt lgkmcnt(1)
	v_mfma_f32_16x16x32_bf16 v[50:53], v[138:141], v[170:173], v[50:53]
	v_mfma_f32_16x16x32_bf16 v[50:53], v[142:145], v[174:177], v[50:53]
	s_setprio 0
	s_setprio 1
	v_mfma_f32_16x16x32_bf16 v[46:49], v[130:133], v[178:181], v[46:49]
	v_mfma_f32_16x16x32_bf16 v[46:49], v[134:137], v[182:185], v[46:49]
	v_mfma_f32_16x16x32_bf16 v[42:45], v[138:141], v[178:181], v[42:45]
	v_mfma_f32_16x16x32_bf16 v[42:45], v[142:145], v[182:185], v[42:45]
	s_setprio 0
	s_setprio 1
	v_mfma_f32_16x16x32_bf16 v[38:41], v[130:133], v[186:189], v[38:41]
	v_mfma_f32_16x16x32_bf16 v[38:41], v[134:137], v[190:193], v[38:41]
	s_waitcnt lgkmcnt(0)
	v_mfma_f32_16x16x32_bf16 v[34:37], v[138:141], v[186:189], v[34:37]
	v_mfma_f32_16x16x32_bf16 v[34:37], v[142:145], v[190:193], v[34:37]
	s_setprio 0
	s_setprio 1
	v_mfma_f32_16x16x32_bf16 v[30:33], v[146:149], v[162:165], v[30:33]
	v_mfma_f32_16x16x32_bf16 v[30:33], v[150:153], v[166:169], v[30:33]
	v_mfma_f32_16x16x32_bf16 v[26:29], v[154:157], v[162:165], v[26:29]
	v_mfma_f32_16x16x32_bf16 v[26:29], v[158:161], v[166:169], v[26:29]
	s_setprio 0
	s_setprio 1
	v_mfma_f32_16x16x32_bf16 v[22:25], v[146:149], v[170:173], v[22:25]
	v_mfma_f32_16x16x32_bf16 v[22:25], v[150:153], v[174:177], v[22:25]
	v_mfma_f32_16x16x32_bf16 v[18:21], v[154:157], v[170:173], v[18:21]
	v_mfma_f32_16x16x32_bf16 v[18:21], v[158:161], v[174:177], v[18:21]
	s_setprio 0
	s_setprio 1
	v_mfma_f32_16x16x32_bf16 v[14:17], v[146:149], v[178:181], v[14:17]
	v_mfma_f32_16x16x32_bf16 v[14:17], v[150:153], v[182:185], v[14:17]
	v_mfma_f32_16x16x32_bf16 v[10:13], v[154:157], v[178:181], v[10:13]
	v_mfma_f32_16x16x32_bf16 v[10:13], v[158:161], v[182:185], v[10:13]
	s_setprio 0
	s_setprio 1
	v_mfma_f32_16x16x32_bf16 v[6:9], v[146:149], v[186:189], v[6:9]
	v_mfma_f32_16x16x32_bf16 v[6:9], v[150:153], v[190:193], v[6:9]
	s_setprio 2
	s_barrier
	v_mfma_f32_16x16x32_bf16 v[2:5], v[154:157], v[186:189], v[2:5]
	v_mfma_f32_16x16x32_bf16 v[2:5], v[158:161], v[190:193], v[2:5]
	s_setprio 0
	s_nop 0
	s_cmp_gt_u32 s58, 13
	s_cbranch_scc1 .LBB0_1523
	v_mov_b32_e32 v130, v198
	s_mov_b32 s58, s26
	s_branch .LBB0_1498

.LBB0_1712:
	s_add_u32 s52, s48, 0x10000
	s_addc_u32 s53, s49, 0
	s_and_b64 s[48:49], s[46:47], exec
	s_cselect_b32 s49, s53, s25
	s_cselect_b32 s48, s52, s75
	s_add_u32 s13, s16, s13
	s_addc_u32 s52, s17, 0
	s_add_u32 s13, s13, 0x10000
	s_waitcnt vmcnt(8)
	s_addc_u32 s52, s52, 0
	s_waitcnt lgkmcnt(0)
	s_and_b64 s[46:47], s[46:47], exec
	s_cselect_b32 s47, s52, s27
	s_cselect_b32 s46, s13, s76
	s_setprio 1
	s_barrier
	v_mfma_f32_16x16x32_bf16 v[126:129], v[146:149], v[186:189], v[126:129]
	v_mfma_f32_16x16x32_bf16 v[126:129], v[150:153], v[190:193], v[126:129]
	s_waitcnt lgkmcnt(5)
	v_mfma_f32_16x16x32_bf16 v[122:125], v[154:157], v[186:189], v[122:125]
	v_mfma_f32_16x16x32_bf16 v[122:125], v[158:161], v[190:193], v[122:125]
	s_waitcnt lgkmcnt(3)
	s_setprio 0
	s_setprio 1
	v_mfma_f32_16x16x32_bf16 v[118:121], v[146:149], v[178:181], v[118:121]
	v_mfma_f32_16x16x32_bf16 v[118:121], v[150:153], v[182:185], v[118:121]
	s_waitcnt lgkmcnt(1)
	v_mfma_f32_16x16x32_bf16 v[114:117], v[154:157], v[178:181], v[114:117]
	v_mfma_f32_16x16x32_bf16 v[114:117], v[158:161], v[182:185], v[114:117]
	s_setprio 0
	s_setprio 1
	v_mfma_f32_16x16x32_bf16 v[110:113], v[146:149], v[170:173], v[110:113]
	v_mfma_f32_16x16x32_bf16 v[110:113], v[150:153], v[174:177], v[110:113]
	v_mfma_f32_16x16x32_bf16 v[106:109], v[154:157], v[170:173], v[106:109]
	v_mfma_f32_16x16x32_bf16 v[106:109], v[158:161], v[174:177], v[106:109]
	s_setprio 0
	s_setprio 1
	v_mfma_f32_16x16x32_bf16 v[102:105], v[146:149], v[162:165], v[102:105]
	v_mfma_f32_16x16x32_bf16 v[102:105], v[150:153], v[166:169], v[102:105]
	s_waitcnt lgkmcnt(0)
	v_mfma_f32_16x16x32_bf16 v[98:101], v[154:157], v[162:165], v[98:101]
	v_mfma_f32_16x16x32_bf16 v[98:101], v[158:161], v[166:169], v[98:101]
	s_setprio 0
	s_setprio 1
	v_mfma_f32_16x16x32_bf16 v[94:97], v[130:133], v[186:189], v[94:97]
	v_mfma_f32_16x16x32_bf16 v[94:97], v[134:137], v[190:193], v[94:97]
	v_mfma_f32_16x16x32_bf16 v[90:93], v[138:141], v[186:189], v[90:93]
	v_mfma_f32_16x16x32_bf16 v[90:93], v[142:145], v[190:193], v[90:93]
	s_setprio 0
	s_setprio 1
	v_mfma_f32_16x16x32_bf16 v[86:89], v[130:133], v[178:181], v[86:89]
	v_mfma_f32_16x16x32_bf16 v[86:89], v[134:137], v[182:185], v[86:89]
	v_mfma_f32_16x16x32_bf16 v[82:85], v[138:141], v[178:181], v[82:85]
	v_mfma_f32_16x16x32_bf16 v[82:85], v[142:145], v[182:185], v[82:85]
	s_setprio 0
	s_setprio 1
	v_mfma_f32_16x16x32_bf16 v[78:81], v[130:133], v[170:173], v[78:81]
	v_mfma_f32_16x16x32_bf16 v[78:81], v[134:137], v[174:177], v[78:81]
	v_mfma_f32_16x16x32_bf16 v[74:77], v[138:141], v[170:173], v[74:77]
	v_mfma_f32_16x16x32_bf16 v[74:77], v[142:145], v[174:177], v[74:77]
	s_setprio 0
	s_setprio 1
	v_mfma_f32_16x16x32_bf16 v[70:73], v[130:133], v[162:165], v[70:73]
	v_mfma_f32_16x16x32_bf16 v[70:73], v[134:137], v[166:169], v[70:73]
	s_setprio 2
	s_barrier
	v_mfma_f32_16x16x32_bf16 v[66:69], v[138:141], v[162:165], v[66:69]
	v_mfma_f32_16x16x32_bf16 v[66:69], v[142:145], v[166:169], v[66:69]
	s_setprio 0
	s_nop 0
	ds_read_b128 v[186:189], v209 offset:16384
	ds_read_b128 v[190:193], v209 offset:17408
	ds_read_b128 v[178:181], v209 offset:18432
	ds_read_b128 v[182:185], v209 offset:19456
	ds_read_b128 v[170:173], v209 offset:20480
	ds_read_b128 v[174:177], v209 offset:21504
	ds_read_b128 v[162:165], v209 offset:22528
	ds_read_b128 v[166:169], v209 offset:23552
	s_mov_b32 m0, s58
	s_nop 0
	global_load_lds_dwordx4 v195, s[46:47]
	s_add_u32 m0, s58, 0x2000
	s_nop 0
	global_load_lds_dwordx4 v203, s[46:47]
	s_add_u32 s52, s46, 0x4000
	s_addc_u32 s53, s47, 0
	s_mov_b32 m0, s59
	s_nop 0
	global_load_lds_dwordx4 v195, s[52:53]
	s_add_u32 m0, s59, 0x2000
	s_nop 0
	global_load_lds_dwordx4 v203, s[52:53]
	s_andn2_b64 vcc, exec, s[50:51]
	s_mov_b32 m0, s11
	s_nop 0
	global_load_lds_dwordx4 v195, s[48:49]
	s_add_u32 m0, s11, 0x2000
	s_nop 0
	global_load_lds_dwordx4 v203, s[48:49]
	s_cbranch_vccnz .LBB0_1714
	v_mov_b32_e32 v2, 0
	v_mov_b32_e32 v3, v2
	v_mov_b32_e32 v4, v2
	v_mov_b32_e32 v5, v2
	v_mov_b32_e32 v6, v2
	v_mov_b32_e32 v7, v2
	v_mov_b32_e32 v8, v2
	v_mov_b32_e32 v9, v2
	v_mov_b32_e32 v10, v2
	v_mov_b32_e32 v11, v2
	v_mov_b32_e32 v12, v2
	v_mov_b32_e32 v13, v2
	v_mov_b32_e32 v14, v2
	v_mov_b32_e32 v15, v2
	v_mov_b32_e32 v16, v2
	v_mov_b32_e32 v17, v2
	v_mov_b32_e32 v18, v2
	v_mov_b32_e32 v19, v2
	v_mov_b32_e32 v20, v2
	v_mov_b32_e32 v21, v2
	v_mov_b32_e32 v22, v2
	v_mov_b32_e32 v23, v2
	v_mov_b32_e32 v24, v2
	v_mov_b32_e32 v25, v2
	v_mov_b32_e32 v26, v2
	v_mov_b32_e32 v27, v2
	v_mov_b32_e32 v28, v2
	v_mov_b32_e32 v29, v2
	v_mov_b32_e32 v30, v2
	v_mov_b32_e32 v31, v2
	v_mov_b32_e32 v32, v2
	v_mov_b32_e32 v33, v2
	v_mov_b32_e32 v34, v2
	v_mov_b32_e32 v35, v2
	v_mov_b32_e32 v36, v2
	v_mov_b32_e32 v37, v2
	v_mov_b32_e32 v38, v2
	v_mov_b32_e32 v39, v2
	v_mov_b32_e32 v40, v2
	v_mov_b32_e32 v41, v2
	v_mov_b32_e32 v42, v2
	v_mov_b32_e32 v43, v2
	v_mov_b32_e32 v44, v2
	v_mov_b32_e32 v45, v2
	v_mov_b32_e32 v46, v2
	v_mov_b32_e32 v47, v2
	v_mov_b32_e32 v48, v2
	v_mov_b32_e32 v49, v2
	v_mov_b32_e32 v50, v2
	v_mov_b32_e32 v51, v2
	v_mov_b32_e32 v52, v2
	v_mov_b32_e32 v53, v2
	v_mov_b32_e32 v54, v2
	v_mov_b32_e32 v55, v2
	v_mov_b32_e32 v56, v2
	v_mov_b32_e32 v57, v2
	v_mov_b32_e32 v58, v2
	v_mov_b32_e32 v59, v2
	v_mov_b32_e32 v60, v2
	v_mov_b32_e32 v61, v2
	v_mov_b32_e32 v62, v2
	v_mov_b32_e32 v63, v2
	v_mov_b32_e32 v64, v2
	v_mov_b32_e32 v65, v2
.LBB0_1714:
	s_waitcnt vmcnt(8)
	s_add_u32 s50, s48, 0x8000
	s_waitcnt lgkmcnt(0)
	s_addc_u32 s51, s49, 0
	s_add_u32 s52, s46, 0x8000
	s_addc_u32 s53, s47, 0
	s_setprio 1
	s_barrier
	v_mfma_f32_16x16x32_bf16 v[62:65], v[146:149], v[186:189], v[62:65]
	v_mfma_f32_16x16x32_bf16 v[62:65], v[150:153], v[190:193], v[62:65]
	s_waitcnt lgkmcnt(5)
	v_mfma_f32_16x16x32_bf16 v[58:61], v[154:157], v[186:189], v[58:61]
	v_mfma_f32_16x16x32_bf16 v[58:61], v[158:161], v[190:193], v[58:61]
	s_waitcnt lgkmcnt(3)
	s_setprio 0
	s_setprio 1
	v_mfma_f32_16x16x32_bf16 v[54:57], v[146:149], v[178:181], v[54:57]
	v_mfma_f32_16x16x32_bf16 v[54:57], v[150:153], v[182:185], v[54:57]
	s_waitcnt lgkmcnt(1)
	v_mfma_f32_16x16x32_bf16 v[50:53], v[154:157], v[178:181], v[50:53]
	v_mfma_f32_16x16x32_bf16 v[50:53], v[158:161], v[182:185], v[50:53]
	s_setprio 0
	s_setprio 1
	v_mfma_f32_16x16x32_bf16 v[46:49], v[146:149], v[170:173], v[46:49]
	v_mfma_f32_16x16x32_bf16 v[46:49], v[150:153], v[174:177], v[46:49]
	v_mfma_f32_16x16x32_bf16 v[42:45], v[154:157], v[170:173], v[42:45]
	v_mfma_f32_16x16x32_bf16 v[42:45], v[158:161], v[174:177], v[42:45]
	s_setprio 0
	s_setprio 1
	v_mfma_f32_16x16x32_bf16 v[38:41], v[146:149], v[162:165], v[38:41]
	v_mfma_f32_16x16x32_bf16 v[38:41], v[150:153], v[166:169], v[38:41]
	s_waitcnt lgkmcnt(0)
	v_mfma_f32_16x16x32_bf16 v[34:37], v[154:157], v[162:165], v[34:37]
	v_mfma_f32_16x16x32_bf16 v[34:37], v[158:161], v[166:169], v[34:37]
	s_setprio 0
	s_setprio 1
	v_mfma_f32_16x16x32_bf16 v[30:33], v[130:133], v[186:189], v[30:33]
	v_mfma_f32_16x16x32_bf16 v[30:33], v[134:137], v[190:193], v[30:33]
	v_mfma_f32_16x16x32_bf16 v[26:29], v[138:141], v[186:189], v[26:29]
	v_mfma_f32_16x16x32_bf16 v[26:29], v[142:145], v[190:193], v[26:29]
	s_setprio 0
	s_setprio 1
	v_mfma_f32_16x16x32_bf16 v[22:25], v[130:133], v[178:181], v[22:25]
	v_mfma_f32_16x16x32_bf16 v[22:25], v[134:137], v[182:185], v[22:25]
	v_mfma_f32_16x16x32_bf16 v[18:21], v[138:141], v[178:181], v[18:21]
	v_mfma_f32_16x16x32_bf16 v[18:21], v[142:145], v[182:185], v[18:21]
	s_setprio 0
	s_setprio 1
	v_mfma_f32_16x16x32_bf16 v[14:17], v[130:133], v[170:173], v[14:17]
	v_mfma_f32_16x16x32_bf16 v[14:17], v[134:137], v[174:177], v[14:17]
	v_mfma_f32_16x16x32_bf16 v[10:13], v[138:141], v[170:173], v[10:13]
	v_mfma_f32_16x16x32_bf16 v[10:13], v[142:145], v[174:177], v[10:13]
	s_setprio 0
	s_setprio 1
	v_mfma_f32_16x16x32_bf16 v[6:9], v[130:133], v[162:165], v[6:9]
	v_mfma_f32_16x16x32_bf16 v[6:9], v[134:137], v[166:169], v[6:9]
	s_setprio 2
	s_barrier
	v_mfma_f32_16x16x32_bf16 v[2:5], v[138:141], v[162:165], v[2:5]
	v_mfma_f32_16x16x32_bf16 v[2:5], v[142:145], v[166:169], v[2:5]
	s_setprio 0
	s_nop 0
	v_add_u32_e32 v142, 0x18000, v208
	v_add_u32_e32 v158, 0x1c000, v208
	ds_read_b128 v[130:133], v142
	ds_read_b128 v[134:137], v142 offset:1024
	ds_read_b128 v[138:141], v142 offset:2048
	ds_read_b128 v[142:145], v142 offset:3072
	ds_read_b128 v[146:149], v158
	ds_read_b128 v[150:153], v158 offset:1024
	ds_read_b128 v[154:157], v158 offset:2048
	ds_read_b128 v[158:161], v158 offset:3072
	ds_read_b128 v[162:165], v209 offset:32768
	ds_read_b128 v[166:169], v209 offset:33792
	ds_read_b128 v[170:173], v209 offset:34816
	ds_read_b128 v[174:177], v209 offset:35840
	ds_read_b128 v[178:181], v209 offset:36864
	ds_read_b128 v[182:185], v209 offset:37888
	ds_read_b128 v[186:189], v209 offset:38912
	ds_read_b128 v[190:193], v209 offset:39936
	s_add_u32 s48, s48, 0x4000
	s_addc_u32 s49, s49, 0
	s_mov_b32 m0, s60
	s_nop 0
	global_load_lds_dwordx4 v195, s[48:49]
	s_add_u32 m0, s60, 0x2000
	s_nop 0
	global_load_lds_dwordx4 v203, s[48:49]
	s_waitcnt vmcnt(8)
	s_waitcnt lgkmcnt(0)
	s_setprio 1
	s_barrier
	v_mfma_f32_16x16x32_bf16 v[126:129], v[130:133], v[162:165], v[126:129]
	v_mfma_f32_16x16x32_bf16 v[126:129], v[134:137], v[166:169], v[126:129]
	s_waitcnt lgkmcnt(5)
	v_mfma_f32_16x16x32_bf16 v[122:125], v[138:141], v[162:165], v[122:125]
	v_mfma_f32_16x16x32_bf16 v[122:125], v[142:145], v[166:169], v[122:125]
	s_waitcnt lgkmcnt(3)
	s_setprio 0
	s_setprio 1
	v_mfma_f32_16x16x32_bf16 v[118:121], v[130:133], v[170:173], v[118:121]
	v_mfma_f32_16x16x32_bf16 v[118:121], v[134:137], v[174:177], v[118:121]
	s_waitcnt lgkmcnt(1)
	v_mfma_f32_16x16x32_bf16 v[114:117], v[138:141], v[170:173], v[114:117]
	v_mfma_f32_16x16x32_bf16 v[114:117], v[142:145], v[174:177], v[114:117]
	s_setprio 0
	s_setprio 1
	v_mfma_f32_16x16x32_bf16 v[110:113], v[130:133], v[178:181], v[110:113]
	v_mfma_f32_16x16x32_bf16 v[110:113], v[134:137], v[182:185], v[110:113]
	v_mfma_f32_16x16x32_bf16 v[106:109], v[138:141], v[178:181], v[106:109]
	v_mfma_f32_16x16x32_bf16 v[106:109], v[142:145], v[182:185], v[106:109]
	s_setprio 0
	s_setprio 1
	v_mfma_f32_16x16x32_bf16 v[102:105], v[130:133], v[186:189], v[102:105]
	v_mfma_f32_16x16x32_bf16 v[102:105], v[134:137], v[190:193], v[102:105]
	s_waitcnt lgkmcnt(0)
	v_mfma_f32_16x16x32_bf16 v[98:101], v[138:141], v[186:189], v[98:101]
	v_mfma_f32_16x16x32_bf16 v[98:101], v[142:145], v[190:193], v[98:101]
	s_setprio 0
	s_setprio 1
	v_mfma_f32_16x16x32_bf16 v[94:97], v[146:149], v[162:165], v[94:97]
	v_mfma_f32_16x16x32_bf16 v[94:97], v[150:153], v[166:169], v[94:97]
	v_mfma_f32_16x16x32_bf16 v[90:93], v[154:157], v[162:165], v[90:93]
	v_mfma_f32_16x16x32_bf16 v[90:93], v[158:161], v[166:169], v[90:93]
	s_setprio 0
	s_setprio 1
	v_mfma_f32_16x16x32_bf16 v[86:89], v[146:149], v[170:173], v[86:89]
	v_mfma_f32_16x16x32_bf16 v[86:89], v[150:153], v[174:177], v[86:89]
	v_mfma_f32_16x16x32_bf16 v[82:85], v[154:157], v[170:173], v[82:85]
	v_mfma_f32_16x16x32_bf16 v[82:85], v[158:161], v[174:177], v[82:85]
	s_setprio 0
	s_setprio 1
	v_mfma_f32_16x16x32_bf16 v[78:81], v[146:149], v[178:181], v[78:81]
	v_mfma_f32_16x16x32_bf16 v[78:81], v[150:153], v[182:185], v[78:81]
	v_mfma_f32_16x16x32_bf16 v[74:77], v[154:157], v[178:181], v[74:77]
	v_mfma_f32_16x16x32_bf16 v[74:77], v[158:161], v[182:185], v[74:77]
	s_setprio 0
	s_setprio 1
	v_mfma_f32_16x16x32_bf16 v[70:73], v[146:149], v[186:189], v[70:73]
	v_mfma_f32_16x16x32_bf16 v[70:73], v[150:153], v[190:193], v[70:73]
	s_setprio 2
	s_barrier
	v_mfma_f32_16x16x32_bf16 v[66:69], v[154:157], v[186:189], v[66:69]
	v_mfma_f32_16x16x32_bf16 v[66:69], v[158:161], v[190:193], v[66:69]
	s_setprio 0
	s_nop 0
	ds_read_b128 v[162:165], v209 offset:49152
	ds_read_b128 v[166:169], v209 offset:50176
	ds_read_b128 v[170:173], v209 offset:51200
	ds_read_b128 v[174:177], v209 offset:52224
	ds_read_b128 v[178:181], v209 offset:53248
	ds_read_b128 v[182:185], v209 offset:54272
	ds_read_b128 v[186:189], v209 offset:55296
	ds_read_b128 v[190:193], v209 offset:56320
	s_mov_b32 m0, s64
	s_nop 0
	global_load_lds_dwordx4 v195, s[52:53]
	s_add_u32 m0, s64, 0x2000
	s_nop 0
	global_load_lds_dwordx4 v203, s[52:53]
	s_add_u32 s46, s46, 0xc000
	s_addc_u32 s47, s47, 0
	s_mov_b32 m0, s66
	s_nop 0
	global_load_lds_dwordx4 v195, s[46:47]
	s_add_u32 m0, s66, 0x2000
	s_nop 0
	global_load_lds_dwordx4 v203, s[46:47]
	s_nop 0
	s_mov_b32 m0, s65
	s_nop 0
	global_load_lds_dwordx4 v195, s[50:51]
	s_add_u32 m0, s65, 0x2000
	s_nop 0
	global_load_lds_dwordx4 v203, s[50:51]
	s_waitcnt vmcnt(8)
	s_waitcnt lgkmcnt(0)
	s_setprio 1
	s_barrier
	v_mfma_f32_16x16x32_bf16 v[62:65], v[130:133], v[162:165], v[62:65]
	v_mfma_f32_16x16x32_bf16 v[62:65], v[134:137], v[166:169], v[62:65]
	s_waitcnt lgkmcnt(5)
	v_mfma_f32_16x16x32_bf16 v[58:61], v[138:141], v[162:165], v[58:61]
	v_mfma_f32_16x16x32_bf16 v[58:61], v[142:145], v[166:169], v[58:61]
	s_waitcnt lgkmcnt(3)
	s_setprio 0
	s_setprio 1
	v_mfma_f32_16x16x32_bf16 v[54:57], v[130:133], v[170:173], v[54:57]
	v_mfma_f32_16x16x32_bf16 v[54:57], v[134:137], v[174:177], v[54:57]
	s_waitcnt lgkmcnt(1)
	v_mfma_f32_16x16x32_bf16 v[50:53], v[138:141], v[170:173], v[50:53]
	v_mfma_f32_16x16x32_bf16 v[50:53], v[142:145], v[174:177], v[50:53]
	s_setprio 0
	s_setprio 1
	v_mfma_f32_16x16x32_bf16 v[46:49], v[130:133], v[178:181], v[46:49]
	v_mfma_f32_16x16x32_bf16 v[46:49], v[134:137], v[182:185], v[46:49]
	v_mfma_f32_16x16x32_bf16 v[42:45], v[138:141], v[178:181], v[42:45]
	v_mfma_f32_16x16x32_bf16 v[42:45], v[142:145], v[182:185], v[42:45]
	s_setprio 0
	s_setprio 1
	v_mfma_f32_16x16x32_bf16 v[38:41], v[130:133], v[186:189], v[38:41]
	v_mfma_f32_16x16x32_bf16 v[38:41], v[134:137], v[190:193], v[38:41]
	s_waitcnt lgkmcnt(0)
	v_mfma_f32_16x16x32_bf16 v[34:37], v[138:141], v[186:189], v[34:37]
	v_mfma_f32_16x16x32_bf16 v[34:37], v[142:145], v[190:193], v[34:37]
	s_setprio 0
	s_setprio 1
	v_mfma_f32_16x16x32_bf16 v[30:33], v[146:149], v[162:165], v[30:33]
	v_mfma_f32_16x16x32_bf16 v[30:33], v[150:153], v[166:169], v[30:33]
	v_mfma_f32_16x16x32_bf16 v[26:29], v[154:157], v[162:165], v[26:29]
	v_mfma_f32_16x16x32_bf16 v[26:29], v[158:161], v[166:169], v[26:29]
	s_setprio 0
	s_setprio 1
	v_mfma_f32_16x16x32_bf16 v[22:25], v[146:149], v[170:173], v[22:25]
	v_mfma_f32_16x16x32_bf16 v[22:25], v[150:153], v[174:177], v[22:25]
	v_mfma_f32_16x16x32_bf16 v[18:21], v[154:157], v[170:173], v[18:21]
	v_mfma_f32_16x16x32_bf16 v[18:21], v[158:161], v[174:177], v[18:21]
	s_setprio 0
	s_setprio 1
	v_mfma_f32_16x16x32_bf16 v[14:17], v[146:149], v[178:181], v[14:17]
	v_mfma_f32_16x16x32_bf16 v[14:17], v[150:153], v[182:185], v[14:17]
	v_mfma_f32_16x16x32_bf16 v[10:13], v[154:157], v[178:181], v[10:13]
	v_mfma_f32_16x16x32_bf16 v[10:13], v[158:161], v[182:185], v[10:13]
	s_setprio 0
	s_setprio 1
	v_mfma_f32_16x16x32_bf16 v[6:9], v[146:149], v[186:189], v[6:9]
	v_mfma_f32_16x16x32_bf16 v[6:9], v[150:153], v[190:193], v[6:9]
	s_setprio 2
	s_barrier
	v_mfma_f32_16x16x32_bf16 v[2:5], v[154:157], v[186:189], v[2:5]
	v_mfma_f32_16x16x32_bf16 v[2:5], v[158:161], v[190:193], v[2:5]
	s_setprio 0
	s_nop 0
	s_add_i32 s13, s77, 2
	s_cmp_gt_u32 s77, 13
	s_cbranch_scc1 .LBB0_1716
	s_mov_b32 s77, s13
	s_branch .LBB0_1693

.LBB0_1919:
	s_or_b64 exec, exec, s[10:11]
	s_add_u32 s50, s16, s6
	ds_read_b128 v[134:137], v201
	ds_read_b128 v[138:141], v201 offset:1024
	ds_read_b128 v[142:145], v201 offset:2048
	ds_read_b128 v[146:149], v201 offset:3072
	ds_read_b128 v[150:153], v202
	ds_read_b128 v[154:157], v202 offset:1024
	ds_read_b128 v[162:165], v202 offset:2048
	ds_read_b128 v[166:169], v202 offset:3072
	s_addc_u32 s51, s17, s7
	s_add_u32 s10, s50, 0x20000
	s_addc_u32 s11, s51, 0
	s_add_u32 s42, s75, s6
	s_addc_u32 s43, s76, s7
	s_cmp_eq_u32 s6, 0x60000
	s_cselect_b32 s46, s29, s10
	s_cselect_b32 s47, s20, s11
	s_cselect_b32 s11, s27, s43
	s_cselect_b32 s10, s48, s42
	s_add_u32 s42, s46, 0x8000
	s_addc_u32 s43, s47, 0
	s_add_u32 s44, s10, 0x8000
	s_addc_u32 s45, s11, 0
	ds_read_b128 v[170:173], v203
	ds_read_b128 v[174:177], v203 offset:1024
	ds_read_b128 v[178:181], v203 offset:2048
	ds_read_b128 v[182:185], v203 offset:3072
	ds_read_b128 v[186:189], v203 offset:4096
	ds_read_b128 v[190:193], v203 offset:5120
	ds_read_b128 v[212:215], v203 offset:6144
	ds_read_b128 v[216:219], v203 offset:7168
	s_add_u32 s50, s50, 0x1c000
	s_addc_u32 s51, s51, 0
	s_mov_b32 m0, s65
	s_nop 0
	global_load_lds_dwordx4 v195, s[50:51]
	s_add_u32 m0, s65, 0x2000
	s_nop 0
	global_load_lds_dwordx4 v197, s[50:51]
	s_waitcnt vmcnt(8)
	s_waitcnt lgkmcnt(0)
	s_setprio 1
	s_barrier
	v_mfma_f32_16x16x32_bf16 v[130:133], v[134:137], v[170:173], v[130:133]
	v_mfma_f32_16x16x32_bf16 v[126:129], v[142:145], v[170:173], v[126:129]
	s_waitcnt lgkmcnt(5)
	v_mfma_f32_16x16x32_bf16 v[110:113], v[134:137], v[178:181], v[110:113]
	v_mfma_f32_16x16x32_bf16 v[106:109], v[142:145], v[178:181], v[106:109]
	s_waitcnt lgkmcnt(3)
	v_mfma_f32_16x16x32_bf16 v[94:97], v[134:137], v[186:189], v[94:97]
	v_mfma_f32_16x16x32_bf16 v[90:93], v[142:145], v[186:189], v[90:93]
	s_waitcnt lgkmcnt(1)
	v_mfma_f32_16x16x32_bf16 v[78:81], v[134:137], v[212:215], v[78:81]
	v_mfma_f32_16x16x32_bf16 v[74:77], v[142:145], v[212:215], v[74:77]
	v_mfma_f32_16x16x32_bf16 v[130:133], v[138:141], v[174:177], v[130:133]
	v_mfma_f32_16x16x32_bf16 v[126:129], v[146:149], v[174:177], v[126:129]
	v_mfma_f32_16x16x32_bf16 v[110:113], v[138:141], v[182:185], v[110:113]
	v_mfma_f32_16x16x32_bf16 v[106:109], v[146:149], v[182:185], v[106:109]
	v_mfma_f32_16x16x32_bf16 v[94:97], v[138:141], v[190:193], v[94:97]
	v_mfma_f32_16x16x32_bf16 v[90:93], v[146:149], v[190:193], v[90:93]
	s_waitcnt lgkmcnt(0)
	v_mfma_f32_16x16x32_bf16 v[78:81], v[138:141], v[216:219], v[78:81]
	v_mfma_f32_16x16x32_bf16 v[74:77], v[146:149], v[216:219], v[74:77]
	s_setprio 0
	s_setprio 1
	v_mfma_f32_16x16x32_bf16 v[122:125], v[150:153], v[170:173], v[122:125]
	v_mfma_f32_16x16x32_bf16 v[116:119], v[162:165], v[170:173], v[118:121]
	v_mfma_f32_16x16x32_bf16 v[102:105], v[150:153], v[178:181], v[102:105]
	v_mfma_f32_16x16x32_bf16 v[98:101], v[162:165], v[178:181], v[98:101]
	v_mfma_f32_16x16x32_bf16 v[86:89], v[150:153], v[186:189], v[86:89]
	v_mfma_f32_16x16x32_bf16 v[82:85], v[162:165], v[186:189], v[82:85]
	v_mfma_f32_16x16x32_bf16 v[70:73], v[150:153], v[212:215], v[70:73]
	v_mfma_f32_16x16x32_bf16 v[66:69], v[162:165], v[212:215], v[66:69]
	v_mfma_f32_16x16x32_bf16 v[122:125], v[154:157], v[174:177], v[122:125]
	v_mfma_f32_16x16x32_bf16 v[116:119], v[166:169], v[174:177], v[116:119]
	v_mfma_f32_16x16x32_bf16 v[102:105], v[154:157], v[182:185], v[102:105]
	v_mfma_f32_16x16x32_bf16 v[98:101], v[166:169], v[182:185], v[98:101]
	v_mfma_f32_16x16x32_bf16 v[86:89], v[154:157], v[190:193], v[86:89]
	v_mfma_f32_16x16x32_bf16 v[82:85], v[166:169], v[190:193], v[82:85]
	s_setprio 2
	s_barrier
	v_mfma_f32_16x16x32_bf16 v[70:73], v[154:157], v[216:219], v[70:73]
	v_mfma_f32_16x16x32_bf16 v[66:69], v[166:169], v[216:219], v[66:69]
	s_setprio 0
	s_nop 0
	ds_read_b128 v[170:173], v203 offset:16384
	ds_read_b128 v[174:177], v203 offset:17408
	ds_read_b128 v[178:181], v203 offset:18432
	ds_read_b128 v[182:185], v203 offset:19456
	ds_read_b128 v[186:189], v203 offset:20480
	ds_read_b128 v[190:193], v203 offset:21504
	ds_read_b128 v[212:215], v203 offset:22528
	ds_read_b128 v[216:219], v203 offset:23552
	s_mov_b32 m0, s13
	s_nop 0
	global_load_lds_dwordx4 v195, s[10:11]
	s_add_u32 m0, s13, 0x2000
	s_nop 0
	global_load_lds_dwordx4 v197, s[10:11]
	s_add_u32 s50, s10, 0x4000
	s_addc_u32 s51, s11, 0
	s_mov_b32 m0, s57
	s_nop 0
	global_load_lds_dwordx4 v195, s[50:51]
	s_add_u32 m0, s57, 0x2000
	s_nop 0
	global_load_lds_dwordx4 v197, s[50:51]
	s_nop 0
	s_mov_b32 m0, s56
	s_nop 0
	global_load_lds_dwordx4 v195, s[46:47]
	s_add_u32 m0, s56, 0x2000
	s_nop 0
	global_load_lds_dwordx4 v197, s[46:47]
	s_waitcnt vmcnt(8)
	s_waitcnt lgkmcnt(0)
	s_setprio 1
	s_barrier
	v_mfma_f32_16x16x32_bf16 v[62:65], v[134:137], v[170:173], v[62:65]
	v_mfma_f32_16x16x32_bf16 v[62:65], v[138:141], v[174:177], v[62:65]
	s_waitcnt lgkmcnt(5)
	v_mfma_f32_16x16x32_bf16 v[58:61], v[142:145], v[170:173], v[58:61]
	v_mfma_f32_16x16x32_bf16 v[58:61], v[146:149], v[174:177], v[58:61]
	s_waitcnt lgkmcnt(3)
	s_setprio 0
	s_setprio 1
	v_mfma_f32_16x16x32_bf16 v[46:49], v[134:137], v[178:181], v[46:49]
	v_mfma_f32_16x16x32_bf16 v[46:49], v[138:141], v[182:185], v[46:49]
	s_waitcnt lgkmcnt(1)
	v_mfma_f32_16x16x32_bf16 v[42:45], v[142:145], v[178:181], v[42:45]
	v_mfma_f32_16x16x32_bf16 v[42:45], v[146:149], v[182:185], v[42:45]
	s_setprio 0
	s_setprio 1
	v_mfma_f32_16x16x32_bf16 v[30:33], v[134:137], v[186:189], v[30:33]
	v_mfma_f32_16x16x32_bf16 v[30:33], v[138:141], v[190:193], v[30:33]
	v_mfma_f32_16x16x32_bf16 v[26:29], v[142:145], v[186:189], v[26:29]
	v_mfma_f32_16x16x32_bf16 v[26:29], v[146:149], v[190:193], v[26:29]
	s_setprio 0
	s_setprio 1
	v_mfma_f32_16x16x32_bf16 v[14:17], v[134:137], v[212:215], v[14:17]
	v_mfma_f32_16x16x32_bf16 v[14:17], v[138:141], v[216:219], v[14:17]
	s_waitcnt lgkmcnt(0)
	v_mfma_f32_16x16x32_bf16 v[10:13], v[142:145], v[212:215], v[10:13]
	v_mfma_f32_16x16x32_bf16 v[10:13], v[146:149], v[216:219], v[10:13]
	s_setprio 0
	s_setprio 1
	v_mfma_f32_16x16x32_bf16 v[54:57], v[150:153], v[170:173], v[54:57]
	v_mfma_f32_16x16x32_bf16 v[54:57], v[154:157], v[174:177], v[54:57]
	v_mfma_f32_16x16x32_bf16 v[50:53], v[162:165], v[170:173], v[50:53]
	v_mfma_f32_16x16x32_bf16 v[50:53], v[166:169], v[174:177], v[50:53]
	s_setprio 0
	s_setprio 1
	v_mfma_f32_16x16x32_bf16 v[38:41], v[150:153], v[178:181], v[38:41]
	v_mfma_f32_16x16x32_bf16 v[38:41], v[154:157], v[182:185], v[38:41]
	v_mfma_f32_16x16x32_bf16 v[34:37], v[162:165], v[178:181], v[34:37]
	v_mfma_f32_16x16x32_bf16 v[34:37], v[166:169], v[182:185], v[34:37]
	s_setprio 0
	s_setprio 1
	v_mfma_f32_16x16x32_bf16 v[22:25], v[150:153], v[186:189], v[22:25]
	v_mfma_f32_16x16x32_bf16 v[22:25], v[154:157], v[190:193], v[22:25]
	v_mfma_f32_16x16x32_bf16 v[18:21], v[162:165], v[186:189], v[18:21]
	v_mfma_f32_16x16x32_bf16 v[18:21], v[166:169], v[190:193], v[18:21]
	s_setprio 0
	s_setprio 1
	v_mfma_f32_16x16x32_bf16 v[6:9], v[150:153], v[212:215], v[6:9]
	v_mfma_f32_16x16x32_bf16 v[6:9], v[154:157], v[216:219], v[6:9]
	s_setprio 2
	s_barrier
	v_mfma_f32_16x16x32_bf16 v[2:5], v[162:165], v[212:215], v[2:5]
	v_mfma_f32_16x16x32_bf16 v[2:5], v[166:169], v[216:219], v[2:5]
	s_setprio 0
	s_nop 0
	ds_read_b128 v[134:137], v204
	ds_read_b128 v[138:141], v204 offset:1024
	ds_read_b128 v[142:145], v204 offset:2048
	ds_read_b128 v[146:149], v204 offset:3072
	ds_read_b128 v[150:153], v205
	ds_read_b128 v[154:157], v205 offset:1024
	ds_read_b128 v[162:165], v205 offset:2048
	ds_read_b128 v[166:169], v205 offset:3072
	ds_read_b128 v[170:173], v203 offset:32768
	ds_read_b128 v[174:177], v203 offset:33792
	ds_read_b128 v[178:181], v203 offset:34816
	ds_read_b128 v[182:185], v203 offset:35840
	ds_read_b128 v[186:189], v203 offset:36864
	ds_read_b128 v[190:193], v203 offset:37888
	ds_read_b128 v[212:215], v203 offset:38912
	ds_read_b128 v[216:219], v203 offset:39936
	s_add_u32 s46, s46, 0x4000
	s_addc_u32 s47, s47, 0
	s_mov_b32 m0, s58
	s_nop 0
	global_load_lds_dwordx4 v195, s[46:47]
	s_add_u32 m0, s58, 0x2000
	s_nop 0
	global_load_lds_dwordx4 v197, s[46:47]
	s_waitcnt vmcnt(8)
	s_waitcnt lgkmcnt(0)
	s_setprio 1
	s_barrier
	v_mfma_f32_16x16x32_bf16 v[130:133], v[134:137], v[170:173], v[130:133]
	v_mfma_f32_16x16x32_bf16 v[126:129], v[142:145], v[170:173], v[126:129]
	s_waitcnt lgkmcnt(5)
	v_mfma_f32_16x16x32_bf16 v[110:113], v[134:137], v[178:181], v[110:113]
	v_mfma_f32_16x16x32_bf16 v[106:109], v[142:145], v[178:181], v[106:109]
	s_waitcnt lgkmcnt(3)
	v_mfma_f32_16x16x32_bf16 v[94:97], v[134:137], v[186:189], v[94:97]
	v_mfma_f32_16x16x32_bf16 v[90:93], v[142:145], v[186:189], v[90:93]
	s_waitcnt lgkmcnt(1)
	v_mfma_f32_16x16x32_bf16 v[78:81], v[134:137], v[212:215], v[78:81]
	v_mfma_f32_16x16x32_bf16 v[74:77], v[142:145], v[212:215], v[74:77]
	v_mfma_f32_16x16x32_bf16 v[130:133], v[138:141], v[174:177], v[130:133]
	v_mfma_f32_16x16x32_bf16 v[126:129], v[146:149], v[174:177], v[126:129]
	v_mfma_f32_16x16x32_bf16 v[110:113], v[138:141], v[182:185], v[110:113]
	v_mfma_f32_16x16x32_bf16 v[106:109], v[146:149], v[182:185], v[106:109]
	v_mfma_f32_16x16x32_bf16 v[94:97], v[138:141], v[190:193], v[94:97]
	v_mfma_f32_16x16x32_bf16 v[90:93], v[146:149], v[190:193], v[90:93]
	s_waitcnt lgkmcnt(0)
	v_mfma_f32_16x16x32_bf16 v[78:81], v[138:141], v[216:219], v[78:81]
	v_mfma_f32_16x16x32_bf16 v[74:77], v[146:149], v[216:219], v[74:77]
	s_setprio 0
	s_setprio 1
	v_mfma_f32_16x16x32_bf16 v[120:123], v[150:153], v[170:173], v[122:125]
	v_mfma_f32_16x16x32_bf16 v[116:119], v[162:165], v[170:173], v[116:119]
	v_mfma_f32_16x16x32_bf16 v[102:105], v[150:153], v[178:181], v[102:105]
	v_mfma_f32_16x16x32_bf16 v[98:101], v[162:165], v[178:181], v[98:101]
	v_mfma_f32_16x16x32_bf16 v[86:89], v[150:153], v[186:189], v[86:89]
	v_mfma_f32_16x16x32_bf16 v[82:85], v[162:165], v[186:189], v[82:85]
	v_mfma_f32_16x16x32_bf16 v[70:73], v[150:153], v[212:215], v[70:73]
	v_mfma_f32_16x16x32_bf16 v[66:69], v[162:165], v[212:215], v[66:69]
	v_mfma_f32_16x16x32_bf16 v[122:125], v[154:157], v[174:177], v[120:123]
	v_mfma_f32_16x16x32_bf16 v[118:121], v[166:169], v[174:177], v[116:119]
	v_mfma_f32_16x16x32_bf16 v[102:105], v[154:157], v[182:185], v[102:105]
	v_mfma_f32_16x16x32_bf16 v[98:101], v[166:169], v[182:185], v[98:101]
	v_mfma_f32_16x16x32_bf16 v[86:89], v[154:157], v[190:193], v[86:89]
	v_mfma_f32_16x16x32_bf16 v[82:85], v[166:169], v[190:193], v[82:85]
	s_setprio 2
	s_barrier
	v_mfma_f32_16x16x32_bf16 v[70:73], v[154:157], v[216:219], v[70:73]
	v_mfma_f32_16x16x32_bf16 v[66:69], v[166:169], v[216:219], v[66:69]
	s_setprio 0
	s_nop 0
	ds_read_b128 v[170:173], v203 offset:49152
	ds_read_b128 v[174:177], v203 offset:50176
	ds_read_b128 v[178:181], v203 offset:51200
	ds_read_b128 v[182:185], v203 offset:52224
	ds_read_b128 v[186:189], v203 offset:53248
	ds_read_b128 v[190:193], v203 offset:54272
	ds_read_b128 v[212:215], v203 offset:55296
	ds_read_b128 v[216:219], v203 offset:56320
	s_mov_b32 m0, s62
	s_nop 0
	global_load_lds_dwordx4 v195, s[44:45]
	s_add_u32 m0, s62, 0x2000
	s_nop 0
	global_load_lds_dwordx4 v197, s[44:45]
	s_add_u32 s10, s10, 0xc000
	s_addc_u32 s11, s11, 0
	s_mov_b32 m0, s64
	s_nop 0
	global_load_lds_dwordx4 v195, s[10:11]
	s_add_u32 m0, s64, 0x2000
	s_nop 0
	global_load_lds_dwordx4 v197, s[10:11]
	s_nop 0
	s_mov_b32 m0, s63
	s_nop 0
	global_load_lds_dwordx4 v195, s[42:43]
	s_add_u32 m0, s63, 0x2000
	s_nop 0
	global_load_lds_dwordx4 v197, s[42:43]
	s_waitcnt vmcnt(8)
	s_waitcnt lgkmcnt(0)
	s_setprio 1
	s_barrier
	v_mfma_f32_16x16x32_bf16 v[62:65], v[134:137], v[170:173], v[62:65]
	v_mfma_f32_16x16x32_bf16 v[62:65], v[138:141], v[174:177], v[62:65]
	s_waitcnt lgkmcnt(5)
	v_mfma_f32_16x16x32_bf16 v[58:61], v[142:145], v[170:173], v[58:61]
	v_mfma_f32_16x16x32_bf16 v[58:61], v[146:149], v[174:177], v[58:61]
	s_waitcnt lgkmcnt(3)
	s_setprio 0
	s_setprio 1
	v_mfma_f32_16x16x32_bf16 v[46:49], v[134:137], v[178:181], v[46:49]
	v_mfma_f32_16x16x32_bf16 v[46:49], v[138:141], v[182:185], v[46:49]
	s_waitcnt lgkmcnt(1)
	v_mfma_f32_16x16x32_bf16 v[42:45], v[142:145], v[178:181], v[42:45]
	v_mfma_f32_16x16x32_bf16 v[42:45], v[146:149], v[182:185], v[42:45]
	s_setprio 0
	s_setprio 1
	v_mfma_f32_16x16x32_bf16 v[30:33], v[134:137], v[186:189], v[30:33]
	v_mfma_f32_16x16x32_bf16 v[30:33], v[138:141], v[190:193], v[30:33]
	v_mfma_f32_16x16x32_bf16 v[26:29], v[142:145], v[186:189], v[26:29]
	v_mfma_f32_16x16x32_bf16 v[26:29], v[146:149], v[190:193], v[26:29]
	s_setprio 0
	s_setprio 1
	v_mfma_f32_16x16x32_bf16 v[14:17], v[134:137], v[212:215], v[14:17]
	v_mfma_f32_16x16x32_bf16 v[14:17], v[138:141], v[216:219], v[14:17]
	s_waitcnt lgkmcnt(0)
	v_mfma_f32_16x16x32_bf16 v[10:13], v[142:145], v[212:215], v[10:13]
	v_mfma_f32_16x16x32_bf16 v[10:13], v[146:149], v[216:219], v[10:13]
	s_setprio 0
	s_setprio 1
	v_mfma_f32_16x16x32_bf16 v[54:57], v[150:153], v[170:173], v[54:57]
	v_mfma_f32_16x16x32_bf16 v[54:57], v[154:157], v[174:177], v[54:57]
	v_mfma_f32_16x16x32_bf16 v[50:53], v[162:165], v[170:173], v[50:53]
	v_mfma_f32_16x16x32_bf16 v[50:53], v[166:169], v[174:177], v[50:53]
	s_setprio 0
	s_setprio 1
	v_mfma_f32_16x16x32_bf16 v[38:41], v[150:153], v[178:181], v[38:41]
	v_mfma_f32_16x16x32_bf16 v[38:41], v[154:157], v[182:185], v[38:41]
	v_mfma_f32_16x16x32_bf16 v[34:37], v[162:165], v[178:181], v[34:37]
	v_mfma_f32_16x16x32_bf16 v[34:37], v[166:169], v[182:185], v[34:37]
	s_setprio 0
	s_setprio 1
	v_mfma_f32_16x16x32_bf16 v[22:25], v[150:153], v[186:189], v[22:25]
	v_mfma_f32_16x16x32_bf16 v[22:25], v[154:157], v[190:193], v[22:25]
	v_mfma_f32_16x16x32_bf16 v[18:21], v[162:165], v[186:189], v[18:21]
	v_mfma_f32_16x16x32_bf16 v[18:21], v[166:169], v[190:193], v[18:21]
	s_setprio 0
	s_setprio 1
	v_mfma_f32_16x16x32_bf16 v[6:9], v[150:153], v[212:215], v[6:9]
	v_mfma_f32_16x16x32_bf16 v[6:9], v[154:157], v[216:219], v[6:9]
	s_setprio 2
	s_barrier
	v_mfma_f32_16x16x32_bf16 v[2:5], v[162:165], v[212:215], v[2:5]
	v_mfma_f32_16x16x32_bf16 v[2:5], v[166:169], v[216:219], v[2:5]
	s_setprio 0
	s_nop 0
	s_add_i32 s49, s49, 2
	s_add_u32 s6, s6, 0x10000
	s_addc_u32 s7, s7, 0
	s_cmp_gt_u32 s49, 13
	v_mov_b32_e32 v115, v114
	s_cbranch_scc1 .LBB0_1922

.LBB0_2120:
	s_add_u32 s56, s52, 0x10000
	s_addc_u32 s57, s53, 0
	s_and_b64 s[52:53], s[50:51], exec
	s_cselect_b32 s53, s57, s43
	s_cselect_b32 s52, s56, s88
	s_add_u32 s15, s18, s15
	s_addc_u32 s56, s19, 0
	s_add_u32 s15, s15, 0x10000
	s_waitcnt vmcnt(8)
	s_addc_u32 s56, s56, 0
	s_waitcnt lgkmcnt(0)
	s_and_b64 s[50:51], s[50:51], exec
	s_cselect_b32 s51, s56, s41
	s_cselect_b32 s50, s15, s89
	s_setprio 1
	s_barrier
	v_mfma_f32_16x16x32_bf16 v[126:129], v[146:149], v[186:189], v[126:129]
	v_mfma_f32_16x16x32_bf16 v[126:129], v[150:153], v[190:193], v[126:129]
	s_waitcnt lgkmcnt(5)
	v_mfma_f32_16x16x32_bf16 v[122:125], v[154:157], v[186:189], v[122:125]
	v_mfma_f32_16x16x32_bf16 v[122:125], v[158:161], v[190:193], v[122:125]
	s_waitcnt lgkmcnt(3)
	s_setprio 0
	s_setprio 1
	v_mfma_f32_16x16x32_bf16 v[118:121], v[146:149], v[178:181], v[118:121]
	v_mfma_f32_16x16x32_bf16 v[118:121], v[150:153], v[182:185], v[118:121]
	s_waitcnt lgkmcnt(1)
	v_mfma_f32_16x16x32_bf16 v[114:117], v[154:157], v[178:181], v[114:117]
	v_mfma_f32_16x16x32_bf16 v[114:117], v[158:161], v[182:185], v[114:117]
	s_setprio 0
	s_setprio 1
	v_mfma_f32_16x16x32_bf16 v[110:113], v[146:149], v[170:173], v[110:113]
	v_mfma_f32_16x16x32_bf16 v[110:113], v[150:153], v[174:177], v[110:113]
	v_mfma_f32_16x16x32_bf16 v[106:109], v[154:157], v[170:173], v[106:109]
	v_mfma_f32_16x16x32_bf16 v[106:109], v[158:161], v[174:177], v[106:109]
	s_setprio 0
	s_setprio 1
	v_mfma_f32_16x16x32_bf16 v[102:105], v[146:149], v[162:165], v[102:105]
	v_mfma_f32_16x16x32_bf16 v[102:105], v[150:153], v[166:169], v[102:105]
	s_waitcnt lgkmcnt(0)
	v_mfma_f32_16x16x32_bf16 v[98:101], v[154:157], v[162:165], v[98:101]
	v_mfma_f32_16x16x32_bf16 v[98:101], v[158:161], v[166:169], v[98:101]
	s_setprio 0
	s_setprio 1
	v_mfma_f32_16x16x32_bf16 v[94:97], v[130:133], v[186:189], v[94:97]
	v_mfma_f32_16x16x32_bf16 v[94:97], v[134:137], v[190:193], v[94:97]
	v_mfma_f32_16x16x32_bf16 v[90:93], v[138:141], v[186:189], v[90:93]
	v_mfma_f32_16x16x32_bf16 v[90:93], v[142:145], v[190:193], v[90:93]
	s_setprio 0
	s_setprio 1
	v_mfma_f32_16x16x32_bf16 v[86:89], v[130:133], v[178:181], v[86:89]
	v_mfma_f32_16x16x32_bf16 v[86:89], v[134:137], v[182:185], v[86:89]
	v_mfma_f32_16x16x32_bf16 v[82:85], v[138:141], v[178:181], v[82:85]
	v_mfma_f32_16x16x32_bf16 v[82:85], v[142:145], v[182:185], v[82:85]
	s_setprio 0
	s_setprio 1
	v_mfma_f32_16x16x32_bf16 v[78:81], v[130:133], v[170:173], v[78:81]
	v_mfma_f32_16x16x32_bf16 v[78:81], v[134:137], v[174:177], v[78:81]
	v_mfma_f32_16x16x32_bf16 v[74:77], v[138:141], v[170:173], v[74:77]
	v_mfma_f32_16x16x32_bf16 v[74:77], v[142:145], v[174:177], v[74:77]
	s_setprio 0
	s_setprio 1
	v_mfma_f32_16x16x32_bf16 v[70:73], v[130:133], v[162:165], v[70:73]
	v_mfma_f32_16x16x32_bf16 v[70:73], v[134:137], v[166:169], v[70:73]
	s_setprio 2
	s_barrier
	v_mfma_f32_16x16x32_bf16 v[66:69], v[138:141], v[162:165], v[66:69]
	v_mfma_f32_16x16x32_bf16 v[66:69], v[142:145], v[166:169], v[66:69]
	s_setprio 0
	s_nop 0
	ds_read_b128 v[186:189], v207 offset:16384
	ds_read_b128 v[190:193], v207 offset:17408
	ds_read_b128 v[178:181], v207 offset:18432
	ds_read_b128 v[182:185], v207 offset:19456
	ds_read_b128 v[170:173], v207 offset:20480
	ds_read_b128 v[174:177], v207 offset:21504
	ds_read_b128 v[162:165], v207 offset:22528
	ds_read_b128 v[166:169], v207 offset:23552
	s_mov_b32 m0, s62
	s_nop 0
	global_load_lds_dwordx4 v195, s[50:51]
	s_add_u32 m0, s62, 0x2000
	s_nop 0
	global_load_lds_dwordx4 v197, s[50:51]
	s_add_u32 s56, s50, 0x4000
	s_addc_u32 s57, s51, 0
	s_mov_b32 m0, s63
	s_nop 0
	global_load_lds_dwordx4 v195, s[56:57]
	s_add_u32 m0, s63, 0x2000
	s_nop 0
	global_load_lds_dwordx4 v197, s[56:57]
	s_andn2_b64 vcc, exec, s[54:55]
	s_mov_b32 m0, s61
	s_nop 0
	global_load_lds_dwordx4 v195, s[52:53]
	s_add_u32 m0, s61, 0x2000
	s_nop 0
	global_load_lds_dwordx4 v197, s[52:53]
	s_cbranch_vccnz .LBB0_2122
	v_mov_b32_e32 v2, 0
	v_mov_b32_e32 v3, v2
	v_mov_b32_e32 v4, v2
	v_mov_b32_e32 v5, v2
	v_mov_b32_e32 v6, v2
	v_mov_b32_e32 v7, v2
	v_mov_b32_e32 v8, v2
	v_mov_b32_e32 v9, v2
	v_mov_b32_e32 v10, v2
	v_mov_b32_e32 v11, v2
	v_mov_b32_e32 v12, v2
	v_mov_b32_e32 v13, v2
	v_mov_b32_e32 v14, v2
	v_mov_b32_e32 v15, v2
	v_mov_b32_e32 v16, v2
	v_mov_b32_e32 v17, v2
	v_mov_b32_e32 v18, v2
	v_mov_b32_e32 v19, v2
	v_mov_b32_e32 v20, v2
	v_mov_b32_e32 v21, v2
	v_mov_b32_e32 v22, v2
	v_mov_b32_e32 v23, v2
	v_mov_b32_e32 v24, v2
	v_mov_b32_e32 v25, v2
	v_mov_b32_e32 v26, v2
	v_mov_b32_e32 v27, v2
	v_mov_b32_e32 v28, v2
	v_mov_b32_e32 v29, v2
	v_mov_b32_e32 v30, v2
	v_mov_b32_e32 v31, v2
	v_mov_b32_e32 v32, v2
	v_mov_b32_e32 v33, v2
	v_mov_b32_e32 v34, v2
	v_mov_b32_e32 v35, v2
	v_mov_b32_e32 v36, v2
	v_mov_b32_e32 v37, v2
	v_mov_b32_e32 v38, v2
	v_mov_b32_e32 v39, v2
	v_mov_b32_e32 v40, v2
	v_mov_b32_e32 v41, v2
	v_mov_b32_e32 v42, v2
	v_mov_b32_e32 v43, v2
	v_mov_b32_e32 v44, v2
	v_mov_b32_e32 v45, v2
	v_mov_b32_e32 v46, v2
	v_mov_b32_e32 v47, v2
	v_mov_b32_e32 v48, v2
	v_mov_b32_e32 v49, v2
	v_mov_b32_e32 v50, v2
	v_mov_b32_e32 v51, v2
	v_mov_b32_e32 v52, v2
	v_mov_b32_e32 v53, v2
	v_mov_b32_e32 v54, v2
	v_mov_b32_e32 v55, v2
	v_mov_b32_e32 v56, v2
	v_mov_b32_e32 v57, v2
	v_mov_b32_e32 v58, v2
	v_mov_b32_e32 v59, v2
	v_mov_b32_e32 v60, v2
	v_mov_b32_e32 v61, v2
	v_mov_b32_e32 v62, v2
	v_mov_b32_e32 v63, v2
	v_mov_b32_e32 v64, v2
	v_mov_b32_e32 v65, v2
.LBB0_2122:
	s_waitcnt vmcnt(8)
	s_add_u32 s54, s52, 0x8000
	s_waitcnt lgkmcnt(0)
	s_addc_u32 s55, s53, 0
	s_add_u32 s56, s50, 0x8000
	s_addc_u32 s57, s51, 0
	s_setprio 1
	s_barrier
	v_mfma_f32_16x16x32_bf16 v[62:65], v[146:149], v[186:189], v[62:65]
	v_mfma_f32_16x16x32_bf16 v[62:65], v[150:153], v[190:193], v[62:65]
	s_waitcnt lgkmcnt(5)
	v_mfma_f32_16x16x32_bf16 v[58:61], v[154:157], v[186:189], v[58:61]
	v_mfma_f32_16x16x32_bf16 v[58:61], v[158:161], v[190:193], v[58:61]
	s_waitcnt lgkmcnt(3)
	s_setprio 0
	s_setprio 1
	v_mfma_f32_16x16x32_bf16 v[54:57], v[146:149], v[178:181], v[54:57]
	v_mfma_f32_16x16x32_bf16 v[54:57], v[150:153], v[182:185], v[54:57]
	s_waitcnt lgkmcnt(1)
	v_mfma_f32_16x16x32_bf16 v[50:53], v[154:157], v[178:181], v[50:53]
	v_mfma_f32_16x16x32_bf16 v[50:53], v[158:161], v[182:185], v[50:53]
	s_setprio 0
	s_setprio 1
	v_mfma_f32_16x16x32_bf16 v[46:49], v[146:149], v[170:173], v[46:49]
	v_mfma_f32_16x16x32_bf16 v[46:49], v[150:153], v[174:177], v[46:49]
	v_mfma_f32_16x16x32_bf16 v[42:45], v[154:157], v[170:173], v[42:45]
	v_mfma_f32_16x16x32_bf16 v[42:45], v[158:161], v[174:177], v[42:45]
	s_setprio 0
	s_setprio 1
	v_mfma_f32_16x16x32_bf16 v[38:41], v[146:149], v[162:165], v[38:41]
	v_mfma_f32_16x16x32_bf16 v[38:41], v[150:153], v[166:169], v[38:41]
	s_waitcnt lgkmcnt(0)
	v_mfma_f32_16x16x32_bf16 v[34:37], v[154:157], v[162:165], v[34:37]
	v_mfma_f32_16x16x32_bf16 v[34:37], v[158:161], v[166:169], v[34:37]
	s_setprio 0
	s_setprio 1
	v_mfma_f32_16x16x32_bf16 v[30:33], v[130:133], v[186:189], v[30:33]
	v_mfma_f32_16x16x32_bf16 v[30:33], v[134:137], v[190:193], v[30:33]
	v_mfma_f32_16x16x32_bf16 v[26:29], v[138:141], v[186:189], v[26:29]
	v_mfma_f32_16x16x32_bf16 v[26:29], v[142:145], v[190:193], v[26:29]
	s_setprio 0
	s_setprio 1
	v_mfma_f32_16x16x32_bf16 v[22:25], v[130:133], v[178:181], v[22:25]
	v_mfma_f32_16x16x32_bf16 v[22:25], v[134:137], v[182:185], v[22:25]
	v_mfma_f32_16x16x32_bf16 v[18:21], v[138:141], v[178:181], v[18:21]
	v_mfma_f32_16x16x32_bf16 v[18:21], v[142:145], v[182:185], v[18:21]
	s_setprio 0
	s_setprio 1
	v_mfma_f32_16x16x32_bf16 v[14:17], v[130:133], v[170:173], v[14:17]
	v_mfma_f32_16x16x32_bf16 v[14:17], v[134:137], v[174:177], v[14:17]
	v_mfma_f32_16x16x32_bf16 v[10:13], v[138:141], v[170:173], v[10:13]
	v_mfma_f32_16x16x32_bf16 v[10:13], v[142:145], v[174:177], v[10:13]
	s_setprio 0
	s_setprio 1
	v_mfma_f32_16x16x32_bf16 v[6:9], v[130:133], v[162:165], v[6:9]
	v_mfma_f32_16x16x32_bf16 v[6:9], v[134:137], v[166:169], v[6:9]
	s_setprio 2
	s_barrier
	v_mfma_f32_16x16x32_bf16 v[2:5], v[138:141], v[162:165], v[2:5]
	v_mfma_f32_16x16x32_bf16 v[2:5], v[142:145], v[166:169], v[2:5]
	s_setprio 0
	s_nop 0
	v_add_u32_e32 v142, 0x18000, v206
	v_add_u32_e32 v158, 0x1c000, v206
	ds_read_b128 v[130:133], v142
	ds_read_b128 v[134:137], v142 offset:1024
	ds_read_b128 v[138:141], v142 offset:2048
	ds_read_b128 v[142:145], v142 offset:3072
	ds_read_b128 v[146:149], v158
	ds_read_b128 v[150:153], v158 offset:1024
	ds_read_b128 v[154:157], v158 offset:2048
	ds_read_b128 v[158:161], v158 offset:3072
	ds_read_b128 v[162:165], v207 offset:32768
	ds_read_b128 v[166:169], v207 offset:33792
	ds_read_b128 v[170:173], v207 offset:34816
	ds_read_b128 v[174:177], v207 offset:35840
	ds_read_b128 v[178:181], v207 offset:36864
	ds_read_b128 v[182:185], v207 offset:37888
	ds_read_b128 v[186:189], v207 offset:38912
	ds_read_b128 v[190:193], v207 offset:39936
	s_add_u32 s52, s52, 0x4000
	s_addc_u32 s53, s53, 0
	s_mov_b32 m0, s64
	s_nop 0
	global_load_lds_dwordx4 v195, s[52:53]
	s_add_u32 m0, s64, 0x2000
	s_nop 0
	global_load_lds_dwordx4 v197, s[52:53]
	s_waitcnt vmcnt(8)
	s_waitcnt lgkmcnt(0)
	s_setprio 1
	s_barrier
	v_mfma_f32_16x16x32_bf16 v[126:129], v[130:133], v[162:165], v[126:129]
	v_mfma_f32_16x16x32_bf16 v[126:129], v[134:137], v[166:169], v[126:129]
	s_waitcnt lgkmcnt(5)
	v_mfma_f32_16x16x32_bf16 v[122:125], v[138:141], v[162:165], v[122:125]
	v_mfma_f32_16x16x32_bf16 v[122:125], v[142:145], v[166:169], v[122:125]
	s_waitcnt lgkmcnt(3)
	s_setprio 0
	s_setprio 1
	v_mfma_f32_16x16x32_bf16 v[118:121], v[130:133], v[170:173], v[118:121]
	v_mfma_f32_16x16x32_bf16 v[118:121], v[134:137], v[174:177], v[118:121]
	s_waitcnt lgkmcnt(1)
	v_mfma_f32_16x16x32_bf16 v[114:117], v[138:141], v[170:173], v[114:117]
	v_mfma_f32_16x16x32_bf16 v[114:117], v[142:145], v[174:177], v[114:117]
	s_setprio 0
	s_setprio 1
	v_mfma_f32_16x16x32_bf16 v[110:113], v[130:133], v[178:181], v[110:113]
	v_mfma_f32_16x16x32_bf16 v[110:113], v[134:137], v[182:185], v[110:113]
	v_mfma_f32_16x16x32_bf16 v[106:109], v[138:141], v[178:181], v[106:109]
	v_mfma_f32_16x16x32_bf16 v[106:109], v[142:145], v[182:185], v[106:109]
	s_setprio 0
	s_setprio 1
	v_mfma_f32_16x16x32_bf16 v[102:105], v[130:133], v[186:189], v[102:105]
	v_mfma_f32_16x16x32_bf16 v[102:105], v[134:137], v[190:193], v[102:105]
	s_waitcnt lgkmcnt(0)
	v_mfma_f32_16x16x32_bf16 v[98:101], v[138:141], v[186:189], v[98:101]
	v_mfma_f32_16x16x32_bf16 v[98:101], v[142:145], v[190:193], v[98:101]
	s_setprio 0
	s_setprio 1
	v_mfma_f32_16x16x32_bf16 v[94:97], v[146:149], v[162:165], v[94:97]
	v_mfma_f32_16x16x32_bf16 v[94:97], v[150:153], v[166:169], v[94:97]
	v_mfma_f32_16x16x32_bf16 v[90:93], v[154:157], v[162:165], v[90:93]
	v_mfma_f32_16x16x32_bf16 v[90:93], v[158:161], v[166:169], v[90:93]
	s_setprio 0
	s_setprio 1
	v_mfma_f32_16x16x32_bf16 v[86:89], v[146:149], v[170:173], v[86:89]
	v_mfma_f32_16x16x32_bf16 v[86:89], v[150:153], v[174:177], v[86:89]
	v_mfma_f32_16x16x32_bf16 v[82:85], v[154:157], v[170:173], v[82:85]
	v_mfma_f32_16x16x32_bf16 v[82:85], v[158:161], v[174:177], v[82:85]
	s_setprio 0
	s_setprio 1
	v_mfma_f32_16x16x32_bf16 v[78:81], v[146:149], v[178:181], v[78:81]
	v_mfma_f32_16x16x32_bf16 v[78:81], v[150:153], v[182:185], v[78:81]
	v_mfma_f32_16x16x32_bf16 v[74:77], v[154:157], v[178:181], v[74:77]
	v_mfma_f32_16x16x32_bf16 v[74:77], v[158:161], v[182:185], v[74:77]
	s_setprio 0
	s_setprio 1
	v_mfma_f32_16x16x32_bf16 v[70:73], v[146:149], v[186:189], v[70:73]
	v_mfma_f32_16x16x32_bf16 v[70:73], v[150:153], v[190:193], v[70:73]
	s_setprio 2
	s_barrier
	v_mfma_f32_16x16x32_bf16 v[66:69], v[154:157], v[186:189], v[66:69]
	v_mfma_f32_16x16x32_bf16 v[66:69], v[158:161], v[190:193], v[66:69]
	s_setprio 0
	s_nop 0
	ds_read_b128 v[162:165], v207 offset:49152
	ds_read_b128 v[166:169], v207 offset:50176
	ds_read_b128 v[170:173], v207 offset:51200
	ds_read_b128 v[174:177], v207 offset:52224
	ds_read_b128 v[178:181], v207 offset:53248
	ds_read_b128 v[182:185], v207 offset:54272
	ds_read_b128 v[186:189], v207 offset:55296
	ds_read_b128 v[190:193], v207 offset:56320
	s_mov_b32 m0, s70
	s_nop 0
	global_load_lds_dwordx4 v195, s[56:57]
	s_add_u32 m0, s70, 0x2000
	s_nop 0
	global_load_lds_dwordx4 v197, s[56:57]
	s_add_u32 s50, s50, 0xc000
	s_addc_u32 s51, s51, 0
	s_mov_b32 m0, s72
	s_nop 0
	global_load_lds_dwordx4 v195, s[50:51]
	s_add_u32 m0, s72, 0x2000
	s_nop 0
	global_load_lds_dwordx4 v197, s[50:51]
	s_nop 0
	s_mov_b32 m0, s71
	s_nop 0
	global_load_lds_dwordx4 v195, s[54:55]
	s_add_u32 m0, s71, 0x2000
	s_nop 0
	global_load_lds_dwordx4 v197, s[54:55]
	s_waitcnt vmcnt(8)
	s_waitcnt lgkmcnt(0)
	s_setprio 1
	s_barrier
	v_mfma_f32_16x16x32_bf16 v[62:65], v[130:133], v[162:165], v[62:65]
	v_mfma_f32_16x16x32_bf16 v[62:65], v[134:137], v[166:169], v[62:65]
	s_waitcnt lgkmcnt(5)
	v_mfma_f32_16x16x32_bf16 v[58:61], v[138:141], v[162:165], v[58:61]
	v_mfma_f32_16x16x32_bf16 v[58:61], v[142:145], v[166:169], v[58:61]
	s_waitcnt lgkmcnt(3)
	s_setprio 0
	s_setprio 1
	v_mfma_f32_16x16x32_bf16 v[54:57], v[130:133], v[170:173], v[54:57]
	v_mfma_f32_16x16x32_bf16 v[54:57], v[134:137], v[174:177], v[54:57]
	s_waitcnt lgkmcnt(1)
	v_mfma_f32_16x16x32_bf16 v[50:53], v[138:141], v[170:173], v[50:53]
	v_mfma_f32_16x16x32_bf16 v[50:53], v[142:145], v[174:177], v[50:53]
	s_setprio 0
	s_setprio 1
	v_mfma_f32_16x16x32_bf16 v[46:49], v[130:133], v[178:181], v[46:49]
	v_mfma_f32_16x16x32_bf16 v[46:49], v[134:137], v[182:185], v[46:49]
	v_mfma_f32_16x16x32_bf16 v[42:45], v[138:141], v[178:181], v[42:45]
	v_mfma_f32_16x16x32_bf16 v[42:45], v[142:145], v[182:185], v[42:45]
	s_setprio 0
	s_setprio 1
	v_mfma_f32_16x16x32_bf16 v[38:41], v[130:133], v[186:189], v[38:41]
	v_mfma_f32_16x16x32_bf16 v[38:41], v[134:137], v[190:193], v[38:41]
	s_waitcnt lgkmcnt(0)
	v_mfma_f32_16x16x32_bf16 v[34:37], v[138:141], v[186:189], v[34:37]
	v_mfma_f32_16x16x32_bf16 v[34:37], v[142:145], v[190:193], v[34:37]
	s_setprio 0
	s_setprio 1
	v_mfma_f32_16x16x32_bf16 v[30:33], v[146:149], v[162:165], v[30:33]
	v_mfma_f32_16x16x32_bf16 v[30:33], v[150:153], v[166:169], v[30:33]
	v_mfma_f32_16x16x32_bf16 v[26:29], v[154:157], v[162:165], v[26:29]
	v_mfma_f32_16x16x32_bf16 v[26:29], v[158:161], v[166:169], v[26:29]
	s_setprio 0
	s_setprio 1
	v_mfma_f32_16x16x32_bf16 v[22:25], v[146:149], v[170:173], v[22:25]
	v_mfma_f32_16x16x32_bf16 v[22:25], v[150:153], v[174:177], v[22:25]
	v_mfma_f32_16x16x32_bf16 v[18:21], v[154:157], v[170:173], v[18:21]
	v_mfma_f32_16x16x32_bf16 v[18:21], v[158:161], v[174:177], v[18:21]
	s_setprio 0
	s_setprio 1
	v_mfma_f32_16x16x32_bf16 v[14:17], v[146:149], v[178:181], v[14:17]
	v_mfma_f32_16x16x32_bf16 v[14:17], v[150:153], v[182:185], v[14:17]
	v_mfma_f32_16x16x32_bf16 v[10:13], v[154:157], v[178:181], v[10:13]
	v_mfma_f32_16x16x32_bf16 v[10:13], v[158:161], v[182:185], v[10:13]
	s_setprio 0
	s_setprio 1
	v_mfma_f32_16x16x32_bf16 v[6:9], v[146:149], v[186:189], v[6:9]
	v_mfma_f32_16x16x32_bf16 v[6:9], v[150:153], v[190:193], v[6:9]
	s_setprio 2
	s_barrier
	v_mfma_f32_16x16x32_bf16 v[2:5], v[154:157], v[186:189], v[2:5]
	v_mfma_f32_16x16x32_bf16 v[2:5], v[158:161], v[190:193], v[2:5]
	s_setprio 0
	s_nop 0
	s_add_i32 s15, s90, 2
	s_cmp_gt_u32 s90, 13
	s_cbranch_scc1 .LBB0_2124
	v_mov_b32_e32 v130, v198
	s_mov_b32 s90, s15
	s_branch .LBB0_2099

.LBB0_2229:
	s_add_i32 s22, s46, 2
	s_lshl_b64 s[42:43], s[22:23], 15
	s_add_u32 s44, s2, s42
	s_addc_u32 s45, s3, s43
	s_and_b64 s[38:39], s[14:15], exec
	s_cselect_b32 s39, s45, s29
	s_cselect_b32 s38, s44, s28
	s_add_u32 s42, s16, s42
	s_waitcnt vmcnt(8)
	s_addc_u32 s43, s17, s43
	s_waitcnt lgkmcnt(0)
	s_and_b64 s[14:15], s[14:15], exec
	s_cselect_b32 s15, s43, s31
	s_cselect_b32 s14, s42, s30
	s_setprio 1
	s_barrier
	v_mfma_f32_16x16x32_bf16 v[126:129], v[146:149], v[186:189], v[126:129]
	v_mfma_f32_16x16x32_bf16 v[126:129], v[150:153], v[190:193], v[126:129]
	s_waitcnt lgkmcnt(5)
	v_mfma_f32_16x16x32_bf16 v[122:125], v[154:157], v[186:189], v[122:125]
	v_mfma_f32_16x16x32_bf16 v[122:125], v[158:161], v[190:193], v[122:125]
	s_waitcnt lgkmcnt(3)
	s_setprio 0
	s_setprio 1
	v_mfma_f32_16x16x32_bf16 v[118:121], v[146:149], v[178:181], v[118:121]
	v_mfma_f32_16x16x32_bf16 v[118:121], v[150:153], v[182:185], v[118:121]
	s_waitcnt lgkmcnt(1)
	v_mfma_f32_16x16x32_bf16 v[114:117], v[154:157], v[178:181], v[114:117]
	v_mfma_f32_16x16x32_bf16 v[114:117], v[158:161], v[182:185], v[114:117]
	s_setprio 0
	s_setprio 1
	v_mfma_f32_16x16x32_bf16 v[110:113], v[146:149], v[170:173], v[110:113]
	v_mfma_f32_16x16x32_bf16 v[110:113], v[150:153], v[174:177], v[110:113]
	v_mfma_f32_16x16x32_bf16 v[106:109], v[154:157], v[170:173], v[106:109]
	v_mfma_f32_16x16x32_bf16 v[106:109], v[158:161], v[174:177], v[106:109]
	s_setprio 0
	s_setprio 1
	v_mfma_f32_16x16x32_bf16 v[102:105], v[146:149], v[162:165], v[102:105]
	v_mfma_f32_16x16x32_bf16 v[102:105], v[150:153], v[166:169], v[102:105]
	s_waitcnt lgkmcnt(0)
	v_mfma_f32_16x16x32_bf16 v[98:101], v[154:157], v[162:165], v[98:101]
	v_mfma_f32_16x16x32_bf16 v[98:101], v[158:161], v[166:169], v[98:101]
	s_setprio 0
	s_setprio 1
	v_mfma_f32_16x16x32_bf16 v[94:97], v[130:133], v[186:189], v[94:97]
	v_mfma_f32_16x16x32_bf16 v[94:97], v[134:137], v[190:193], v[94:97]
	v_mfma_f32_16x16x32_bf16 v[90:93], v[138:141], v[186:189], v[90:93]
	v_mfma_f32_16x16x32_bf16 v[90:93], v[142:145], v[190:193], v[90:93]
	s_setprio 0
	s_setprio 1
	v_mfma_f32_16x16x32_bf16 v[86:89], v[130:133], v[178:181], v[86:89]
	v_mfma_f32_16x16x32_bf16 v[86:89], v[134:137], v[182:185], v[86:89]
	v_mfma_f32_16x16x32_bf16 v[82:85], v[138:141], v[178:181], v[82:85]
	v_mfma_f32_16x16x32_bf16 v[82:85], v[142:145], v[182:185], v[82:85]
	s_setprio 0
	s_setprio 1
	v_mfma_f32_16x16x32_bf16 v[78:81], v[130:133], v[170:173], v[78:81]
	v_mfma_f32_16x16x32_bf16 v[78:81], v[134:137], v[174:177], v[78:81]
	v_mfma_f32_16x16x32_bf16 v[74:77], v[138:141], v[170:173], v[74:77]
	v_mfma_f32_16x16x32_bf16 v[74:77], v[142:145], v[174:177], v[74:77]
	s_setprio 0
	s_setprio 1
	v_mfma_f32_16x16x32_bf16 v[70:73], v[130:133], v[162:165], v[70:73]
	v_mfma_f32_16x16x32_bf16 v[70:73], v[134:137], v[166:169], v[70:73]
	s_setprio 2
	s_barrier
	v_mfma_f32_16x16x32_bf16 v[66:69], v[138:141], v[162:165], v[66:69]
	v_mfma_f32_16x16x32_bf16 v[66:69], v[142:145], v[166:169], v[66:69]
	s_setprio 0
	s_nop 0
	ds_read_b128 v[186:189], v215 offset:16384
	ds_read_b128 v[190:193], v215 offset:17408
	ds_read_b128 v[178:181], v215 offset:18432
	ds_read_b128 v[182:185], v215 offset:19456
	ds_read_b128 v[170:173], v215 offset:20480
	ds_read_b128 v[174:177], v215 offset:21504
	ds_read_b128 v[162:165], v215 offset:22528
	ds_read_b128 v[166:169], v215 offset:23552
	s_mov_b32 m0, s57
	s_nop 0
	global_load_lds_dwordx4 v195, s[14:15]
	s_add_u32 m0, s57, 0x2000
	s_nop 0
	global_load_lds_dwordx4 v208, s[14:15]
	s_add_u32 s42, s14, 0x4000
	s_addc_u32 s43, s15, 0
	s_mov_b32 m0, s58
	s_nop 0
	global_load_lds_dwordx4 v195, s[42:43]
	s_add_u32 m0, s58, 0x2000
	s_nop 0
	global_load_lds_dwordx4 v208, s[42:43]
	s_andn2_b64 vcc, exec, s[40:41]
	s_mov_b32 m0, s56
	s_nop 0
	global_load_lds_dwordx4 v195, s[38:39]
	s_add_u32 m0, s56, 0x2000
	s_nop 0
	global_load_lds_dwordx4 v208, s[38:39]
	s_cbranch_vccnz .LBB0_2231
	v_mov_b32_e32 v2, 0
	v_mov_b32_e32 v3, v2
	v_mov_b32_e32 v4, v2
	v_mov_b32_e32 v5, v2
	v_mov_b32_e32 v6, v2
	v_mov_b32_e32 v7, v2
	v_mov_b32_e32 v8, v2
	v_mov_b32_e32 v9, v2
	v_mov_b32_e32 v10, v2
	v_mov_b32_e32 v11, v2
	v_mov_b32_e32 v12, v2
	v_mov_b32_e32 v13, v2
	v_mov_b32_e32 v14, v2
	v_mov_b32_e32 v15, v2
	v_mov_b32_e32 v16, v2
	v_mov_b32_e32 v17, v2
	v_mov_b32_e32 v18, v2
	v_mov_b32_e32 v19, v2
	v_mov_b32_e32 v20, v2
	v_mov_b32_e32 v21, v2
	v_mov_b32_e32 v22, v2
	v_mov_b32_e32 v23, v2
	v_mov_b32_e32 v24, v2
	v_mov_b32_e32 v25, v2
	v_mov_b32_e32 v26, v2
	v_mov_b32_e32 v27, v2
	v_mov_b32_e32 v28, v2
	v_mov_b32_e32 v29, v2
	v_mov_b32_e32 v30, v2
	v_mov_b32_e32 v31, v2
	v_mov_b32_e32 v32, v2
	v_mov_b32_e32 v33, v2
	v_mov_b32_e32 v34, v2
	v_mov_b32_e32 v35, v2
	v_mov_b32_e32 v36, v2
	v_mov_b32_e32 v37, v2
	v_mov_b32_e32 v38, v2
	v_mov_b32_e32 v39, v2
	v_mov_b32_e32 v40, v2
	v_mov_b32_e32 v41, v2
	v_mov_b32_e32 v42, v2
	v_mov_b32_e32 v43, v2
	v_mov_b32_e32 v44, v2
	v_mov_b32_e32 v45, v2
	v_mov_b32_e32 v46, v2
	v_mov_b32_e32 v47, v2
	v_mov_b32_e32 v48, v2
	v_mov_b32_e32 v49, v2
	v_mov_b32_e32 v50, v2
	v_mov_b32_e32 v51, v2
	v_mov_b32_e32 v52, v2
	v_mov_b32_e32 v53, v2
	v_mov_b32_e32 v54, v2
	v_mov_b32_e32 v55, v2
	v_mov_b32_e32 v56, v2
	v_mov_b32_e32 v57, v2
	v_mov_b32_e32 v58, v2
	v_mov_b32_e32 v59, v2
	v_mov_b32_e32 v60, v2
	v_mov_b32_e32 v61, v2
	v_mov_b32_e32 v62, v2
	v_mov_b32_e32 v63, v2
	v_mov_b32_e32 v64, v2
	v_mov_b32_e32 v65, v2
.LBB0_2231:
	s_waitcnt vmcnt(8)
	s_add_u32 s40, s38, 0x8000
	s_waitcnt lgkmcnt(0)
	s_addc_u32 s41, s39, 0
	s_add_u32 s42, s14, 0x8000
	s_addc_u32 s43, s15, 0
	s_setprio 1
	s_barrier
	v_mfma_f32_16x16x32_bf16 v[62:65], v[146:149], v[186:189], v[62:65]
	v_mfma_f32_16x16x32_bf16 v[62:65], v[150:153], v[190:193], v[62:65]
	s_waitcnt lgkmcnt(5)
	v_mfma_f32_16x16x32_bf16 v[58:61], v[154:157], v[186:189], v[58:61]
	v_mfma_f32_16x16x32_bf16 v[58:61], v[158:161], v[190:193], v[58:61]
	s_waitcnt lgkmcnt(3)
	s_setprio 0
	s_setprio 1
	v_mfma_f32_16x16x32_bf16 v[54:57], v[146:149], v[178:181], v[54:57]
	v_mfma_f32_16x16x32_bf16 v[54:57], v[150:153], v[182:185], v[54:57]
	s_waitcnt lgkmcnt(1)
	v_mfma_f32_16x16x32_bf16 v[50:53], v[154:157], v[178:181], v[50:53]
	v_mfma_f32_16x16x32_bf16 v[50:53], v[158:161], v[182:185], v[50:53]
	s_setprio 0
	s_setprio 1
	v_mfma_f32_16x16x32_bf16 v[46:49], v[146:149], v[170:173], v[46:49]
	v_mfma_f32_16x16x32_bf16 v[46:49], v[150:153], v[174:177], v[46:49]
	v_mfma_f32_16x16x32_bf16 v[42:45], v[154:157], v[170:173], v[42:45]
	v_mfma_f32_16x16x32_bf16 v[42:45], v[158:161], v[174:177], v[42:45]
	s_setprio 0
	s_setprio 1
	v_mfma_f32_16x16x32_bf16 v[38:41], v[146:149], v[162:165], v[38:41]
	v_mfma_f32_16x16x32_bf16 v[38:41], v[150:153], v[166:169], v[38:41]
	s_waitcnt lgkmcnt(0)
	v_mfma_f32_16x16x32_bf16 v[34:37], v[154:157], v[162:165], v[34:37]
	v_mfma_f32_16x16x32_bf16 v[34:37], v[158:161], v[166:169], v[34:37]
	s_setprio 0
	s_setprio 1
	v_mfma_f32_16x16x32_bf16 v[30:33], v[130:133], v[186:189], v[30:33]
	v_mfma_f32_16x16x32_bf16 v[30:33], v[134:137], v[190:193], v[30:33]
	v_mfma_f32_16x16x32_bf16 v[26:29], v[138:141], v[186:189], v[26:29]
	v_mfma_f32_16x16x32_bf16 v[26:29], v[142:145], v[190:193], v[26:29]
	s_setprio 0
	s_setprio 1
	v_mfma_f32_16x16x32_bf16 v[22:25], v[130:133], v[178:181], v[22:25]
	v_mfma_f32_16x16x32_bf16 v[22:25], v[134:137], v[182:185], v[22:25]
	v_mfma_f32_16x16x32_bf16 v[18:21], v[138:141], v[178:181], v[18:21]
	v_mfma_f32_16x16x32_bf16 v[18:21], v[142:145], v[182:185], v[18:21]
	s_setprio 0
	s_setprio 1
	v_mfma_f32_16x16x32_bf16 v[14:17], v[130:133], v[170:173], v[14:17]
	v_mfma_f32_16x16x32_bf16 v[14:17], v[134:137], v[174:177], v[14:17]
	v_mfma_f32_16x16x32_bf16 v[10:13], v[138:141], v[170:173], v[10:13]
	v_mfma_f32_16x16x32_bf16 v[10:13], v[142:145], v[174:177], v[10:13]
	s_setprio 0
	s_setprio 1
	v_mfma_f32_16x16x32_bf16 v[6:9], v[130:133], v[162:165], v[6:9]
	v_mfma_f32_16x16x32_bf16 v[6:9], v[134:137], v[166:169], v[6:9]
	s_setprio 2
	s_barrier
	v_mfma_f32_16x16x32_bf16 v[2:5], v[138:141], v[162:165], v[2:5]
	v_mfma_f32_16x16x32_bf16 v[2:5], v[142:145], v[166:169], v[2:5]
	s_setprio 0
	s_nop 0
	v_add_u32_e32 v142, 0x18000, v214
	v_add_u32_e32 v158, 0x1c000, v214
	ds_read_b128 v[130:133], v142
	ds_read_b128 v[134:137], v142 offset:1024
	ds_read_b128 v[138:141], v142 offset:2048
	ds_read_b128 v[142:145], v142 offset:3072
	ds_read_b128 v[146:149], v158
	ds_read_b128 v[150:153], v158 offset:1024
	ds_read_b128 v[154:157], v158 offset:2048
	ds_read_b128 v[158:161], v158 offset:3072
	ds_read_b128 v[162:165], v215 offset:32768
	ds_read_b128 v[166:169], v215 offset:33792
	ds_read_b128 v[170:173], v215 offset:34816
	ds_read_b128 v[174:177], v215 offset:35840
	ds_read_b128 v[178:181], v215 offset:36864
	ds_read_b128 v[182:185], v215 offset:37888
	ds_read_b128 v[186:189], v215 offset:38912
	ds_read_b128 v[190:193], v215 offset:39936
	s_add_u32 s38, s38, 0x4000
	s_addc_u32 s39, s39, 0
	s_mov_b32 m0, s59
	s_nop 0
	global_load_lds_dwordx4 v195, s[38:39]
	s_add_u32 m0, s59, 0x2000
	s_nop 0
	global_load_lds_dwordx4 v208, s[38:39]
	s_waitcnt vmcnt(8)
	s_waitcnt lgkmcnt(0)
	s_setprio 1
	s_barrier
	v_mfma_f32_16x16x32_bf16 v[126:129], v[130:133], v[162:165], v[126:129]
	v_mfma_f32_16x16x32_bf16 v[126:129], v[134:137], v[166:169], v[126:129]
	s_waitcnt lgkmcnt(5)
	v_mfma_f32_16x16x32_bf16 v[122:125], v[138:141], v[162:165], v[122:125]
	v_mfma_f32_16x16x32_bf16 v[122:125], v[142:145], v[166:169], v[122:125]
	s_waitcnt lgkmcnt(3)
	s_setprio 0
	s_setprio 1
	v_mfma_f32_16x16x32_bf16 v[118:121], v[130:133], v[170:173], v[118:121]
	v_mfma_f32_16x16x32_bf16 v[118:121], v[134:137], v[174:177], v[118:121]
	s_waitcnt lgkmcnt(1)
	v_mfma_f32_16x16x32_bf16 v[114:117], v[138:141], v[170:173], v[114:117]
	v_mfma_f32_16x16x32_bf16 v[114:117], v[142:145], v[174:177], v[114:117]
	s_setprio 0
	s_setprio 1
	v_mfma_f32_16x16x32_bf16 v[110:113], v[130:133], v[178:181], v[110:113]
	v_mfma_f32_16x16x32_bf16 v[110:113], v[134:137], v[182:185], v[110:113]
	v_mfma_f32_16x16x32_bf16 v[106:109], v[138:141], v[178:181], v[106:109]
	v_mfma_f32_16x16x32_bf16 v[106:109], v[142:145], v[182:185], v[106:109]
	s_setprio 0
	s_setprio 1
	v_mfma_f32_16x16x32_bf16 v[102:105], v[130:133], v[186:189], v[102:105]
	v_mfma_f32_16x16x32_bf16 v[102:105], v[134:137], v[190:193], v[102:105]
	s_waitcnt lgkmcnt(0)
	v_mfma_f32_16x16x32_bf16 v[98:101], v[138:141], v[186:189], v[98:101]
	v_mfma_f32_16x16x32_bf16 v[98:101], v[142:145], v[190:193], v[98:101]
	s_setprio 0
	s_setprio 1
	v_mfma_f32_16x16x32_bf16 v[94:97], v[146:149], v[162:165], v[94:97]
	v_mfma_f32_16x16x32_bf16 v[94:97], v[150:153], v[166:169], v[94:97]
	v_mfma_f32_16x16x32_bf16 v[90:93], v[154:157], v[162:165], v[90:93]
	v_mfma_f32_16x16x32_bf16 v[90:93], v[158:161], v[166:169], v[90:93]
	s_setprio 0
	s_setprio 1
	v_mfma_f32_16x16x32_bf16 v[86:89], v[146:149], v[170:173], v[86:89]
	v_mfma_f32_16x16x32_bf16 v[86:89], v[150:153], v[174:177], v[86:89]
	v_mfma_f32_16x16x32_bf16 v[82:85], v[154:157], v[170:173], v[82:85]
	v_mfma_f32_16x16x32_bf16 v[82:85], v[158:161], v[174:177], v[82:85]
	s_setprio 0
	s_setprio 1
	v_mfma_f32_16x16x32_bf16 v[78:81], v[146:149], v[178:181], v[78:81]
	v_mfma_f32_16x16x32_bf16 v[78:81], v[150:153], v[182:185], v[78:81]
	v_mfma_f32_16x16x32_bf16 v[74:77], v[154:157], v[178:181], v[74:77]
	v_mfma_f32_16x16x32_bf16 v[74:77], v[158:161], v[182:185], v[74:77]
	s_setprio 0
	s_setprio 1
	v_mfma_f32_16x16x32_bf16 v[70:73], v[146:149], v[186:189], v[70:73]
	v_mfma_f32_16x16x32_bf16 v[70:73], v[150:153], v[190:193], v[70:73]
	s_setprio 2
	s_barrier
	v_mfma_f32_16x16x32_bf16 v[66:69], v[154:157], v[186:189], v[66:69]
	v_mfma_f32_16x16x32_bf16 v[66:69], v[158:161], v[190:193], v[66:69]
	s_setprio 0
	s_nop 0
	ds_read_b128 v[162:165], v215 offset:49152
	ds_read_b128 v[166:169], v215 offset:50176
	ds_read_b128 v[170:173], v215 offset:51200
	ds_read_b128 v[174:177], v215 offset:52224
	ds_read_b128 v[178:181], v215 offset:53248
	ds_read_b128 v[182:185], v215 offset:54272
	ds_read_b128 v[186:189], v215 offset:55296
	ds_read_b128 v[190:193], v215 offset:56320
	s_mov_b32 m0, s63
	s_nop 0
	global_load_lds_dwordx4 v195, s[42:43]
	s_add_u32 m0, s63, 0x2000
	s_nop 0
	global_load_lds_dwordx4 v208, s[42:43]
	s_add_u32 s14, s14, 0xc000
	s_addc_u32 s15, s15, 0
	s_mov_b32 m0, s65
	s_nop 0
	global_load_lds_dwordx4 v195, s[14:15]
	s_add_u32 m0, s65, 0x2000
	s_nop 0
	global_load_lds_dwordx4 v208, s[14:15]
	s_nop 0
	s_mov_b32 m0, s64
	s_nop 0
	global_load_lds_dwordx4 v195, s[40:41]
	s_add_u32 m0, s64, 0x2000
	s_nop 0
	global_load_lds_dwordx4 v208, s[40:41]
	s_waitcnt vmcnt(8)
	s_waitcnt lgkmcnt(0)
	s_setprio 1
	s_barrier
	v_mfma_f32_16x16x32_bf16 v[62:65], v[130:133], v[162:165], v[62:65]
	v_mfma_f32_16x16x32_bf16 v[62:65], v[134:137], v[166:169], v[62:65]
	s_waitcnt lgkmcnt(5)
	v_mfma_f32_16x16x32_bf16 v[58:61], v[138:141], v[162:165], v[58:61]
	v_mfma_f32_16x16x32_bf16 v[58:61], v[142:145], v[166:169], v[58:61]
	s_waitcnt lgkmcnt(3)
	s_setprio 0
	s_setprio 1
	v_mfma_f32_16x16x32_bf16 v[54:57], v[130:133], v[170:173], v[54:57]
	v_mfma_f32_16x16x32_bf16 v[54:57], v[134:137], v[174:177], v[54:57]
	s_waitcnt lgkmcnt(1)
	v_mfma_f32_16x16x32_bf16 v[50:53], v[138:141], v[170:173], v[50:53]
	v_mfma_f32_16x16x32_bf16 v[50:53], v[142:145], v[174:177], v[50:53]
	s_setprio 0
	s_setprio 1
	v_mfma_f32_16x16x32_bf16 v[46:49], v[130:133], v[178:181], v[46:49]
	v_mfma_f32_16x16x32_bf16 v[46:49], v[134:137], v[182:185], v[46:49]
	v_mfma_f32_16x16x32_bf16 v[42:45], v[138:141], v[178:181], v[42:45]
	v_mfma_f32_16x16x32_bf16 v[42:45], v[142:145], v[182:185], v[42:45]
	s_setprio 0
	s_setprio 1
	v_mfma_f32_16x16x32_bf16 v[38:41], v[130:133], v[186:189], v[38:41]
	v_mfma_f32_16x16x32_bf16 v[38:41], v[134:137], v[190:193], v[38:41]
	s_waitcnt lgkmcnt(0)
	v_mfma_f32_16x16x32_bf16 v[34:37], v[138:141], v[186:189], v[34:37]
	v_mfma_f32_16x16x32_bf16 v[34:37], v[142:145], v[190:193], v[34:37]
	s_setprio 0
	s_setprio 1
	v_mfma_f32_16x16x32_bf16 v[30:33], v[146:149], v[162:165], v[30:33]
	v_mfma_f32_16x16x32_bf16 v[30:33], v[150:153], v[166:169], v[30:33]
	v_mfma_f32_16x16x32_bf16 v[26:29], v[154:157], v[162:165], v[26:29]
	v_mfma_f32_16x16x32_bf16 v[26:29], v[158:161], v[166:169], v[26:29]
	s_setprio 0
	s_setprio 1
	v_mfma_f32_16x16x32_bf16 v[22:25], v[146:149], v[170:173], v[22:25]
	v_mfma_f32_16x16x32_bf16 v[22:25], v[150:153], v[174:177], v[22:25]
	v_mfma_f32_16x16x32_bf16 v[18:21], v[154:157], v[170:173], v[18:21]
	v_mfma_f32_16x16x32_bf16 v[18:21], v[158:161], v[174:177], v[18:21]
	s_setprio 0
	s_setprio 1
	v_mfma_f32_16x16x32_bf16 v[14:17], v[146:149], v[178:181], v[14:17]
	v_mfma_f32_16x16x32_bf16 v[14:17], v[150:153], v[182:185], v[14:17]
	v_mfma_f32_16x16x32_bf16 v[10:13], v[154:157], v[178:181], v[10:13]
	v_mfma_f32_16x16x32_bf16 v[10:13], v[158:161], v[182:185], v[10:13]
	s_setprio 0
	s_setprio 1
	v_mfma_f32_16x16x32_bf16 v[6:9], v[146:149], v[186:189], v[6:9]
	v_mfma_f32_16x16x32_bf16 v[6:9], v[150:153], v[190:193], v[6:9]
	s_setprio 2
	s_barrier
	v_mfma_f32_16x16x32_bf16 v[2:5], v[154:157], v[186:189], v[2:5]
	v_mfma_f32_16x16x32_bf16 v[2:5], v[158:161], v[190:193], v[2:5]
	s_setprio 0
	s_nop 0
	s_cmp_gt_u32 s46, 41
	s_cbranch_scc1 .LBB0_2233
	v_mov_b32_e32 v130, v196
	s_mov_b32 s46, s22
	s_branch .LBB0_2208
